# v25 + weight-converter f32 loads issued sc1 nt (read-once source kept out of the XCD L2) instead of nt
# speedup vs baseline: 1.0090x; 1.0028x over previous
; #define LAS __attribute__((address_space(3)))
; __device__ __forceinline__ unsigned cvt_pk_bf16(float lo, float hi) { unsigned r; asm volatile("v_cvt_pk_bf16_f32 %0, %1, %2" : "=v"(r) : "v"(lo), "v"(hi)); return r; }
; #define LDS_WAIT() asm volatile("s_waitcnt lgkmcnt(0)" ::: "memory")
; __device__ __forceinline__ unsigned cvt_pk_bf16(float lo, float hi) { unsigned r; asm volatile("v_cvt_pk_bf16_f32 %0, %1, %2" : "=v"(r) : "v"(lo), "v"(hi)); return r; }
; template <bool NT = true> __device__ __forceinline__ void tr_load(const TrDesc& d, f32x4 (&v)[8], int lane) {
;     const float* sp = d.src + (size_t)(lane >> 3) * d.ldn + 4 * (lane & 7);
; #pragma unroll
;     for (int i = 0; i < 8; ++i) v[i] = NT ? __builtin_nontemporal_load((const f32x4*)(sp + (size_t)(8 * i) * d.ldn)) : *(const f32x4*)(sp + (size_t)(8 * i) * d.ldn);
; }
; template <bool NT = true> __device__ __forceinline__ void tr_finish(const TrDesc& d, const f32x4 (&v)[8], LAS float* scr, int lane) {
;     const int c = lane & 7;
;     f32x4 g0 = {1.f, 1.f, 1.f, 1.f}, g1 = {1.f, 1.f, 1.f, 1.f};
;     if (d.gain) { g0 = *(const f32x4*)(d.gain + 8 * c); g1 = *(const f32x4*)(d.gain + 8 * c + 4); }
; #pragma unroll
;     for (int i = 0; i < 8; ++i) { LAS float* w = scr + (8 * i + (lane >> 3)) * 33 + 4 * c; w[0] = v[i].x; w[1] = v[i].y; w[2] = v[i].z; w[3] = v[i].w; }
;     LDS_WAIT(); asm volatile("" ::: "memory");
; #pragma unroll
;     for (int j = 0; j < 4; ++j) { const int n = (lane >> 3) + 8 * j; const LAS float* s = scr + (8 * c) * 33 + n;
;         u32x4 o; o.x = cvt_pk_bf16(s[0 * 33] * g0.x, s[1 * 33] * g0.y); o.y = cvt_pk_bf16(s[2 * 33] * g0.z, s[3 * 33] * g0.w); o.z = cvt_pk_bf16(s[4 * 33] * g1.x, s[5 * 33] * g1.y); o.w = cvt_pk_bf16(s[6 * 33] * g1.z, s[7 * 33] * g1.w);
;         if (NT) __builtin_nontemporal_store(o, (u32x4*)(d.dst + (size_t)n * d.K + 8 * c)); else *(u32x4*)(d.dst + (size_t)n * d.K + 8 * c) = o; }
.Lpz_run:
	s_cmp_eq_u32 s74, 0
	s_cbranch_scc1 .Lpz_ret
	v_mul_lo_u32 v229, v238, s78
	v_lshlrev_b32_e32 v229, 3, v229
	v_lshl_add_u32 v2, v239, 4, v229
	v_add_u32_e32 v120, s78, v2
	v_add_u32_e32 v121, s78, v120
	v_add_u32_e32 v126, s78, v121
	v_add_u32_e32 v144, s78, v126
	v_add_u32_e32 v145, s78, v144
	v_add_u32_e32 v147, s78, v145
	v_add_u32_e32 v165, s78, v147
	v_lshlrev_b32_e32 v230, 2, v239
	v_mul_lo_u32 v230, v230, s79
	v_lshl_add_u32 v214, v238, 4, v230
	v_add_u32_e32 v215, s79, v214
	v_add_u32_e32 v219, s79, v215
	v_add_u32_e32 v236, s79, v219
	s_cmp_eq_u32 s80, 0
	s_cbranch_scc1 .Lpz_nogain
	global_load_dwordx4 v[220:223], v237, s[76:77]
	global_load_dwordx4 v[224:227], v237, s[76:77] offset:16
	global_load_dwordx4 v[6:9], v2, s[60:61] offset:0 sc1 nt
	global_load_dwordx4 v[10:13], v120, s[60:61] offset:0 sc1 nt
	global_load_dwordx4 v[14:17], v121, s[60:61] offset:0 sc1 nt
	global_load_dwordx4 v[18:21], v126, s[60:61] offset:0 sc1 nt
	global_load_dwordx4 v[22:25], v144, s[60:61] offset:0 sc1 nt
	global_load_dwordx4 v[26:29], v145, s[60:61] offset:0 sc1 nt
	global_load_dwordx4 v[30:33], v147, s[60:61] offset:0 sc1 nt
	global_load_dwordx4 v[66:69], v165, s[60:61] offset:0 sc1 nt
	global_load_dwordx4 v[100:103], v2, s[60:61] offset:128 sc1 nt
	global_load_dwordx4 v[104:107], v120, s[60:61] offset:128 sc1 nt
	global_load_dwordx4 v[108:111], v121, s[60:61] offset:128 sc1 nt
	global_load_dwordx4 v[112:115], v126, s[60:61] offset:128 sc1 nt
	global_load_dwordx4 v[116:119], v144, s[60:61] offset:128 sc1 nt
	global_load_dwordx4 v[132:135], v145, s[60:61] offset:128 sc1 nt
	global_load_dwordx4 v[136:139], v147, s[60:61] offset:128 sc1 nt
	global_load_dwordx4 v[140:143], v165, s[60:61] offset:128 sc1 nt
	global_load_dwordx4 v[148:151], v2, s[60:61] offset:256 sc1 nt
	global_load_dwordx4 v[152:155], v120, s[60:61] offset:256 sc1 nt
	global_load_dwordx4 v[156:159], v121, s[60:61] offset:256 sc1 nt
	global_load_dwordx4 v[160:163], v126, s[60:61] offset:256 sc1 nt
	global_load_dwordx4 v[166:169], v144, s[60:61] offset:256 sc1 nt
	global_load_dwordx4 v[170:173], v145, s[60:61] offset:256 sc1 nt
	global_load_dwordx4 v[174:177], v147, s[60:61] offset:256 sc1 nt
	global_load_dwordx4 v[178:181], v165, s[60:61] offset:256 sc1 nt
	global_load_dwordx4 v[182:185], v2, s[60:61] offset:384 sc1 nt
	global_load_dwordx4 v[186:189], v120, s[60:61] offset:384 sc1 nt
	global_load_dwordx4 v[190:193], v121, s[60:61] offset:384 sc1 nt
	global_load_dwordx4 v[194:197], v126, s[60:61] offset:384 sc1 nt
	global_load_dwordx4 v[198:201], v144, s[60:61] offset:384 sc1 nt
	global_load_dwordx4 v[202:205], v145, s[60:61] offset:384 sc1 nt
	global_load_dwordx4 v[206:209], v147, s[60:61] offset:384 sc1 nt
	global_load_dwordx4 v[210:213], v165, s[60:61] offset:384 sc1 nt
	s_add_u32 s60, s60, s70
	s_addc_u32 s61, s61, s71
	s_cmp_eq_u32 s74, 1
	s_cbranch_scc1 .Lpz_g_last
	s_waitcnt vmcnt(24)
	v_mul_f32_e32 v6, v220, v6
	v_mul_f32_e32 v7, v220, v7
	v_mul_f32_e32 v8, v220, v8
	v_mul_f32_e32 v9, v220, v9
	v_mul_f32_e32 v10, v221, v10
	v_mul_f32_e32 v11, v221, v11
	v_mul_f32_e32 v12, v221, v12
	v_mul_f32_e32 v13, v221, v13
	v_mul_f32_e32 v14, v222, v14
	v_mul_f32_e32 v15, v222, v15
	v_mul_f32_e32 v16, v222, v16
	v_mul_f32_e32 v17, v222, v17
	v_mul_f32_e32 v18, v223, v18
	v_mul_f32_e32 v19, v223, v19
	v_mul_f32_e32 v20, v223, v20
	v_mul_f32_e32 v21, v223, v21
	v_mul_f32_e32 v22, v224, v22
	v_mul_f32_e32 v23, v224, v23
	v_mul_f32_e32 v24, v224, v24
	v_mul_f32_e32 v25, v224, v25
	v_mul_f32_e32 v26, v225, v26
	v_mul_f32_e32 v27, v225, v27
	v_mul_f32_e32 v28, v225, v28
	v_mul_f32_e32 v29, v225, v29
	v_mul_f32_e32 v30, v226, v30
	v_mul_f32_e32 v31, v226, v31
	v_mul_f32_e32 v32, v226, v32
	v_mul_f32_e32 v33, v226, v33
	v_mul_f32_e32 v66, v227, v66
	v_mul_f32_e32 v67, v227, v67
	v_mul_f32_e32 v68, v227, v68
	v_mul_f32_e32 v69, v227, v69
	v_cvt_pk_bf16_f32 v228, v6, v10
	v_cvt_pk_bf16_f32 v229, v14, v18
	v_cvt_pk_bf16_f32 v230, v22, v26
	v_cvt_pk_bf16_f32 v231, v30, v66
	global_store_dwordx4 v214, v[228:231], s[62:63] sc1
	v_cvt_pk_bf16_f32 v232, v7, v11
	v_cvt_pk_bf16_f32 v233, v15, v19
	v_cvt_pk_bf16_f32 v234, v23, v27
	v_cvt_pk_bf16_f32 v235, v31, v67
	global_store_dwordx4 v215, v[232:235], s[62:63] sc1
	v_cvt_pk_bf16_f32 v228, v8, v12
	v_cvt_pk_bf16_f32 v229, v16, v20
	v_cvt_pk_bf16_f32 v230, v24, v28
	v_cvt_pk_bf16_f32 v231, v32, v68
	global_store_dwordx4 v219, v[228:231], s[62:63] sc1
	v_cvt_pk_bf16_f32 v232, v9, v13
	v_cvt_pk_bf16_f32 v233, v17, v21
	v_cvt_pk_bf16_f32 v234, v25, v29
	v_cvt_pk_bf16_f32 v235, v33, v69
	global_store_dwordx4 v236, v[232:235], s[62:63] sc1
	global_load_dwordx4 v[6:9], v2, s[60:61] offset:0 sc1 nt
	global_load_dwordx4 v[10:13], v120, s[60:61] offset:0 sc1 nt
	global_load_dwordx4 v[14:17], v121, s[60:61] offset:0 sc1 nt
	global_load_dwordx4 v[18:21], v126, s[60:61] offset:0 sc1 nt
	global_load_dwordx4 v[22:25], v144, s[60:61] offset:0 sc1 nt
	global_load_dwordx4 v[26:29], v145, s[60:61] offset:0 sc1 nt
	global_load_dwordx4 v[30:33], v147, s[60:61] offset:0 sc1 nt
	global_load_dwordx4 v[66:69], v165, s[60:61] offset:0 sc1 nt
	s_add_u32 s62, s62, s72
	s_addc_u32 s63, s63, s73
	s_waitcnt vmcnt(28)
; #define LAS __attribute__((address_space(3)))
; __device__ __forceinline__ unsigned cvt_pk_bf16(float lo, float hi) { unsigned r; asm volatile("v_cvt_pk_bf16_f32 %0, %1, %2" : "=v"(r) : "v"(lo), "v"(hi)); return r; }
; template <bool NT = true> __device__ __forceinline__ void tr_load(const TrDesc& d, f32x4 (&v)[8], int lane) {
;     const float* sp = d.src + (size_t)(lane >> 3) * d.ldn + 4 * (lane & 7);
; #pragma unroll
;     for (int i = 0; i < 8; ++i) v[i] = NT ? __builtin_nontemporal_load((const f32x4*)(sp + (size_t)(8 * i) * d.ldn)) : *(const f32x4*)(sp + (size_t)(8 * i) * d.ldn);
; }
; template <bool NT = true> __device__ __forceinline__ void tr_finish(const TrDesc& d, const f32x4 (&v)[8], LAS float* scr, int lane) {
;     const int c = lane & 7;
;     f32x4 g0 = {1.f, 1.f, 1.f, 1.f}, g1 = {1.f, 1.f, 1.f, 1.f};
;     if (d.gain) { g0 = *(const f32x4*)(d.gain + 8 * c); g1 = *(const f32x4*)(d.gain + 8 * c + 4); }
; #pragma unroll
;     for (int i = 0; i < 8; ++i) { LAS float* w = scr + (8 * i + (lane >> 3)) * 33 + 4 * c; w[0] = v[i].x; w[1] = v[i].y; w[2] = v[i].z; w[3] = v[i].w; }
;     LDS_WAIT(); asm volatile("" ::: "memory");
; #pragma unroll
;     for (int j = 0; j < 4; ++j) { const int n = (lane >> 3) + 8 * j; const LAS float* s = scr + (8 * c) * 33 + n;
;         u32x4 o; o.x = cvt_pk_bf16(s[0 * 33] * g0.x, s[1 * 33] * g0.y); o.y = cvt_pk_bf16(s[2 * 33] * g0.z, s[3 * 33] * g0.w); o.z = cvt_pk_bf16(s[4 * 33] * g1.x, s[5 * 33] * g1.y); o.w = cvt_pk_bf16(s[6 * 33] * g1.z, s[7 * 33] * g1.w);
;         if (NT) __builtin_nontemporal_store(o, (u32x4*)(d.dst + (size_t)n * d.K + 8 * c)); else *(u32x4*)(d.dst + (size_t)n * d.K + 8 * c) = o; }
; template <class F, bool NT = true> __device__ __forceinline__ void tr_run(F item, int first, int step, int n, LAS float* scr, int lane) {
;     ...
;     for (int it = first; it < n; it += 3 * step) {
;         const bool h1 = it + step < n, h2 = it + 2 * step < n, h3 = it + 3 * step < n, h4 = it + 4 * step < n;
;         if (h2) { dc = item(it + 2 * step); tr_load<NT>(dc, vc, lane); }
;         tr_finish<NT>(da, va, scr, lane);
;         if (h3) { da = item(it + 3 * step); tr_load<NT>(da, va, lane); }
;         if (h1) tr_finish<NT>(db, vb, scr, lane);
;         if (h4) { db = item(it + 4 * step); tr_load<NT>(db, vb, lane); }
;         if (h2) tr_finish<NT>(dc, vc, scr, lane);
;     }
	v_mul_f32_e32 v100, v220, v100
	v_mul_f32_e32 v101, v220, v101
	v_mul_f32_e32 v102, v220, v102
	v_mul_f32_e32 v103, v220, v103
	v_mul_f32_e32 v104, v221, v104
	v_mul_f32_e32 v105, v221, v105
	v_mul_f32_e32 v106, v221, v106
	v_mul_f32_e32 v107, v221, v107
	v_mul_f32_e32 v108, v222, v108
	v_mul_f32_e32 v109, v222, v109
	v_mul_f32_e32 v110, v222, v110
	v_mul_f32_e32 v111, v222, v111
	v_mul_f32_e32 v112, v223, v112
	v_mul_f32_e32 v113, v223, v113
	v_mul_f32_e32 v114, v223, v114
	v_mul_f32_e32 v115, v223, v115
	v_mul_f32_e32 v116, v224, v116
	v_mul_f32_e32 v117, v224, v117
	v_mul_f32_e32 v118, v224, v118
	v_mul_f32_e32 v119, v224, v119
	v_mul_f32_e32 v132, v225, v132
	v_mul_f32_e32 v133, v225, v133
	v_mul_f32_e32 v134, v225, v134
	v_mul_f32_e32 v135, v225, v135
	v_mul_f32_e32 v136, v226, v136
	v_mul_f32_e32 v137, v226, v137
	v_mul_f32_e32 v138, v226, v138
	v_mul_f32_e32 v139, v226, v139
	v_mul_f32_e32 v140, v227, v140
	v_mul_f32_e32 v141, v227, v141
	v_mul_f32_e32 v142, v227, v142
	v_mul_f32_e32 v143, v227, v143
	v_cvt_pk_bf16_f32 v228, v100, v104
	v_cvt_pk_bf16_f32 v229, v108, v112
	v_cvt_pk_bf16_f32 v230, v116, v132
	v_cvt_pk_bf16_f32 v231, v136, v140
	global_store_dwordx4 v214, v[228:231], s[64:65] sc1
	v_cvt_pk_bf16_f32 v232, v101, v105
	v_cvt_pk_bf16_f32 v233, v109, v113
	v_cvt_pk_bf16_f32 v234, v117, v133
	v_cvt_pk_bf16_f32 v235, v137, v141
	global_store_dwordx4 v215, v[232:235], s[64:65] sc1
	v_cvt_pk_bf16_f32 v228, v102, v106
	v_cvt_pk_bf16_f32 v229, v110, v114
	v_cvt_pk_bf16_f32 v230, v118, v134
	v_cvt_pk_bf16_f32 v231, v138, v142
	global_store_dwordx4 v219, v[228:231], s[64:65] sc1
	v_cvt_pk_bf16_f32 v232, v103, v107
	v_cvt_pk_bf16_f32 v233, v111, v115
	v_cvt_pk_bf16_f32 v234, v119, v135
	v_cvt_pk_bf16_f32 v235, v139, v143
	global_store_dwordx4 v236, v[232:235], s[64:65] sc1
	global_load_dwordx4 v[100:103], v2, s[60:61] offset:128 sc1 nt
	global_load_dwordx4 v[104:107], v120, s[60:61] offset:128 sc1 nt
	global_load_dwordx4 v[108:111], v121, s[60:61] offset:128 sc1 nt
	global_load_dwordx4 v[112:115], v126, s[60:61] offset:128 sc1 nt
	global_load_dwordx4 v[116:119], v144, s[60:61] offset:128 sc1 nt
	global_load_dwordx4 v[132:135], v145, s[60:61] offset:128 sc1 nt
	global_load_dwordx4 v[136:139], v147, s[60:61] offset:128 sc1 nt
	global_load_dwordx4 v[140:143], v165, s[60:61] offset:128 sc1 nt
	s_add_u32 s64, s64, s72
	s_addc_u32 s65, s65, s73
	s_waitcnt vmcnt(32)
	v_mul_f32_e32 v148, v220, v148
	v_mul_f32_e32 v149, v220, v149
	v_mul_f32_e32 v150, v220, v150
	v_mul_f32_e32 v151, v220, v151
	v_mul_f32_e32 v152, v221, v152
	v_mul_f32_e32 v153, v221, v153
	v_mul_f32_e32 v154, v221, v154
	v_mul_f32_e32 v155, v221, v155
	v_mul_f32_e32 v156, v222, v156
	v_mul_f32_e32 v157, v222, v157
	v_mul_f32_e32 v158, v222, v158
	v_mul_f32_e32 v159, v222, v159
	v_mul_f32_e32 v160, v223, v160
	v_mul_f32_e32 v161, v223, v161
	v_mul_f32_e32 v162, v223, v162
	v_mul_f32_e32 v163, v223, v163
	v_mul_f32_e32 v166, v224, v166
	v_mul_f32_e32 v167, v224, v167
	v_mul_f32_e32 v168, v224, v168
	v_mul_f32_e32 v169, v224, v169
	v_mul_f32_e32 v170, v225, v170
	v_mul_f32_e32 v171, v225, v171
	v_mul_f32_e32 v172, v225, v172
	v_mul_f32_e32 v173, v225, v173
	v_mul_f32_e32 v174, v226, v174
	v_mul_f32_e32 v175, v226, v175
	v_mul_f32_e32 v176, v226, v176
	v_mul_f32_e32 v177, v226, v177
	v_mul_f32_e32 v178, v227, v178
	v_mul_f32_e32 v179, v227, v179
	v_mul_f32_e32 v180, v227, v180
	v_mul_f32_e32 v181, v227, v181
	v_cvt_pk_bf16_f32 v228, v148, v152
	v_cvt_pk_bf16_f32 v229, v156, v160
	v_cvt_pk_bf16_f32 v230, v166, v170
	v_cvt_pk_bf16_f32 v231, v174, v178
	global_store_dwordx4 v214, v[228:231], s[66:67] sc1
	v_cvt_pk_bf16_f32 v232, v149, v153
	v_cvt_pk_bf16_f32 v233, v157, v161
	v_cvt_pk_bf16_f32 v234, v167, v171
	v_cvt_pk_bf16_f32 v235, v175, v179
	global_store_dwordx4 v215, v[232:235], s[66:67] sc1
	v_cvt_pk_bf16_f32 v228, v150, v154
	v_cvt_pk_bf16_f32 v229, v158, v162
	v_cvt_pk_bf16_f32 v230, v168, v172
	v_cvt_pk_bf16_f32 v231, v176, v180
	global_store_dwordx4 v219, v[228:231], s[66:67] sc1
	v_cvt_pk_bf16_f32 v232, v151, v155
	v_cvt_pk_bf16_f32 v233, v159, v163
	v_cvt_pk_bf16_f32 v234, v169, v173
	v_cvt_pk_bf16_f32 v235, v177, v181
	global_store_dwordx4 v236, v[232:235], s[66:67] sc1
	global_load_dwordx4 v[148:151], v2, s[60:61] offset:256 sc1 nt
	global_load_dwordx4 v[152:155], v120, s[60:61] offset:256 sc1 nt
	global_load_dwordx4 v[156:159], v121, s[60:61] offset:256 sc1 nt
	global_load_dwordx4 v[160:163], v126, s[60:61] offset:256 sc1 nt
	global_load_dwordx4 v[166:169], v144, s[60:61] offset:256 sc1 nt
	global_load_dwordx4 v[170:173], v145, s[60:61] offset:256 sc1 nt
	global_load_dwordx4 v[174:177], v147, s[60:61] offset:256 sc1 nt
	global_load_dwordx4 v[178:181], v165, s[60:61] offset:256 sc1 nt
	s_add_u32 s66, s66, s72
	s_addc_u32 s67, s67, s73
	s_waitcnt vmcnt(36)
; #define LAS __attribute__((address_space(3)))
; __device__ __forceinline__ unsigned cvt_pk_bf16(float lo, float hi) { unsigned r; asm volatile("v_cvt_pk_bf16_f32 %0, %1, %2" : "=v"(r) : "v"(lo), "v"(hi)); return r; }
; template <bool NT = true> __device__ __forceinline__ void tr_load(const TrDesc& d, f32x4 (&v)[8], int lane) {
;     const float* sp = d.src + (size_t)(lane >> 3) * d.ldn + 4 * (lane & 7);
; #pragma unroll
;     for (int i = 0; i < 8; ++i) v[i] = NT ? __builtin_nontemporal_load((const f32x4*)(sp + (size_t)(8 * i) * d.ldn)) : *(const f32x4*)(sp + (size_t)(8 * i) * d.ldn);
; }
; template <bool NT = true> __device__ __forceinline__ void tr_finish(const TrDesc& d, const f32x4 (&v)[8], LAS float* scr, int lane) {
;     const int c = lane & 7;
;     f32x4 g0 = {1.f, 1.f, 1.f, 1.f}, g1 = {1.f, 1.f, 1.f, 1.f};
;     if (d.gain) { g0 = *(const f32x4*)(d.gain + 8 * c); g1 = *(const f32x4*)(d.gain + 8 * c + 4); }
; #pragma unroll
;     for (int i = 0; i < 8; ++i) { LAS float* w = scr + (8 * i + (lane >> 3)) * 33 + 4 * c; w[0] = v[i].x; w[1] = v[i].y; w[2] = v[i].z; w[3] = v[i].w; }
;     LDS_WAIT(); asm volatile("" ::: "memory");
; #pragma unroll
;     for (int j = 0; j < 4; ++j) { const int n = (lane >> 3) + 8 * j; const LAS float* s = scr + (8 * c) * 33 + n;
;         u32x4 o; o.x = cvt_pk_bf16(s[0 * 33] * g0.x, s[1 * 33] * g0.y); o.y = cvt_pk_bf16(s[2 * 33] * g0.z, s[3 * 33] * g0.w); o.z = cvt_pk_bf16(s[4 * 33] * g1.x, s[5 * 33] * g1.y); o.w = cvt_pk_bf16(s[6 * 33] * g1.z, s[7 * 33] * g1.w);
;         if (NT) __builtin_nontemporal_store(o, (u32x4*)(d.dst + (size_t)n * d.K + 8 * c)); else *(u32x4*)(d.dst + (size_t)n * d.K + 8 * c) = o; }
; template <class F, bool NT = true> __device__ __forceinline__ void tr_run(F item, int first, int step, int n, LAS float* scr, int lane) {
;     ...
;     for (int it = first; it < n; it += 3 * step) {
;         const bool h1 = it + step < n, h2 = it + 2 * step < n, h3 = it + 3 * step < n, h4 = it + 4 * step < n;
;         if (h2) { dc = item(it + 2 * step); tr_load<NT>(dc, vc, lane); }
;         tr_finish<NT>(da, va, scr, lane);
;         if (h3) { da = item(it + 3 * step); tr_load<NT>(da, va, lane); }
;         if (h1) tr_finish<NT>(db, vb, scr, lane);
;         if (h4) { db = item(it + 4 * step); tr_load<NT>(db, vb, lane); }
;         if (h2) tr_finish<NT>(dc, vc, scr, lane);
;     }
	v_mul_f32_e32 v182, v220, v182
	v_mul_f32_e32 v183, v220, v183
	v_mul_f32_e32 v184, v220, v184
	v_mul_f32_e32 v185, v220, v185
	v_mul_f32_e32 v186, v221, v186
	v_mul_f32_e32 v187, v221, v187
	v_mul_f32_e32 v188, v221, v188
	v_mul_f32_e32 v189, v221, v189
	v_mul_f32_e32 v190, v222, v190
	v_mul_f32_e32 v191, v222, v191
	v_mul_f32_e32 v192, v222, v192
	v_mul_f32_e32 v193, v222, v193
	v_mul_f32_e32 v194, v223, v194
	v_mul_f32_e32 v195, v223, v195
	v_mul_f32_e32 v196, v223, v196
	v_mul_f32_e32 v197, v223, v197
	v_mul_f32_e32 v198, v224, v198
	v_mul_f32_e32 v199, v224, v199
	v_mul_f32_e32 v200, v224, v200
	v_mul_f32_e32 v201, v224, v201
	v_mul_f32_e32 v202, v225, v202
	v_mul_f32_e32 v203, v225, v203
	v_mul_f32_e32 v204, v225, v204
	v_mul_f32_e32 v205, v225, v205
	v_mul_f32_e32 v206, v226, v206
	v_mul_f32_e32 v207, v226, v207
	v_mul_f32_e32 v208, v226, v208
	v_mul_f32_e32 v209, v226, v209
	v_mul_f32_e32 v210, v227, v210
	v_mul_f32_e32 v211, v227, v211
	v_mul_f32_e32 v212, v227, v212
	v_mul_f32_e32 v213, v227, v213
	v_cvt_pk_bf16_f32 v228, v182, v186
	v_cvt_pk_bf16_f32 v229, v190, v194
	v_cvt_pk_bf16_f32 v230, v198, v202
	v_cvt_pk_bf16_f32 v231, v206, v210
	global_store_dwordx4 v214, v[228:231], s[68:69] sc1
	v_cvt_pk_bf16_f32 v232, v183, v187
	v_cvt_pk_bf16_f32 v233, v191, v195
	v_cvt_pk_bf16_f32 v234, v199, v203
	v_cvt_pk_bf16_f32 v235, v207, v211
	global_store_dwordx4 v215, v[232:235], s[68:69] sc1
	v_cvt_pk_bf16_f32 v228, v184, v188
	v_cvt_pk_bf16_f32 v229, v192, v196
	v_cvt_pk_bf16_f32 v230, v200, v204
	v_cvt_pk_bf16_f32 v231, v208, v212
	global_store_dwordx4 v219, v[228:231], s[68:69] sc1
	v_cvt_pk_bf16_f32 v232, v185, v189
	v_cvt_pk_bf16_f32 v233, v193, v197
	v_cvt_pk_bf16_f32 v234, v201, v205
	v_cvt_pk_bf16_f32 v235, v209, v213
	global_store_dwordx4 v236, v[232:235], s[68:69] sc1
	global_load_dwordx4 v[182:185], v2, s[60:61] offset:384 sc1 nt
	global_load_dwordx4 v[186:189], v120, s[60:61] offset:384 sc1 nt
	global_load_dwordx4 v[190:193], v121, s[60:61] offset:384 sc1 nt
	global_load_dwordx4 v[194:197], v126, s[60:61] offset:384 sc1 nt
	global_load_dwordx4 v[198:201], v144, s[60:61] offset:384 sc1 nt
	global_load_dwordx4 v[202:205], v145, s[60:61] offset:384 sc1 nt
	global_load_dwordx4 v[206:209], v147, s[60:61] offset:384 sc1 nt
	global_load_dwordx4 v[210:213], v165, s[60:61] offset:384 sc1 nt
	s_add_u32 s68, s68, s72
	s_addc_u32 s69, s69, s73
	s_add_u32 s60, s60, s70
	s_addc_u32 s61, s61, s71
	s_sub_i32 s74, s74, 1
	s_cmp_eq_u32 s74, 1
	s_cbranch_scc1 .Lpz_g_last
.Lpz_g_steady:
	s_waitcnt vmcnt(36)
	v_mul_f32_e32 v6, v220, v6
	v_mul_f32_e32 v7, v220, v7
	v_mul_f32_e32 v8, v220, v8
	v_mul_f32_e32 v9, v220, v9
	v_mul_f32_e32 v10, v221, v10
	v_mul_f32_e32 v11, v221, v11
	v_mul_f32_e32 v12, v221, v12
	v_mul_f32_e32 v13, v221, v13
	v_mul_f32_e32 v14, v222, v14
	v_mul_f32_e32 v15, v222, v15
	v_mul_f32_e32 v16, v222, v16
	v_mul_f32_e32 v17, v222, v17
	v_mul_f32_e32 v18, v223, v18
	v_mul_f32_e32 v19, v223, v19
	v_mul_f32_e32 v20, v223, v20
	v_mul_f32_e32 v21, v223, v21
	v_mul_f32_e32 v22, v224, v22
	v_mul_f32_e32 v23, v224, v23
	v_mul_f32_e32 v24, v224, v24
	v_mul_f32_e32 v25, v224, v25
	v_mul_f32_e32 v26, v225, v26
	v_mul_f32_e32 v27, v225, v27
	v_mul_f32_e32 v28, v225, v28
	v_mul_f32_e32 v29, v225, v29
	v_mul_f32_e32 v30, v226, v30
	v_mul_f32_e32 v31, v226, v31
	v_mul_f32_e32 v32, v226, v32
	v_mul_f32_e32 v33, v226, v33
	v_mul_f32_e32 v66, v227, v66
	v_mul_f32_e32 v67, v227, v67
	v_mul_f32_e32 v68, v227, v68
	v_mul_f32_e32 v69, v227, v69
	v_cvt_pk_bf16_f32 v228, v6, v10
	v_cvt_pk_bf16_f32 v229, v14, v18
	v_cvt_pk_bf16_f32 v230, v22, v26
	v_cvt_pk_bf16_f32 v231, v30, v66
	global_store_dwordx4 v214, v[228:231], s[62:63] sc1
	v_cvt_pk_bf16_f32 v232, v7, v11
	v_cvt_pk_bf16_f32 v233, v15, v19
	v_cvt_pk_bf16_f32 v234, v23, v27
	v_cvt_pk_bf16_f32 v235, v31, v67
	global_store_dwordx4 v215, v[232:235], s[62:63] sc1
	v_cvt_pk_bf16_f32 v228, v8, v12
	v_cvt_pk_bf16_f32 v229, v16, v20
	v_cvt_pk_bf16_f32 v230, v24, v28
	v_cvt_pk_bf16_f32 v231, v32, v68
	global_store_dwordx4 v219, v[228:231], s[62:63] sc1
	v_cvt_pk_bf16_f32 v232, v9, v13
	v_cvt_pk_bf16_f32 v233, v17, v21
	v_cvt_pk_bf16_f32 v234, v25, v29
	v_cvt_pk_bf16_f32 v235, v33, v69
	global_store_dwordx4 v236, v[232:235], s[62:63] sc1
	global_load_dwordx4 v[6:9], v2, s[60:61] offset:0 sc1 nt
	global_load_dwordx4 v[10:13], v120, s[60:61] offset:0 sc1 nt
	global_load_dwordx4 v[14:17], v121, s[60:61] offset:0 sc1 nt
	global_load_dwordx4 v[18:21], v126, s[60:61] offset:0 sc1 nt
	global_load_dwordx4 v[22:25], v144, s[60:61] offset:0 sc1 nt
	global_load_dwordx4 v[26:29], v145, s[60:61] offset:0 sc1 nt
	global_load_dwordx4 v[30:33], v147, s[60:61] offset:0 sc1 nt
	global_load_dwordx4 v[66:69], v165, s[60:61] offset:0 sc1 nt
	s_add_u32 s62, s62, s72
	s_addc_u32 s63, s63, s73
	s_waitcnt vmcnt(36)
; #define LAS __attribute__((address_space(3)))
; __device__ __forceinline__ unsigned cvt_pk_bf16(float lo, float hi) { unsigned r; asm volatile("v_cvt_pk_bf16_f32 %0, %1, %2" : "=v"(r) : "v"(lo), "v"(hi)); return r; }
; template <bool NT = true> __device__ __forceinline__ void tr_load(const TrDesc& d, f32x4 (&v)[8], int lane) {
;     const float* sp = d.src + (size_t)(lane >> 3) * d.ldn + 4 * (lane & 7);
; #pragma unroll
;     for (int i = 0; i < 8; ++i) v[i] = NT ? __builtin_nontemporal_load((const f32x4*)(sp + (size_t)(8 * i) * d.ldn)) : *(const f32x4*)(sp + (size_t)(8 * i) * d.ldn);
; }
; template <bool NT = true> __device__ __forceinline__ void tr_finish(const TrDesc& d, const f32x4 (&v)[8], LAS float* scr, int lane) {
;     const int c = lane & 7;
;     f32x4 g0 = {1.f, 1.f, 1.f, 1.f}, g1 = {1.f, 1.f, 1.f, 1.f};
;     if (d.gain) { g0 = *(const f32x4*)(d.gain + 8 * c); g1 = *(const f32x4*)(d.gain + 8 * c + 4); }
; #pragma unroll
;     for (int i = 0; i < 8; ++i) { LAS float* w = scr + (8 * i + (lane >> 3)) * 33 + 4 * c; w[0] = v[i].x; w[1] = v[i].y; w[2] = v[i].z; w[3] = v[i].w; }
;     LDS_WAIT(); asm volatile("" ::: "memory");
; #pragma unroll
;     for (int j = 0; j < 4; ++j) { const int n = (lane >> 3) + 8 * j; const LAS float* s = scr + (8 * c) * 33 + n;
;         u32x4 o; o.x = cvt_pk_bf16(s[0 * 33] * g0.x, s[1 * 33] * g0.y); o.y = cvt_pk_bf16(s[2 * 33] * g0.z, s[3 * 33] * g0.w); o.z = cvt_pk_bf16(s[4 * 33] * g1.x, s[5 * 33] * g1.y); o.w = cvt_pk_bf16(s[6 * 33] * g1.z, s[7 * 33] * g1.w);
;         if (NT) __builtin_nontemporal_store(o, (u32x4*)(d.dst + (size_t)n * d.K + 8 * c)); else *(u32x4*)(d.dst + (size_t)n * d.K + 8 * c) = o; }
; template <class F, bool NT = true> __device__ __forceinline__ void tr_run(F item, int first, int step, int n, LAS float* scr, int lane) {
;     ...
;     for (int it = first; it < n; it += 3 * step) {
;         const bool h1 = it + step < n, h2 = it + 2 * step < n, h3 = it + 3 * step < n, h4 = it + 4 * step < n;
;         if (h2) { dc = item(it + 2 * step); tr_load<NT>(dc, vc, lane); }
;         tr_finish<NT>(da, va, scr, lane);
;         if (h3) { da = item(it + 3 * step); tr_load<NT>(da, va, lane); }
;         if (h1) tr_finish<NT>(db, vb, scr, lane);
;         if (h4) { db = item(it + 4 * step); tr_load<NT>(db, vb, lane); }
;         if (h2) tr_finish<NT>(dc, vc, scr, lane);
;     }
	v_mul_f32_e32 v100, v220, v100
	v_mul_f32_e32 v101, v220, v101
	v_mul_f32_e32 v102, v220, v102
	v_mul_f32_e32 v103, v220, v103
	v_mul_f32_e32 v104, v221, v104
	v_mul_f32_e32 v105, v221, v105
	v_mul_f32_e32 v106, v221, v106
	v_mul_f32_e32 v107, v221, v107
	v_mul_f32_e32 v108, v222, v108
	v_mul_f32_e32 v109, v222, v109
	v_mul_f32_e32 v110, v222, v110
	v_mul_f32_e32 v111, v222, v111
	v_mul_f32_e32 v112, v223, v112
	v_mul_f32_e32 v113, v223, v113
	v_mul_f32_e32 v114, v223, v114
	v_mul_f32_e32 v115, v223, v115
	v_mul_f32_e32 v116, v224, v116
	v_mul_f32_e32 v117, v224, v117
	v_mul_f32_e32 v118, v224, v118
	v_mul_f32_e32 v119, v224, v119
	v_mul_f32_e32 v132, v225, v132
	v_mul_f32_e32 v133, v225, v133
	v_mul_f32_e32 v134, v225, v134
	v_mul_f32_e32 v135, v225, v135
	v_mul_f32_e32 v136, v226, v136
	v_mul_f32_e32 v137, v226, v137
	v_mul_f32_e32 v138, v226, v138
	v_mul_f32_e32 v139, v226, v139
	v_mul_f32_e32 v140, v227, v140
	v_mul_f32_e32 v141, v227, v141
	v_mul_f32_e32 v142, v227, v142
	v_mul_f32_e32 v143, v227, v143
	v_cvt_pk_bf16_f32 v228, v100, v104
	v_cvt_pk_bf16_f32 v229, v108, v112
	v_cvt_pk_bf16_f32 v230, v116, v132
	v_cvt_pk_bf16_f32 v231, v136, v140
	global_store_dwordx4 v214, v[228:231], s[64:65] sc1
	v_cvt_pk_bf16_f32 v232, v101, v105
	v_cvt_pk_bf16_f32 v233, v109, v113
	v_cvt_pk_bf16_f32 v234, v117, v133
	v_cvt_pk_bf16_f32 v235, v137, v141
	global_store_dwordx4 v215, v[232:235], s[64:65] sc1
	v_cvt_pk_bf16_f32 v228, v102, v106
	v_cvt_pk_bf16_f32 v229, v110, v114
	v_cvt_pk_bf16_f32 v230, v118, v134
	v_cvt_pk_bf16_f32 v231, v138, v142
	global_store_dwordx4 v219, v[228:231], s[64:65] sc1
	v_cvt_pk_bf16_f32 v232, v103, v107
	v_cvt_pk_bf16_f32 v233, v111, v115
	v_cvt_pk_bf16_f32 v234, v119, v135
	v_cvt_pk_bf16_f32 v235, v139, v143
	global_store_dwordx4 v236, v[232:235], s[64:65] sc1
	global_load_dwordx4 v[100:103], v2, s[60:61] offset:128 sc1 nt
	global_load_dwordx4 v[104:107], v120, s[60:61] offset:128 sc1 nt
	global_load_dwordx4 v[108:111], v121, s[60:61] offset:128 sc1 nt
	global_load_dwordx4 v[112:115], v126, s[60:61] offset:128 sc1 nt
	global_load_dwordx4 v[116:119], v144, s[60:61] offset:128 sc1 nt
	global_load_dwordx4 v[132:135], v145, s[60:61] offset:128 sc1 nt
	global_load_dwordx4 v[136:139], v147, s[60:61] offset:128 sc1 nt
	global_load_dwordx4 v[140:143], v165, s[60:61] offset:128 sc1 nt
	s_add_u32 s64, s64, s72
	s_addc_u32 s65, s65, s73
	s_waitcnt vmcnt(36)
	v_mul_f32_e32 v148, v220, v148
	v_mul_f32_e32 v149, v220, v149
	v_mul_f32_e32 v150, v220, v150
	v_mul_f32_e32 v151, v220, v151
	v_mul_f32_e32 v152, v221, v152
	v_mul_f32_e32 v153, v221, v153
	v_mul_f32_e32 v154, v221, v154
	v_mul_f32_e32 v155, v221, v155
	v_mul_f32_e32 v156, v222, v156
	v_mul_f32_e32 v157, v222, v157
	v_mul_f32_e32 v158, v222, v158
	v_mul_f32_e32 v159, v222, v159
	v_mul_f32_e32 v160, v223, v160
	v_mul_f32_e32 v161, v223, v161
	v_mul_f32_e32 v162, v223, v162
	v_mul_f32_e32 v163, v223, v163
	v_mul_f32_e32 v166, v224, v166
	v_mul_f32_e32 v167, v224, v167
	v_mul_f32_e32 v168, v224, v168
	v_mul_f32_e32 v169, v224, v169
	v_mul_f32_e32 v170, v225, v170
	v_mul_f32_e32 v171, v225, v171
	v_mul_f32_e32 v172, v225, v172
	v_mul_f32_e32 v173, v225, v173
	v_mul_f32_e32 v174, v226, v174
	v_mul_f32_e32 v175, v226, v175
	v_mul_f32_e32 v176, v226, v176
	v_mul_f32_e32 v177, v226, v177
	v_mul_f32_e32 v178, v227, v178
	v_mul_f32_e32 v179, v227, v179
	v_mul_f32_e32 v180, v227, v180
	v_mul_f32_e32 v181, v227, v181
	v_cvt_pk_bf16_f32 v228, v148, v152
	v_cvt_pk_bf16_f32 v229, v156, v160
	v_cvt_pk_bf16_f32 v230, v166, v170
	v_cvt_pk_bf16_f32 v231, v174, v178
	global_store_dwordx4 v214, v[228:231], s[66:67] sc1
	v_cvt_pk_bf16_f32 v232, v149, v153
	v_cvt_pk_bf16_f32 v233, v157, v161
	v_cvt_pk_bf16_f32 v234, v167, v171
	v_cvt_pk_bf16_f32 v235, v175, v179
	global_store_dwordx4 v215, v[232:235], s[66:67] sc1
	v_cvt_pk_bf16_f32 v228, v150, v154
	v_cvt_pk_bf16_f32 v229, v158, v162
	v_cvt_pk_bf16_f32 v230, v168, v172
	v_cvt_pk_bf16_f32 v231, v176, v180
	global_store_dwordx4 v219, v[228:231], s[66:67] sc1
	v_cvt_pk_bf16_f32 v232, v151, v155
	v_cvt_pk_bf16_f32 v233, v159, v163
	v_cvt_pk_bf16_f32 v234, v169, v173
	v_cvt_pk_bf16_f32 v235, v177, v181
	global_store_dwordx4 v236, v[232:235], s[66:67] sc1
	global_load_dwordx4 v[148:151], v2, s[60:61] offset:256 sc1 nt
	global_load_dwordx4 v[152:155], v120, s[60:61] offset:256 sc1 nt
	global_load_dwordx4 v[156:159], v121, s[60:61] offset:256 sc1 nt
	global_load_dwordx4 v[160:163], v126, s[60:61] offset:256 sc1 nt
	global_load_dwordx4 v[166:169], v144, s[60:61] offset:256 sc1 nt
	global_load_dwordx4 v[170:173], v145, s[60:61] offset:256 sc1 nt
	global_load_dwordx4 v[174:177], v147, s[60:61] offset:256 sc1 nt
	global_load_dwordx4 v[178:181], v165, s[60:61] offset:256 sc1 nt
	s_add_u32 s66, s66, s72
	s_addc_u32 s67, s67, s73
	s_waitcnt vmcnt(36)
; #define LAS __attribute__((address_space(3)))
; __device__ __forceinline__ unsigned cvt_pk_bf16(float lo, float hi) { unsigned r; asm volatile("v_cvt_pk_bf16_f32 %0, %1, %2" : "=v"(r) : "v"(lo), "v"(hi)); return r; }
; template <bool NT = true> __device__ __forceinline__ void tr_load(const TrDesc& d, f32x4 (&v)[8], int lane) {
;     const float* sp = d.src + (size_t)(lane >> 3) * d.ldn + 4 * (lane & 7);
; #pragma unroll
;     for (int i = 0; i < 8; ++i) v[i] = NT ? __builtin_nontemporal_load((const f32x4*)(sp + (size_t)(8 * i) * d.ldn)) : *(const f32x4*)(sp + (size_t)(8 * i) * d.ldn);
; }
; template <bool NT = true> __device__ __forceinline__ void tr_finish(const TrDesc& d, const f32x4 (&v)[8], LAS float* scr, int lane) {
;     const int c = lane & 7;
;     f32x4 g0 = {1.f, 1.f, 1.f, 1.f}, g1 = {1.f, 1.f, 1.f, 1.f};
;     if (d.gain) { g0 = *(const f32x4*)(d.gain + 8 * c); g1 = *(const f32x4*)(d.gain + 8 * c + 4); }
; #pragma unroll
;     for (int i = 0; i < 8; ++i) { LAS float* w = scr + (8 * i + (lane >> 3)) * 33 + 4 * c; w[0] = v[i].x; w[1] = v[i].y; w[2] = v[i].z; w[3] = v[i].w; }
;     LDS_WAIT(); asm volatile("" ::: "memory");
; #pragma unroll
;     for (int j = 0; j < 4; ++j) { const int n = (lane >> 3) + 8 * j; const LAS float* s = scr + (8 * c) * 33 + n;
;         u32x4 o; o.x = cvt_pk_bf16(s[0 * 33] * g0.x, s[1 * 33] * g0.y); o.y = cvt_pk_bf16(s[2 * 33] * g0.z, s[3 * 33] * g0.w); o.z = cvt_pk_bf16(s[4 * 33] * g1.x, s[5 * 33] * g1.y); o.w = cvt_pk_bf16(s[6 * 33] * g1.z, s[7 * 33] * g1.w);
;         if (NT) __builtin_nontemporal_store(o, (u32x4*)(d.dst + (size_t)n * d.K + 8 * c)); else *(u32x4*)(d.dst + (size_t)n * d.K + 8 * c) = o; }
; template <class F, bool NT = true> __device__ __forceinline__ void tr_run(F item, int first, int step, int n, LAS float* scr, int lane) {
;     ...
;     for (int it = first; it < n; it += 3 * step) {
;         const bool h1 = it + step < n, h2 = it + 2 * step < n, h3 = it + 3 * step < n, h4 = it + 4 * step < n;
;         if (h2) { dc = item(it + 2 * step); tr_load<NT>(dc, vc, lane); }
;         tr_finish<NT>(da, va, scr, lane);
;         if (h3) { da = item(it + 3 * step); tr_load<NT>(da, va, lane); }
;         if (h1) tr_finish<NT>(db, vb, scr, lane);
;         if (h4) { db = item(it + 4 * step); tr_load<NT>(db, vb, lane); }
;         if (h2) tr_finish<NT>(dc, vc, scr, lane);
;     }
	v_mul_f32_e32 v182, v220, v182
	v_mul_f32_e32 v183, v220, v183
	v_mul_f32_e32 v184, v220, v184
	v_mul_f32_e32 v185, v220, v185
	v_mul_f32_e32 v186, v221, v186
	v_mul_f32_e32 v187, v221, v187
	v_mul_f32_e32 v188, v221, v188
	v_mul_f32_e32 v189, v221, v189
	v_mul_f32_e32 v190, v222, v190
	v_mul_f32_e32 v191, v222, v191
	v_mul_f32_e32 v192, v222, v192
	v_mul_f32_e32 v193, v222, v193
	v_mul_f32_e32 v194, v223, v194
	v_mul_f32_e32 v195, v223, v195
	v_mul_f32_e32 v196, v223, v196
	v_mul_f32_e32 v197, v223, v197
	v_mul_f32_e32 v198, v224, v198
	v_mul_f32_e32 v199, v224, v199
	v_mul_f32_e32 v200, v224, v200
	v_mul_f32_e32 v201, v224, v201
	v_mul_f32_e32 v202, v225, v202
	v_mul_f32_e32 v203, v225, v203
	v_mul_f32_e32 v204, v225, v204
	v_mul_f32_e32 v205, v225, v205
	v_mul_f32_e32 v206, v226, v206
	v_mul_f32_e32 v207, v226, v207
	v_mul_f32_e32 v208, v226, v208
	v_mul_f32_e32 v209, v226, v209
	v_mul_f32_e32 v210, v227, v210
	v_mul_f32_e32 v211, v227, v211
	v_mul_f32_e32 v212, v227, v212
	v_mul_f32_e32 v213, v227, v213
	v_cvt_pk_bf16_f32 v228, v182, v186
	v_cvt_pk_bf16_f32 v229, v190, v194
	v_cvt_pk_bf16_f32 v230, v198, v202
	v_cvt_pk_bf16_f32 v231, v206, v210
	global_store_dwordx4 v214, v[228:231], s[68:69] sc1
	v_cvt_pk_bf16_f32 v232, v183, v187
	v_cvt_pk_bf16_f32 v233, v191, v195
	v_cvt_pk_bf16_f32 v234, v199, v203
	v_cvt_pk_bf16_f32 v235, v207, v211
	global_store_dwordx4 v215, v[232:235], s[68:69] sc1
	v_cvt_pk_bf16_f32 v228, v184, v188
	v_cvt_pk_bf16_f32 v229, v192, v196
	v_cvt_pk_bf16_f32 v230, v200, v204
	v_cvt_pk_bf16_f32 v231, v208, v212
	global_store_dwordx4 v219, v[228:231], s[68:69] sc1
	v_cvt_pk_bf16_f32 v232, v185, v189
	v_cvt_pk_bf16_f32 v233, v193, v197
	v_cvt_pk_bf16_f32 v234, v201, v205
	v_cvt_pk_bf16_f32 v235, v209, v213
	global_store_dwordx4 v236, v[232:235], s[68:69] sc1
	global_load_dwordx4 v[182:185], v2, s[60:61] offset:384 sc1 nt
	global_load_dwordx4 v[186:189], v120, s[60:61] offset:384 sc1 nt
	global_load_dwordx4 v[190:193], v121, s[60:61] offset:384 sc1 nt
	global_load_dwordx4 v[194:197], v126, s[60:61] offset:384 sc1 nt
	global_load_dwordx4 v[198:201], v144, s[60:61] offset:384 sc1 nt
	global_load_dwordx4 v[202:205], v145, s[60:61] offset:384 sc1 nt
	global_load_dwordx4 v[206:209], v147, s[60:61] offset:384 sc1 nt
	global_load_dwordx4 v[210:213], v165, s[60:61] offset:384 sc1 nt
	s_add_u32 s68, s68, s72
	s_addc_u32 s69, s69, s73
	s_add_u32 s60, s60, s70
	s_addc_u32 s61, s61, s71
	s_sub_i32 s74, s74, 1
	s_cmp_eq_u32 s74, 1
	s_cbranch_scc0 .Lpz_g_steady

; #define LAS __attribute__((address_space(3)))
; __device__ __forceinline__ unsigned cvt_pk_bf16(float lo, float hi) { unsigned r; asm volatile("v_cvt_pk_bf16_f32 %0, %1, %2" : "=v"(r) : "v"(lo), "v"(hi)); return r; }
; #define LDS_WAIT() asm volatile("s_waitcnt lgkmcnt(0)" ::: "memory")
; __device__ __forceinline__ unsigned cvt_pk_bf16(float lo, float hi) { unsigned r; asm volatile("v_cvt_pk_bf16_f32 %0, %1, %2" : "=v"(r) : "v"(lo), "v"(hi)); return r; }
; template <bool NT = true> __device__ __forceinline__ void tr_load(const TrDesc& d, f32x4 (&v)[8], int lane) {
;     const float* sp = d.src + (size_t)(lane >> 3) * d.ldn + 4 * (lane & 7);
; #pragma unroll
;     for (int i = 0; i < 8; ++i) v[i] = NT ? __builtin_nontemporal_load((const f32x4*)(sp + (size_t)(8 * i) * d.ldn)) : *(const f32x4*)(sp + (size_t)(8 * i) * d.ldn);
; }
; template <bool NT = true> __device__ __forceinline__ void tr_finish(const TrDesc& d, const f32x4 (&v)[8], LAS float* scr, int lane) {
;     const int c = lane & 7;
;     f32x4 g0 = {1.f, 1.f, 1.f, 1.f}, g1 = {1.f, 1.f, 1.f, 1.f};
;     if (d.gain) { g0 = *(const f32x4*)(d.gain + 8 * c); g1 = *(const f32x4*)(d.gain + 8 * c + 4); }
; #pragma unroll
;     for (int i = 0; i < 8; ++i) { LAS float* w = scr + (8 * i + (lane >> 3)) * 33 + 4 * c; w[0] = v[i].x; w[1] = v[i].y; w[2] = v[i].z; w[3] = v[i].w; }
;     LDS_WAIT(); asm volatile("" ::: "memory");
; #pragma unroll
;     for (int j = 0; j < 4; ++j) { const int n = (lane >> 3) + 8 * j; const LAS float* s = scr + (8 * c) * 33 + n;
;         u32x4 o; o.x = cvt_pk_bf16(s[0 * 33] * g0.x, s[1 * 33] * g0.y); o.y = cvt_pk_bf16(s[2 * 33] * g0.z, s[3 * 33] * g0.w); o.z = cvt_pk_bf16(s[4 * 33] * g1.x, s[5 * 33] * g1.y); o.w = cvt_pk_bf16(s[6 * 33] * g1.z, s[7 * 33] * g1.w);
;         if (NT) __builtin_nontemporal_store(o, (u32x4*)(d.dst + (size_t)n * d.K + 8 * c)); else *(u32x4*)(d.dst + (size_t)n * d.K + 8 * c) = o; }
.Lpz_nogain:
	global_load_dwordx4 v[6:9], v2, s[60:61] offset:0 sc1 nt
	global_load_dwordx4 v[10:13], v120, s[60:61] offset:0 sc1 nt
	global_load_dwordx4 v[14:17], v121, s[60:61] offset:0 sc1 nt
	global_load_dwordx4 v[18:21], v126, s[60:61] offset:0 sc1 nt
	global_load_dwordx4 v[22:25], v144, s[60:61] offset:0 sc1 nt
	global_load_dwordx4 v[26:29], v145, s[60:61] offset:0 sc1 nt
	global_load_dwordx4 v[30:33], v147, s[60:61] offset:0 sc1 nt
	global_load_dwordx4 v[66:69], v165, s[60:61] offset:0 sc1 nt
	global_load_dwordx4 v[100:103], v2, s[60:61] offset:128 sc1 nt
	global_load_dwordx4 v[104:107], v120, s[60:61] offset:128 sc1 nt
	global_load_dwordx4 v[108:111], v121, s[60:61] offset:128 sc1 nt
	global_load_dwordx4 v[112:115], v126, s[60:61] offset:128 sc1 nt
	global_load_dwordx4 v[116:119], v144, s[60:61] offset:128 sc1 nt
	global_load_dwordx4 v[132:135], v145, s[60:61] offset:128 sc1 nt
	global_load_dwordx4 v[136:139], v147, s[60:61] offset:128 sc1 nt
	global_load_dwordx4 v[140:143], v165, s[60:61] offset:128 sc1 nt
	global_load_dwordx4 v[148:151], v2, s[60:61] offset:256 sc1 nt
	global_load_dwordx4 v[152:155], v120, s[60:61] offset:256 sc1 nt
	global_load_dwordx4 v[156:159], v121, s[60:61] offset:256 sc1 nt
	global_load_dwordx4 v[160:163], v126, s[60:61] offset:256 sc1 nt
	global_load_dwordx4 v[166:169], v144, s[60:61] offset:256 sc1 nt
	global_load_dwordx4 v[170:173], v145, s[60:61] offset:256 sc1 nt
	global_load_dwordx4 v[174:177], v147, s[60:61] offset:256 sc1 nt
	global_load_dwordx4 v[178:181], v165, s[60:61] offset:256 sc1 nt
	global_load_dwordx4 v[182:185], v2, s[60:61] offset:384 sc1 nt
	global_load_dwordx4 v[186:189], v120, s[60:61] offset:384 sc1 nt
	global_load_dwordx4 v[190:193], v121, s[60:61] offset:384 sc1 nt
	global_load_dwordx4 v[194:197], v126, s[60:61] offset:384 sc1 nt
	global_load_dwordx4 v[198:201], v144, s[60:61] offset:384 sc1 nt
	global_load_dwordx4 v[202:205], v145, s[60:61] offset:384 sc1 nt
	global_load_dwordx4 v[206:209], v147, s[60:61] offset:384 sc1 nt
	global_load_dwordx4 v[210:213], v165, s[60:61] offset:384 sc1 nt
	s_add_u32 s60, s60, s70
	s_addc_u32 s61, s61, s71
	s_cmp_eq_u32 s74, 1
	s_cbranch_scc1 .Lpz_n_last
	s_waitcnt vmcnt(24)
	v_cvt_pk_bf16_f32 v228, v6, v10
	v_cvt_pk_bf16_f32 v229, v14, v18
	v_cvt_pk_bf16_f32 v230, v22, v26
	v_cvt_pk_bf16_f32 v231, v30, v66
	global_store_dwordx4 v214, v[228:231], s[62:63] sc1
	v_cvt_pk_bf16_f32 v232, v7, v11
	v_cvt_pk_bf16_f32 v233, v15, v19
	v_cvt_pk_bf16_f32 v234, v23, v27
	v_cvt_pk_bf16_f32 v235, v31, v67
	global_store_dwordx4 v215, v[232:235], s[62:63] sc1
	v_cvt_pk_bf16_f32 v228, v8, v12
	v_cvt_pk_bf16_f32 v229, v16, v20
	v_cvt_pk_bf16_f32 v230, v24, v28
	v_cvt_pk_bf16_f32 v231, v32, v68
	global_store_dwordx4 v219, v[228:231], s[62:63] sc1
	v_cvt_pk_bf16_f32 v232, v9, v13
	v_cvt_pk_bf16_f32 v233, v17, v21
	v_cvt_pk_bf16_f32 v234, v25, v29
	v_cvt_pk_bf16_f32 v235, v33, v69
	global_store_dwordx4 v236, v[232:235], s[62:63] sc1
	global_load_dwordx4 v[6:9], v2, s[60:61] offset:0 sc1 nt
	global_load_dwordx4 v[10:13], v120, s[60:61] offset:0 sc1 nt
	global_load_dwordx4 v[14:17], v121, s[60:61] offset:0 sc1 nt
	global_load_dwordx4 v[18:21], v126, s[60:61] offset:0 sc1 nt
	global_load_dwordx4 v[22:25], v144, s[60:61] offset:0 sc1 nt
	global_load_dwordx4 v[26:29], v145, s[60:61] offset:0 sc1 nt
	global_load_dwordx4 v[30:33], v147, s[60:61] offset:0 sc1 nt
	global_load_dwordx4 v[66:69], v165, s[60:61] offset:0 sc1 nt
	s_add_u32 s62, s62, s72
	s_addc_u32 s63, s63, s73
	s_waitcnt vmcnt(28)
	v_cvt_pk_bf16_f32 v228, v100, v104
	v_cvt_pk_bf16_f32 v229, v108, v112
	v_cvt_pk_bf16_f32 v230, v116, v132
	v_cvt_pk_bf16_f32 v231, v136, v140
	global_store_dwordx4 v214, v[228:231], s[64:65] sc1
	v_cvt_pk_bf16_f32 v232, v101, v105
	v_cvt_pk_bf16_f32 v233, v109, v113
	v_cvt_pk_bf16_f32 v234, v117, v133
	v_cvt_pk_bf16_f32 v235, v137, v141
	global_store_dwordx4 v215, v[232:235], s[64:65] sc1
	v_cvt_pk_bf16_f32 v228, v102, v106
	v_cvt_pk_bf16_f32 v229, v110, v114
	v_cvt_pk_bf16_f32 v230, v118, v134
	v_cvt_pk_bf16_f32 v231, v138, v142
	global_store_dwordx4 v219, v[228:231], s[64:65] sc1
	v_cvt_pk_bf16_f32 v232, v103, v107
	v_cvt_pk_bf16_f32 v233, v111, v115
	v_cvt_pk_bf16_f32 v234, v119, v135
	v_cvt_pk_bf16_f32 v235, v139, v143
	global_store_dwordx4 v236, v[232:235], s[64:65] sc1
	global_load_dwordx4 v[100:103], v2, s[60:61] offset:128 sc1 nt
	global_load_dwordx4 v[104:107], v120, s[60:61] offset:128 sc1 nt
	global_load_dwordx4 v[108:111], v121, s[60:61] offset:128 sc1 nt
	global_load_dwordx4 v[112:115], v126, s[60:61] offset:128 sc1 nt
	global_load_dwordx4 v[116:119], v144, s[60:61] offset:128 sc1 nt
	global_load_dwordx4 v[132:135], v145, s[60:61] offset:128 sc1 nt
	global_load_dwordx4 v[136:139], v147, s[60:61] offset:128 sc1 nt
	global_load_dwordx4 v[140:143], v165, s[60:61] offset:128 sc1 nt
	s_add_u32 s64, s64, s72
	s_addc_u32 s65, s65, s73
	s_waitcnt vmcnt(32)
	v_cvt_pk_bf16_f32 v228, v148, v152
	v_cvt_pk_bf16_f32 v229, v156, v160
	v_cvt_pk_bf16_f32 v230, v166, v170
	v_cvt_pk_bf16_f32 v231, v174, v178
	global_store_dwordx4 v214, v[228:231], s[66:67] sc1
	v_cvt_pk_bf16_f32 v232, v149, v153
	v_cvt_pk_bf16_f32 v233, v157, v161
	v_cvt_pk_bf16_f32 v234, v167, v171
	v_cvt_pk_bf16_f32 v235, v175, v179
	global_store_dwordx4 v215, v[232:235], s[66:67] sc1
	v_cvt_pk_bf16_f32 v228, v150, v154
	v_cvt_pk_bf16_f32 v229, v158, v162
	v_cvt_pk_bf16_f32 v230, v168, v172
	v_cvt_pk_bf16_f32 v231, v176, v180
	global_store_dwordx4 v219, v[228:231], s[66:67] sc1
	v_cvt_pk_bf16_f32 v232, v151, v155
	v_cvt_pk_bf16_f32 v233, v159, v163
	v_cvt_pk_bf16_f32 v234, v169, v173
	v_cvt_pk_bf16_f32 v235, v177, v181
	global_store_dwordx4 v236, v[232:235], s[66:67] sc1
	global_load_dwordx4 v[148:151], v2, s[60:61] offset:256 sc1 nt
	global_load_dwordx4 v[152:155], v120, s[60:61] offset:256 sc1 nt
	global_load_dwordx4 v[156:159], v121, s[60:61] offset:256 sc1 nt
	global_load_dwordx4 v[160:163], v126, s[60:61] offset:256 sc1 nt
	global_load_dwordx4 v[166:169], v144, s[60:61] offset:256 sc1 nt
	global_load_dwordx4 v[170:173], v145, s[60:61] offset:256 sc1 nt
	global_load_dwordx4 v[174:177], v147, s[60:61] offset:256 sc1 nt
	global_load_dwordx4 v[178:181], v165, s[60:61] offset:256 sc1 nt
	s_add_u32 s66, s66, s72
	s_addc_u32 s67, s67, s73
	s_waitcnt vmcnt(36)
; #define LAS __attribute__((address_space(3)))
; __device__ __forceinline__ unsigned cvt_pk_bf16(float lo, float hi) { unsigned r; asm volatile("v_cvt_pk_bf16_f32 %0, %1, %2" : "=v"(r) : "v"(lo), "v"(hi)); return r; }
; #define LDS_WAIT() asm volatile("s_waitcnt lgkmcnt(0)" ::: "memory")
; __device__ __forceinline__ unsigned cvt_pk_bf16(float lo, float hi) { unsigned r; asm volatile("v_cvt_pk_bf16_f32 %0, %1, %2" : "=v"(r) : "v"(lo), "v"(hi)); return r; }
; template <bool NT = true> __device__ __forceinline__ void tr_load(const TrDesc& d, f32x4 (&v)[8], int lane) {
;     const float* sp = d.src + (size_t)(lane >> 3) * d.ldn + 4 * (lane & 7);
; #pragma unroll
;     for (int i = 0; i < 8; ++i) v[i] = NT ? __builtin_nontemporal_load((const f32x4*)(sp + (size_t)(8 * i) * d.ldn)) : *(const f32x4*)(sp + (size_t)(8 * i) * d.ldn);
; }
; template <bool NT = true> __device__ __forceinline__ void tr_finish(const TrDesc& d, const f32x4 (&v)[8], LAS float* scr, int lane) {
;     const int c = lane & 7;
;     f32x4 g0 = {1.f, 1.f, 1.f, 1.f}, g1 = {1.f, 1.f, 1.f, 1.f};
;     if (d.gain) { g0 = *(const f32x4*)(d.gain + 8 * c); g1 = *(const f32x4*)(d.gain + 8 * c + 4); }
; #pragma unroll
;     for (int i = 0; i < 8; ++i) { LAS float* w = scr + (8 * i + (lane >> 3)) * 33 + 4 * c; w[0] = v[i].x; w[1] = v[i].y; w[2] = v[i].z; w[3] = v[i].w; }
;     LDS_WAIT(); asm volatile("" ::: "memory");
; #pragma unroll
;     for (int j = 0; j < 4; ++j) { const int n = (lane >> 3) + 8 * j; const LAS float* s = scr + (8 * c) * 33 + n;
;         u32x4 o; o.x = cvt_pk_bf16(s[0 * 33] * g0.x, s[1 * 33] * g0.y); o.y = cvt_pk_bf16(s[2 * 33] * g0.z, s[3 * 33] * g0.w); o.z = cvt_pk_bf16(s[4 * 33] * g1.x, s[5 * 33] * g1.y); o.w = cvt_pk_bf16(s[6 * 33] * g1.z, s[7 * 33] * g1.w);
;         if (NT) __builtin_nontemporal_store(o, (u32x4*)(d.dst + (size_t)n * d.K + 8 * c)); else *(u32x4*)(d.dst + (size_t)n * d.K + 8 * c) = o; }
	v_cvt_pk_bf16_f32 v228, v182, v186
	v_cvt_pk_bf16_f32 v229, v190, v194
	v_cvt_pk_bf16_f32 v230, v198, v202
	v_cvt_pk_bf16_f32 v231, v206, v210
	global_store_dwordx4 v214, v[228:231], s[68:69] sc1
	v_cvt_pk_bf16_f32 v232, v183, v187
	v_cvt_pk_bf16_f32 v233, v191, v195
	v_cvt_pk_bf16_f32 v234, v199, v203
	v_cvt_pk_bf16_f32 v235, v207, v211
	global_store_dwordx4 v215, v[232:235], s[68:69] sc1
	v_cvt_pk_bf16_f32 v228, v184, v188
	v_cvt_pk_bf16_f32 v229, v192, v196
	v_cvt_pk_bf16_f32 v230, v200, v204
	v_cvt_pk_bf16_f32 v231, v208, v212
	global_store_dwordx4 v219, v[228:231], s[68:69] sc1
	v_cvt_pk_bf16_f32 v232, v185, v189
	v_cvt_pk_bf16_f32 v233, v193, v197
	v_cvt_pk_bf16_f32 v234, v201, v205
	v_cvt_pk_bf16_f32 v235, v209, v213
	global_store_dwordx4 v236, v[232:235], s[68:69] sc1
	global_load_dwordx4 v[182:185], v2, s[60:61] offset:384 sc1 nt
	global_load_dwordx4 v[186:189], v120, s[60:61] offset:384 sc1 nt
	global_load_dwordx4 v[190:193], v121, s[60:61] offset:384 sc1 nt
	global_load_dwordx4 v[194:197], v126, s[60:61] offset:384 sc1 nt
	global_load_dwordx4 v[198:201], v144, s[60:61] offset:384 sc1 nt
	global_load_dwordx4 v[202:205], v145, s[60:61] offset:384 sc1 nt
	global_load_dwordx4 v[206:209], v147, s[60:61] offset:384 sc1 nt
	global_load_dwordx4 v[210:213], v165, s[60:61] offset:384 sc1 nt
	s_add_u32 s68, s68, s72
	s_addc_u32 s69, s69, s73
	s_add_u32 s60, s60, s70
	s_addc_u32 s61, s61, s71
	s_sub_i32 s74, s74, 1
	s_cmp_eq_u32 s74, 1
	s_cbranch_scc1 .Lpz_n_last
; #define LAS __attribute__((address_space(3)))
; __device__ __forceinline__ unsigned cvt_pk_bf16(float lo, float hi) { unsigned r; asm volatile("v_cvt_pk_bf16_f32 %0, %1, %2" : "=v"(r) : "v"(lo), "v"(hi)); return r; }
; #define LDS_WAIT() asm volatile("s_waitcnt lgkmcnt(0)" ::: "memory")
; __device__ __forceinline__ unsigned cvt_pk_bf16(float lo, float hi) { unsigned r; asm volatile("v_cvt_pk_bf16_f32 %0, %1, %2" : "=v"(r) : "v"(lo), "v"(hi)); return r; }
; template <bool NT = true> __device__ __forceinline__ void tr_load(const TrDesc& d, f32x4 (&v)[8], int lane) {
;     const float* sp = d.src + (size_t)(lane >> 3) * d.ldn + 4 * (lane & 7);
; #pragma unroll
;     for (int i = 0; i < 8; ++i) v[i] = NT ? __builtin_nontemporal_load((const f32x4*)(sp + (size_t)(8 * i) * d.ldn)) : *(const f32x4*)(sp + (size_t)(8 * i) * d.ldn);
; }
; template <bool NT = true> __device__ __forceinline__ void tr_finish(const TrDesc& d, const f32x4 (&v)[8], LAS float* scr, int lane) {
;     const int c = lane & 7;
;     f32x4 g0 = {1.f, 1.f, 1.f, 1.f}, g1 = {1.f, 1.f, 1.f, 1.f};
;     if (d.gain) { g0 = *(const f32x4*)(d.gain + 8 * c); g1 = *(const f32x4*)(d.gain + 8 * c + 4); }
; #pragma unroll
;     for (int i = 0; i < 8; ++i) { LAS float* w = scr + (8 * i + (lane >> 3)) * 33 + 4 * c; w[0] = v[i].x; w[1] = v[i].y; w[2] = v[i].z; w[3] = v[i].w; }
;     LDS_WAIT(); asm volatile("" ::: "memory");
; #pragma unroll
;     for (int j = 0; j < 4; ++j) { const int n = (lane >> 3) + 8 * j; const LAS float* s = scr + (8 * c) * 33 + n;
;         u32x4 o; o.x = cvt_pk_bf16(s[0 * 33] * g0.x, s[1 * 33] * g0.y); o.y = cvt_pk_bf16(s[2 * 33] * g0.z, s[3 * 33] * g0.w); o.z = cvt_pk_bf16(s[4 * 33] * g1.x, s[5 * 33] * g1.y); o.w = cvt_pk_bf16(s[6 * 33] * g1.z, s[7 * 33] * g1.w);
;         if (NT) __builtin_nontemporal_store(o, (u32x4*)(d.dst + (size_t)n * d.K + 8 * c)); else *(u32x4*)(d.dst + (size_t)n * d.K + 8 * c) = o; }
.Lpz_n_steady:
	s_waitcnt vmcnt(36)
	v_cvt_pk_bf16_f32 v228, v6, v10
	v_cvt_pk_bf16_f32 v229, v14, v18
	v_cvt_pk_bf16_f32 v230, v22, v26
	v_cvt_pk_bf16_f32 v231, v30, v66
	global_store_dwordx4 v214, v[228:231], s[62:63] sc1
	v_cvt_pk_bf16_f32 v232, v7, v11
	v_cvt_pk_bf16_f32 v233, v15, v19
	v_cvt_pk_bf16_f32 v234, v23, v27
	v_cvt_pk_bf16_f32 v235, v31, v67
	global_store_dwordx4 v215, v[232:235], s[62:63] sc1
	v_cvt_pk_bf16_f32 v228, v8, v12
	v_cvt_pk_bf16_f32 v229, v16, v20
	v_cvt_pk_bf16_f32 v230, v24, v28
	v_cvt_pk_bf16_f32 v231, v32, v68
	global_store_dwordx4 v219, v[228:231], s[62:63] sc1
	v_cvt_pk_bf16_f32 v232, v9, v13
	v_cvt_pk_bf16_f32 v233, v17, v21
	v_cvt_pk_bf16_f32 v234, v25, v29
	v_cvt_pk_bf16_f32 v235, v33, v69
	global_store_dwordx4 v236, v[232:235], s[62:63] sc1
	global_load_dwordx4 v[6:9], v2, s[60:61] offset:0 sc1 nt
	global_load_dwordx4 v[10:13], v120, s[60:61] offset:0 sc1 nt
	global_load_dwordx4 v[14:17], v121, s[60:61] offset:0 sc1 nt
	global_load_dwordx4 v[18:21], v126, s[60:61] offset:0 sc1 nt
	global_load_dwordx4 v[22:25], v144, s[60:61] offset:0 sc1 nt
	global_load_dwordx4 v[26:29], v145, s[60:61] offset:0 sc1 nt
	global_load_dwordx4 v[30:33], v147, s[60:61] offset:0 sc1 nt
	global_load_dwordx4 v[66:69], v165, s[60:61] offset:0 sc1 nt
	s_add_u32 s62, s62, s72
	s_addc_u32 s63, s63, s73
	s_waitcnt vmcnt(36)
	v_cvt_pk_bf16_f32 v228, v100, v104
	v_cvt_pk_bf16_f32 v229, v108, v112
	v_cvt_pk_bf16_f32 v230, v116, v132
	v_cvt_pk_bf16_f32 v231, v136, v140
	global_store_dwordx4 v214, v[228:231], s[64:65] sc1
	v_cvt_pk_bf16_f32 v232, v101, v105
	v_cvt_pk_bf16_f32 v233, v109, v113
	v_cvt_pk_bf16_f32 v234, v117, v133
	v_cvt_pk_bf16_f32 v235, v137, v141
	global_store_dwordx4 v215, v[232:235], s[64:65] sc1
	v_cvt_pk_bf16_f32 v228, v102, v106
	v_cvt_pk_bf16_f32 v229, v110, v114
	v_cvt_pk_bf16_f32 v230, v118, v134
	v_cvt_pk_bf16_f32 v231, v138, v142
	global_store_dwordx4 v219, v[228:231], s[64:65] sc1
	v_cvt_pk_bf16_f32 v232, v103, v107
	v_cvt_pk_bf16_f32 v233, v111, v115
	v_cvt_pk_bf16_f32 v234, v119, v135
	v_cvt_pk_bf16_f32 v235, v139, v143
	global_store_dwordx4 v236, v[232:235], s[64:65] sc1
	global_load_dwordx4 v[100:103], v2, s[60:61] offset:128 sc1 nt
	global_load_dwordx4 v[104:107], v120, s[60:61] offset:128 sc1 nt
	global_load_dwordx4 v[108:111], v121, s[60:61] offset:128 sc1 nt
	global_load_dwordx4 v[112:115], v126, s[60:61] offset:128 sc1 nt
	global_load_dwordx4 v[116:119], v144, s[60:61] offset:128 sc1 nt
	global_load_dwordx4 v[132:135], v145, s[60:61] offset:128 sc1 nt
	global_load_dwordx4 v[136:139], v147, s[60:61] offset:128 sc1 nt
	global_load_dwordx4 v[140:143], v165, s[60:61] offset:128 sc1 nt
	s_add_u32 s64, s64, s72
	s_addc_u32 s65, s65, s73
	s_waitcnt vmcnt(36)
	v_cvt_pk_bf16_f32 v228, v148, v152
	v_cvt_pk_bf16_f32 v229, v156, v160
	v_cvt_pk_bf16_f32 v230, v166, v170
	v_cvt_pk_bf16_f32 v231, v174, v178
	global_store_dwordx4 v214, v[228:231], s[66:67] sc1
	v_cvt_pk_bf16_f32 v232, v149, v153
	v_cvt_pk_bf16_f32 v233, v157, v161
	v_cvt_pk_bf16_f32 v234, v167, v171
	v_cvt_pk_bf16_f32 v235, v175, v179
	global_store_dwordx4 v215, v[232:235], s[66:67] sc1
	v_cvt_pk_bf16_f32 v228, v150, v154
	v_cvt_pk_bf16_f32 v229, v158, v162
	v_cvt_pk_bf16_f32 v230, v168, v172
	v_cvt_pk_bf16_f32 v231, v176, v180
	global_store_dwordx4 v219, v[228:231], s[66:67] sc1
	v_cvt_pk_bf16_f32 v232, v151, v155
	v_cvt_pk_bf16_f32 v233, v159, v163
	v_cvt_pk_bf16_f32 v234, v169, v173
	v_cvt_pk_bf16_f32 v235, v177, v181
	global_store_dwordx4 v236, v[232:235], s[66:67] sc1
	global_load_dwordx4 v[148:151], v2, s[60:61] offset:256 sc1 nt
	global_load_dwordx4 v[152:155], v120, s[60:61] offset:256 sc1 nt
	global_load_dwordx4 v[156:159], v121, s[60:61] offset:256 sc1 nt
	global_load_dwordx4 v[160:163], v126, s[60:61] offset:256 sc1 nt
	global_load_dwordx4 v[166:169], v144, s[60:61] offset:256 sc1 nt
	global_load_dwordx4 v[170:173], v145, s[60:61] offset:256 sc1 nt
	global_load_dwordx4 v[174:177], v147, s[60:61] offset:256 sc1 nt
	global_load_dwordx4 v[178:181], v165, s[60:61] offset:256 sc1 nt
	s_add_u32 s66, s66, s72
	s_addc_u32 s67, s67, s73
	s_waitcnt vmcnt(36)
	v_cvt_pk_bf16_f32 v228, v182, v186
	v_cvt_pk_bf16_f32 v229, v190, v194
	v_cvt_pk_bf16_f32 v230, v198, v202
	v_cvt_pk_bf16_f32 v231, v206, v210
	global_store_dwordx4 v214, v[228:231], s[68:69] sc1
	v_cvt_pk_bf16_f32 v232, v183, v187
	v_cvt_pk_bf16_f32 v233, v191, v195
	v_cvt_pk_bf16_f32 v234, v199, v203
	v_cvt_pk_bf16_f32 v235, v207, v211
	global_store_dwordx4 v215, v[232:235], s[68:69] sc1
	v_cvt_pk_bf16_f32 v228, v184, v188
	v_cvt_pk_bf16_f32 v229, v192, v196
	v_cvt_pk_bf16_f32 v230, v200, v204
	v_cvt_pk_bf16_f32 v231, v208, v212
	global_store_dwordx4 v219, v[228:231], s[68:69] sc1
	v_cvt_pk_bf16_f32 v232, v185, v189
	v_cvt_pk_bf16_f32 v233, v193, v197
	v_cvt_pk_bf16_f32 v234, v201, v205
	v_cvt_pk_bf16_f32 v235, v209, v213
	global_store_dwordx4 v236, v[232:235], s[68:69] sc1
	global_load_dwordx4 v[182:185], v2, s[60:61] offset:384 sc1 nt
	global_load_dwordx4 v[186:189], v120, s[60:61] offset:384 sc1 nt
	global_load_dwordx4 v[190:193], v121, s[60:61] offset:384 sc1 nt
	global_load_dwordx4 v[194:197], v126, s[60:61] offset:384 sc1 nt
	global_load_dwordx4 v[198:201], v144, s[60:61] offset:384 sc1 nt
	global_load_dwordx4 v[202:205], v145, s[60:61] offset:384 sc1 nt
	global_load_dwordx4 v[206:209], v147, s[60:61] offset:384 sc1 nt
	global_load_dwordx4 v[210:213], v165, s[60:61] offset:384 sc1 nt
	s_add_u32 s68, s68, s72
	s_addc_u32 s69, s69, s73
	s_add_u32 s60, s60, s70
	s_addc_u32 s61, s61, s71
	s_sub_i32 s74, s74, 1
	s_cmp_eq_u32 s74, 1
	s_cbranch_scc0 .Lpz_n_steady

; #define TR_JOB_GU(W_, WT_, off_, gain_) { constexpr int nnb_ = DFF / 32, nit_ = (DM / 64) * nnb_; \
;     if (r < nit_) { const int kb_ = r / nnb_, nb_ = r % nnb_, c0_ = 32 * nb_; \
;         return TrDesc{(W_) + (size_t)(64 * kb_) * DFF + c0_, (WT_) + (size_t)(256 * (c0_ / 128) + (c0_ % 128) + (off_)) * DM + 64 * kb_, (gain_) + 64 * kb_, DFF, DM}; } r -= nit_; }
; template <bool NT = true> __device__ __forceinline__ void tr_load(const TrDesc& d, f32x4 (&v)[8], int lane) {
;     const float* sp = d.src + (size_t)(lane >> 3) * d.ldn + 4 * (lane & 7);
; #pragma unroll
;     for (int i = 0; i < 8; ++i) v[i] = NT ? __builtin_nontemporal_load((const f32x4*)(sp + (size_t)(8 * i) * d.ldn)) : *(const f32x4*)(sp + (size_t)(8 * i) * d.ldn);
; __device__ __forceinline__ TrDesc p0_item(const Params& p, int it) {
;     unsigned char* ws = p.ws;
;     bf16_t* WAB_IN = (bf16_t*)(ws + WS_WAB_IN); bf16_t* WAB_OUT = (bf16_t*)(ws + WS_WAB_OUT); bf16_t* WGU0 = (bf16_t*)(ws + WS_WGU0); bf16_t* WDN0 = (bf16_t*)(ws + WS_WDN0);
;     bf16_t* WCD_IN = (bf16_t*)(ws + WS_WCD_IN); bf16_t* WGU1 = (bf16_t*)(ws + WS_WGU1);
;     bf16_t* WRG = (bf16_t*)(ws + WS_WRG);
;     int r = it;
;     TR_JOB(p.ab_w_in, AB_IN, DM, 0, 6144, WAB_IN, 0, p.norm_mix)
;     TR_JOB(p.ab_w_in, AB_IN, DM, 6160, 6144, WAB_IN, 6144, p.norm_mix)
;     TR_JOB(p.ab_w_out, DM, DM, 0, DM, WAB_OUT, 0, (const float*)nullptr)
;     TR_JOB_GU(p.ffn_w_gate, WGU0, 0, p.norm_ffn)
;     TR_JOB_GU(p.ffn_w_up, WGU0, 128, p.norm_ffn)
;     TR_JOB(p.ffn_w_down, DM, DFF, 0, DM, WDN0, 0, (const float*)nullptr)
;     TR_JOB(p.cd_w_in, CD_IN, DM, 0, CD_IN, WCD_IN, 0, p.norm_mix + DM)
;     TR_JOB_GU(p.ffn_w_gate + (size_t)DM * DFF, WGU1, 0, p.norm_ffn + DM)
;     TR_JOB_GU(p.ffn_w_up + (size_t)DM * DFF, WGU1, 128, p.norm_ffn + DM)
;     TR_JOB(p.cd_w_out, DM, DM, 0, DM, (bf16_t*)(ws + WS_WCD_OUT), 0, (const float*)nullptr)
;     const int mat = r / 32, rr = r % 32, kb_ = rr / 8, nb_ = rr % 8;
;     const float* W = (mat < 8 ? p.rg_w_x : p.rg_w_a) + (size_t)(mat & 7) * 65536;
;     return TrDesc{W + (size_t)(64 * kb_) * 256 + 32 * nb_, WRG + (size_t)mat * 65536 + (size_t)(32 * nb_) * 256 + 64 * kb_, nullptr, 256, 256};
; }
.LBB0_140:
	v_lshrrev_b32_e32 v109, 3, v164
	v_mul_u32_u24_e32 v2, s19, v109
	v_lshlrev_b32_e32 v146, 2, v0
	v_mov_b32_e32 v107, 0
	v_lshlrev_b32_e32 v106, 2, v2
	v_and_b32_e32 v4, 28, v146
	v_lshl_add_u64 v[2:3], s[6:7], 0, v[106:107]
	v_lshlrev_b32_e32 v106, 2, v4
	s_mov_b32 s9, 0
	v_lshl_add_u64 v[2:3], v[2:3], 0, v[106:107]
	s_lshl_b32 s8, s19, 5
	s_waitcnt vmcnt(5)
	v_lshl_add_u64 v[10:11], v[2:3], 0, s[8:9]
	global_load_dwordx4 v[2:5], v[2:3], off sc1 nt
	s_nop 0
	global_load_dwordx4 v[6:9], v[10:11], off sc1 nt
	v_lshl_add_u64 v[10:11], v[10:11], 0, s[8:9]
	s_waitcnt vmcnt(5)
	v_lshl_add_u64 v[18:19], v[10:11], 0, s[8:9]
	global_load_dwordx4 v[10:13], v[10:11], off sc1 nt
	s_nop 0
	global_load_dwordx4 v[14:17], v[18:19], off sc1 nt
	v_lshl_add_u64 v[18:19], v[18:19], 0, s[8:9]
	s_waitcnt vmcnt(5)
	v_lshl_add_u64 v[26:27], v[18:19], 0, s[8:9]
	global_load_dwordx4 v[18:21], v[18:19], off sc1 nt
	s_nop 0
	global_load_dwordx4 v[22:25], v[26:27], off sc1 nt
	v_lshl_add_u64 v[26:27], v[26:27], 0, s[8:9]
	s_waitcnt vmcnt(6)
	v_lshl_add_u64 v[30:31], v[26:27], 0, s[8:9]
	global_load_dwordx4 v[26:29], v[26:27], off sc1 nt
	s_nop 0
	global_load_dwordx4 v[30:33], v[30:31], off sc1 nt
	v_readlane_b32 s6, v240, 29
	v_readlane_b32 s8, v240, 27
	v_readlane_b32 s7, v240, 30
	v_readlane_b32 s9, v240, 28
	s_add_i32 s16, s6, s8
	s_cmp_gt_i32 s16, 0x23fff
	s_mov_b64 s[8:9], s[4:5]
	s_mov_b64 s[6:7], s[0:1]
	s_mov_b32 s43, s93
	s_cbranch_scc1 .LBB0_169
	s_cmpk_gt_i32 s16, 0xcfff
	s_cselect_b64 s[12:13], -1, 0
	s_and_b64 vcc, exec, s[12:13]
	s_cbranch_vccnz .LBB0_147
	s_add_i32 s22, s16, 0x6000
	s_mul_hi_i32 s6, s22, 0x2aaaaaab
	s_lshr_b32 s7, s6, 31
	s_ashr_i32 s6, s6, 5
	s_add_i32 s8, s6, s7
	s_mul_i32 s6, s8, 0xc0
	s_sub_i32 s9, s22, s6
	s_lshl_b32 s6, s8, 6
	v_readlane_b32 s60, v240, 4
	s_ashr_i32 s7, s6, 31
	s_mul_i32 s8, s8, 0x302000
	v_readlane_b32 s72, v240, 16
	s_mul_hi_i32 s10, s6, 0xc080
	v_readlane_b32 s73, v240, 17
	s_add_u32 s14, s72, s8
	s_addc_u32 s15, s73, s10
	s_lshl_b32 s8, s9, 5
	s_ashr_i32 s9, s8, 31
	s_lshl_b64 s[10:11], s[8:9], 2
	s_add_u32 s10, s14, s10
	s_addc_u32 s11, s15, s11
	s_lshl_b64 s[8:9], s[8:9], 13
	s_add_u32 s14, s33, s8
	s_addc_u32 s15, s42, s9
	s_lshl_b64 s[8:9], s[6:7], 1
	s_add_u32 s8, s14, s8
	v_readlane_b32 s62, v240, 6
	s_addc_u32 s9, s15, s9
	s_lshl_b64 s[6:7], s[6:7], 2
	v_readlane_b32 s63, v240, 7
	s_add_u32 s6, s62, s6
	s_addc_u32 s7, s63, s7
	s_cmp_lg_u64 s[62:63], 0
	s_mov_b64 s[14:15], 0
	s_cselect_b32 s7, s7, 0
	s_cselect_b32 s6, s6, 0
	v_readlane_b32 s61, v240, 5
	v_readlane_b32 s64, v240, 8
	v_readlane_b32 s65, v240, 9
	v_readlane_b32 s66, v240, 10
	v_readlane_b32 s67, v240, 11
	v_readlane_b32 s68, v240, 12
	v_readlane_b32 s69, v240, 13
	v_readlane_b32 s70, v240, 14
	v_readlane_b32 s71, v240, 15
	v_readlane_b32 s74, v240, 18
	v_readlane_b32 s75, v240, 19
	s_branch .LBB0_148

; template <bool NT = true> __device__ __forceinline__ void tr_load(const TrDesc& d, f32x4 (&v)[8], int lane) {
;     const float* sp = d.src + (size_t)(lane >> 3) * d.ldn + 4 * (lane & 7);
; #pragma unroll
;     for (int i = 0; i < 8; ++i) v[i] = NT ? __builtin_nontemporal_load((const f32x4*)(sp + (size_t)(8 * i) * d.ldn)) : *(const f32x4*)(sp + (size_t)(8 * i) * d.ldn);
; template <class F, bool NT = true> __device__ __forceinline__ void tr_run(F item, int first, int step, int n, LAS float* scr, int lane) {
;     ...
;     if (first + step < n) { db = item(first + step); tr_load<NT>(db, vb, lane); }
;     for (int it = first; it < n; it += 3 * step) {
;         const bool h1 = it + step < n, h2 = it + 2 * step < n, h3 = it + 3 * step < n, h4 = it + 4 * step < n;
;         if (h2) { dc = item(it + 2 * step); tr_load<NT>(dc, vc, lane); }
;         tr_finish<NT>(da, va, scr, lane);
;         if (h3) { da = item(it + 3 * step); tr_load<NT>(da, va, lane); }
;         if (h1) tr_finish<NT>(db, vb, scr, lane);
;         if (h4) { db = item(it + 4 * step); tr_load<NT>(db, vb, lane); }
.LBB0_168:
	v_mul_u32_u24_e32 v34, s23, v109
	v_lshlrev_b32_e32 v34, 2, v34
	v_mov_b32_e32 v35, 0
	v_lshl_add_u64 v[36:37], s[10:11], 0, v[34:35]
	v_mov_b32_e32 v107, v35
	s_mov_b32 s13, 0
	v_lshl_add_u64 v[34:35], v[36:37], 0, v[106:107]
	s_lshl_b32 s12, s23, 5
	v_lshl_add_u64 v[42:43], v[34:35], 0, s[12:13]
	global_load_dwordx4 v[34:37], v[34:35], off sc1 nt
	s_nop 0
	global_load_dwordx4 v[38:41], v[42:43], off sc1 nt
	v_lshl_add_u64 v[42:43], v[42:43], 0, s[12:13]
	v_lshl_add_u64 v[50:51], v[42:43], 0, s[12:13]
	global_load_dwordx4 v[42:45], v[42:43], off sc1 nt
	s_nop 0
	global_load_dwordx4 v[46:49], v[50:51], off sc1 nt
	v_lshl_add_u64 v[50:51], v[50:51], 0, s[12:13]
	v_lshl_add_u64 v[58:59], v[50:51], 0, s[12:13]
	global_load_dwordx4 v[50:53], v[50:51], off sc1 nt
	s_nop 0
	global_load_dwordx4 v[54:57], v[58:59], off sc1 nt
	v_lshl_add_u64 v[58:59], v[58:59], 0, s[12:13]
	v_lshl_add_u64 v[62:63], v[58:59], 0, s[12:13]
	global_load_dwordx4 v[58:61], v[58:59], off sc1 nt
	s_nop 0
	global_load_dwordx4 v[62:65], v[62:63], off sc1 nt

; template <bool NT = true> __device__ __forceinline__ void tr_load(const TrDesc& d, f32x4 (&v)[8], int lane) {
;     const float* sp = d.src + (size_t)(lane >> 3) * d.ldn + 4 * (lane & 7);
; #pragma unroll
;     for (int i = 0; i < 8; ++i) v[i] = NT ? __builtin_nontemporal_load((const f32x4*)(sp + (size_t)(8 * i) * d.ldn)) : *(const f32x4*)(sp + (size_t)(8 * i) * d.ldn);
; template <class F, bool NT = true> __device__ __forceinline__ void tr_run(F item, int first, int step, int n, LAS float* scr, int lane) {
;     ...
;     for (int it = first; it < n; it += 3 * step) {
;         const bool h1 = it + step < n, h2 = it + 2 * step < n, h3 = it + 3 * step < n, h4 = it + 4 * step < n;
;         if (h2) { dc = item(it + 2 * step); tr_load<NT>(dc, vc, lane); }
;         tr_finish<NT>(da, va, scr, lane);
;         if (h3) { da = item(it + 3 * step); tr_load<NT>(da, va, lane); }
;         if (h1) tr_finish<NT>(db, vb, scr, lane);
;         if (h4) { db = item(it + 4 * step); tr_load<NT>(db, vb, lane); }
.LBB0_184:
	v_mul_u32_u24_e32 v66, s10, v109
	v_lshlrev_b32_e32 v66, 2, v66
	v_mov_b32_e32 v67, v111
	v_lshl_add_u64 v[66:67], s[20:21], 0, v[66:67]
	v_mov_b32_e32 v107, v111
	v_lshl_add_u64 v[66:67], v[66:67], 0, v[106:107]
	s_lshl_b32 s10, s10, 5
	v_lshl_add_u64 v[74:75], v[66:67], 0, s[10:11]
	global_load_dwordx4 v[66:69], v[66:67], off sc1 nt
	s_nop 0
	global_load_dwordx4 v[70:73], v[74:75], off sc1 nt
	v_lshl_add_u64 v[74:75], v[74:75], 0, s[10:11]
	v_lshl_add_u64 v[82:83], v[74:75], 0, s[10:11]
	global_load_dwordx4 v[74:77], v[74:75], off sc1 nt
	s_nop 0
	global_load_dwordx4 v[78:81], v[82:83], off sc1 nt
	v_lshl_add_u64 v[82:83], v[82:83], 0, s[10:11]
	v_lshl_add_u64 v[90:91], v[82:83], 0, s[10:11]
	global_load_dwordx4 v[82:85], v[82:83], off sc1 nt
	s_nop 0
	global_load_dwordx4 v[86:89], v[90:91], off sc1 nt
	v_lshl_add_u64 v[90:91], v[90:91], 0, s[10:11]
	v_lshl_add_u64 v[94:95], v[90:91], 0, s[10:11]
	global_load_dwordx4 v[90:93], v[90:91], off sc1 nt
	s_nop 0
	global_load_dwordx4 v[94:97], v[94:95], off sc1 nt

; template <bool NT = true> __device__ __forceinline__ void tr_load(const TrDesc& d, f32x4 (&v)[8], int lane) {
;     const float* sp = d.src + (size_t)(lane >> 3) * d.ldn + 4 * (lane & 7);
; #pragma unroll
;     for (int i = 0; i < 8; ++i) v[i] = NT ? __builtin_nontemporal_load((const f32x4*)(sp + (size_t)(8 * i) * d.ldn)) : *(const f32x4*)(sp + (size_t)(8 * i) * d.ldn);
; template <class F, bool NT = true> __device__ __forceinline__ void tr_run(F item, int first, int step, int n, LAS float* scr, int lane) {
;     ...
;     for (int it = first; it < n; it += 3 * step) {
;         const bool h1 = it + step < n, h2 = it + 2 * step < n, h3 = it + 3 * step < n, h4 = it + 4 * step < n;
;         if (h2) { dc = item(it + 2 * step); tr_load<NT>(dc, vc, lane); }
;         tr_finish<NT>(da, va, scr, lane);
;         if (h3) { da = item(it + 3 * step); tr_load<NT>(da, va, lane); }
;         if (h1) tr_finish<NT>(db, vb, scr, lane);
;         if (h4) { db = item(it + 4 * step); tr_load<NT>(db, vb, lane); }
.LBB0_199:
	v_mul_u32_u24_e32 v2, s10, v109
	v_lshlrev_b32_e32 v2, 2, v2
	v_mov_b32_e32 v3, v111
	v_lshl_add_u64 v[2:3], s[20:21], 0, v[2:3]
	v_mov_b32_e32 v107, v111
	v_lshl_add_u64 v[2:3], v[2:3], 0, v[106:107]
	s_lshl_b32 s10, s10, 5
	v_lshl_add_u64 v[10:11], v[2:3], 0, s[10:11]
	global_load_dwordx4 v[2:5], v[2:3], off sc1 nt
	s_nop 0
	global_load_dwordx4 v[6:9], v[10:11], off sc1 nt
	v_lshl_add_u64 v[10:11], v[10:11], 0, s[10:11]
	v_lshl_add_u64 v[18:19], v[10:11], 0, s[10:11]
	global_load_dwordx4 v[10:13], v[10:11], off sc1 nt
	s_nop 0
	global_load_dwordx4 v[14:17], v[18:19], off sc1 nt
	v_lshl_add_u64 v[18:19], v[18:19], 0, s[10:11]
	v_lshl_add_u64 v[26:27], v[18:19], 0, s[10:11]
	global_load_dwordx4 v[18:21], v[18:19], off sc1 nt
	s_nop 0
	global_load_dwordx4 v[22:25], v[26:27], off sc1 nt
	v_lshl_add_u64 v[26:27], v[26:27], 0, s[10:11]
	v_lshl_add_u64 v[30:31], v[26:27], 0, s[10:11]
	global_load_dwordx4 v[26:29], v[26:27], off sc1 nt
	s_nop 0
	global_load_dwordx4 v[30:33], v[30:31], off sc1 nt

; template <bool NT = true> __device__ __forceinline__ void tr_load(const TrDesc& d, f32x4 (&v)[8], int lane) {
;     const float* sp = d.src + (size_t)(lane >> 3) * d.ldn + 4 * (lane & 7);
; #pragma unroll
;     for (int i = 0; i < 8; ++i) v[i] = NT ? __builtin_nontemporal_load((const f32x4*)(sp + (size_t)(8 * i) * d.ldn)) : *(const f32x4*)(sp + (size_t)(8 * i) * d.ldn);
; template <class F, bool NT = true> __device__ __forceinline__ void tr_run(F item, int first, int step, int n, LAS float* scr, int lane) {
;     ...
;     for (int it = first; it < n; it += 3 * step) {
;         const bool h1 = it + step < n, h2 = it + 2 * step < n, h3 = it + 3 * step < n, h4 = it + 4 * step < n;
;         if (h2) { dc = item(it + 2 * step); tr_load<NT>(dc, vc, lane); }
;         tr_finish<NT>(da, va, scr, lane);
;         if (h3) { da = item(it + 3 * step); tr_load<NT>(da, va, lane); }
;         if (h1) tr_finish<NT>(db, vb, scr, lane);
;         if (h4) { db = item(it + 4 * step); tr_load<NT>(db, vb, lane); }
;         if (h2) tr_finish<NT>(dc, vc, scr, lane);
;     }
.LBB0_217:
	v_mul_u32_u24_e32 v34, s10, v109
	v_lshlrev_b32_e32 v34, 2, v34
	v_mov_b32_e32 v35, v111
	v_lshl_add_u64 v[34:35], s[20:21], 0, v[34:35]
	v_mov_b32_e32 v107, v111
	v_lshl_add_u64 v[34:35], v[34:35], 0, v[106:107]
	s_lshl_b32 s10, s10, 5
	v_lshl_add_u64 v[42:43], v[34:35], 0, s[10:11]
	global_load_dwordx4 v[34:37], v[34:35], off sc1 nt
	s_nop 0
	global_load_dwordx4 v[38:41], v[42:43], off sc1 nt
	v_lshl_add_u64 v[42:43], v[42:43], 0, s[10:11]
	v_lshl_add_u64 v[50:51], v[42:43], 0, s[10:11]
	global_load_dwordx4 v[42:45], v[42:43], off sc1 nt
	s_nop 0
	global_load_dwordx4 v[46:49], v[50:51], off sc1 nt
	v_lshl_add_u64 v[50:51], v[50:51], 0, s[10:11]
	v_lshl_add_u64 v[58:59], v[50:51], 0, s[10:11]
	global_load_dwordx4 v[50:53], v[50:51], off sc1 nt
	s_nop 0
	global_load_dwordx4 v[54:57], v[58:59], off sc1 nt
	v_lshl_add_u64 v[58:59], v[58:59], 0, s[10:11]
	v_lshl_add_u64 v[62:63], v[58:59], 0, s[10:11]
	global_load_dwordx4 v[58:61], v[58:59], off sc1 nt
	s_nop 0
	global_load_dwordx4 v[62:65], v[62:63], off sc1 nt
	s_andn2_b64 vcc, exec, s[14:15]
	s_cbranch_vccnz .LBB0_172

; #define LAS __attribute__((address_space(3)))
; __device__ __forceinline__ unsigned cvt_pk_bf16(float lo, float hi) { unsigned r; asm volatile("v_cvt_pk_bf16_f32 %0, %1, %2" : "=v"(r) : "v"(lo), "v"(hi)); return r; }
; #define LDS_WAIT() asm volatile("s_waitcnt lgkmcnt(0)" ::: "memory")
; __device__ __forceinline__ unsigned cvt_pk_bf16(float lo, float hi) { unsigned r; asm volatile("v_cvt_pk_bf16_f32 %0, %1, %2" : "=v"(r) : "v"(lo), "v"(hi)); return r; }
; template <bool NT = true> __device__ __forceinline__ void tr_load(const TrDesc& d, f32x4 (&v)[8], int lane) {
;     const float* sp = d.src + (size_t)(lane >> 3) * d.ldn + 4 * (lane & 7);
; #pragma unroll
;     for (int i = 0; i < 8; ++i) v[i] = NT ? __builtin_nontemporal_load((const f32x4*)(sp + (size_t)(8 * i) * d.ldn)) : *(const f32x4*)(sp + (size_t)(8 * i) * d.ldn);
; }
; template <bool NT = true> __device__ __forceinline__ void tr_finish(const TrDesc& d, const f32x4 (&v)[8], LAS float* scr, int lane) {
;     const int c = lane & 7;
;     f32x4 g0 = {1.f, 1.f, 1.f, 1.f}, g1 = {1.f, 1.f, 1.f, 1.f};
;     if (d.gain) { g0 = *(const f32x4*)(d.gain + 8 * c); g1 = *(const f32x4*)(d.gain + 8 * c + 4); }
; #pragma unroll
;     for (int i = 0; i < 8; ++i) { LAS float* w = scr + (8 * i + (lane >> 3)) * 33 + 4 * c; w[0] = v[i].x; w[1] = v[i].y; w[2] = v[i].z; w[3] = v[i].w; }
;     LDS_WAIT(); asm volatile("" ::: "memory");
; #pragma unroll
;     for (int j = 0; j < 4; ++j) { const int n = (lane >> 3) + 8 * j; const LAS float* s = scr + (8 * c) * 33 + n;
;         u32x4 o; o.x = cvt_pk_bf16(s[0 * 33] * g0.x, s[1 * 33] * g0.y); o.y = cvt_pk_bf16(s[2 * 33] * g0.z, s[3 * 33] * g0.w); o.z = cvt_pk_bf16(s[4 * 33] * g1.x, s[5 * 33] * g1.y); o.w = cvt_pk_bf16(s[6 * 33] * g1.z, s[7 * 33] * g1.w);
;         if (NT) __builtin_nontemporal_store(o, (u32x4*)(d.dst + (size_t)n * d.K + 8 * c)); else *(u32x4*)(d.dst + (size_t)n * d.K + 8 * c) = o; }
.Lcv_run:
	s_cmp_eq_u32 s74, 0
	s_cbranch_scc1 .Lcv_ret
	v_mul_lo_u32 v189, v3, s6
	v_lshlrev_b32_e32 v189, 3, v189
	v_lshl_add_u32 v174, v132, 4, v189
	v_add_u32_e32 v175, s6, v174
	v_add_u32_e32 v176, s6, v175
	v_add_u32_e32 v177, s6, v176
	v_add_u32_e32 v178, s6, v177
	v_add_u32_e32 v179, s6, v178
	v_add_u32_e32 v180, s6, v179
	v_add_u32_e32 v181, s6, v180
	v_lshlrev_b32_e32 v190, 2, v132
	v_mul_lo_u32 v190, v190, s7
	v_lshl_add_u32 v182, v3, 4, v190
	v_add_u32_e32 v183, s7, v182
	v_add_u32_e32 v184, s7, v183
	v_add_u32_e32 v185, s7, v184
	s_cmp_eq_u32 s8, 0
	s_cbranch_scc1 .Lcv_nogain
	global_load_dwordx4 v[166:169], v186, s[4:5]
	global_load_dwordx4 v[170:173], v186, s[4:5] offset:16
	global_load_dwordx4 v[4:7], v174, s[60:61] offset:0 sc1 nt
	global_load_dwordx4 v[8:11], v175, s[60:61] offset:0 sc1 nt
	global_load_dwordx4 v[12:15], v176, s[60:61] offset:0 sc1 nt
	global_load_dwordx4 v[16:19], v177, s[60:61] offset:0 sc1 nt
	global_load_dwordx4 v[20:23], v178, s[60:61] offset:0 sc1 nt
	global_load_dwordx4 v[24:27], v179, s[60:61] offset:0 sc1 nt
	global_load_dwordx4 v[28:31], v180, s[60:61] offset:0 sc1 nt
	global_load_dwordx4 v[32:35], v181, s[60:61] offset:0 sc1 nt
	global_load_dwordx4 v[36:39], v174, s[60:61] offset:128 sc1 nt
	global_load_dwordx4 v[40:43], v175, s[60:61] offset:128 sc1 nt
	global_load_dwordx4 v[44:47], v176, s[60:61] offset:128 sc1 nt
	global_load_dwordx4 v[48:51], v177, s[60:61] offset:128 sc1 nt
	global_load_dwordx4 v[52:55], v178, s[60:61] offset:128 sc1 nt
	global_load_dwordx4 v[56:59], v179, s[60:61] offset:128 sc1 nt
	global_load_dwordx4 v[60:63], v180, s[60:61] offset:128 sc1 nt
	global_load_dwordx4 v[64:67], v181, s[60:61] offset:128 sc1 nt
	global_load_dwordx4 v[68:71], v174, s[60:61] offset:256 sc1 nt
	global_load_dwordx4 v[72:75], v175, s[60:61] offset:256 sc1 nt
	global_load_dwordx4 v[76:79], v176, s[60:61] offset:256 sc1 nt
	global_load_dwordx4 v[80:83], v177, s[60:61] offset:256 sc1 nt
	global_load_dwordx4 v[84:87], v178, s[60:61] offset:256 sc1 nt
	global_load_dwordx4 v[88:91], v179, s[60:61] offset:256 sc1 nt
	global_load_dwordx4 v[92:95], v180, s[60:61] offset:256 sc1 nt
	global_load_dwordx4 v[96:99], v181, s[60:61] offset:256 sc1 nt
	global_load_dwordx4 v[100:103], v174, s[60:61] offset:384 sc1 nt
	global_load_dwordx4 v[104:107], v175, s[60:61] offset:384 sc1 nt
	global_load_dwordx4 v[108:111], v176, s[60:61] offset:384 sc1 nt
	global_load_dwordx4 v[112:115], v177, s[60:61] offset:384 sc1 nt
	global_load_dwordx4 v[116:119], v178, s[60:61] offset:384 sc1 nt
	global_load_dwordx4 v[120:123], v179, s[60:61] offset:384 sc1 nt
	global_load_dwordx4 v[124:127], v180, s[60:61] offset:384 sc1 nt
	global_load_dwordx4 v[128:131], v181, s[60:61] offset:384 sc1 nt
	s_add_u32 s60, s60, s70
	s_addc_u32 s61, s61, s71
	s_cmp_eq_u32 s74, 1
	s_cbranch_scc1 .Lcv_g_last
	s_waitcnt vmcnt(24)
	v_mul_f32_e32 v4, v166, v4
	v_mul_f32_e32 v5, v166, v5
	v_mul_f32_e32 v6, v166, v6
	v_mul_f32_e32 v7, v166, v7
	v_mul_f32_e32 v8, v167, v8
	v_mul_f32_e32 v9, v167, v9
	v_mul_f32_e32 v10, v167, v10
	v_mul_f32_e32 v11, v167, v11
	v_mul_f32_e32 v12, v168, v12
	v_mul_f32_e32 v13, v168, v13
	v_mul_f32_e32 v14, v168, v14
	v_mul_f32_e32 v15, v168, v15
	v_mul_f32_e32 v16, v169, v16
	v_mul_f32_e32 v17, v169, v17
	v_mul_f32_e32 v18, v169, v18
	v_mul_f32_e32 v19, v169, v19
	v_mul_f32_e32 v20, v170, v20
	v_mul_f32_e32 v21, v170, v21
	v_mul_f32_e32 v22, v170, v22
	v_mul_f32_e32 v23, v170, v23
	v_mul_f32_e32 v24, v171, v24
	v_mul_f32_e32 v25, v171, v25
	v_mul_f32_e32 v26, v171, v26
	v_mul_f32_e32 v27, v171, v27
	v_mul_f32_e32 v28, v172, v28
	v_mul_f32_e32 v29, v172, v29
	v_mul_f32_e32 v30, v172, v30
	v_mul_f32_e32 v31, v172, v31
	v_mul_f32_e32 v32, v173, v32
	v_mul_f32_e32 v33, v173, v33
	v_mul_f32_e32 v34, v173, v34
	v_mul_f32_e32 v35, v173, v35
	v_cvt_pk_bf16_f32 v188, v4, v8
	v_cvt_pk_bf16_f32 v189, v12, v16
	v_cvt_pk_bf16_f32 v190, v20, v24
	v_cvt_pk_bf16_f32 v191, v28, v32
	global_store_dwordx4 v182, v[188:191], s[62:63] sc1
	v_cvt_pk_bf16_f32 v192, v5, v9
	v_cvt_pk_bf16_f32 v193, v13, v17
	v_cvt_pk_bf16_f32 v194, v21, v25
	v_cvt_pk_bf16_f32 v195, v29, v33
	global_store_dwordx4 v183, v[192:195], s[62:63] sc1
	v_cvt_pk_bf16_f32 v196, v6, v10
	v_cvt_pk_bf16_f32 v197, v14, v18
	v_cvt_pk_bf16_f32 v198, v22, v26
	v_cvt_pk_bf16_f32 v199, v30, v34
	global_store_dwordx4 v184, v[196:199], s[62:63] sc1
	v_cvt_pk_bf16_f32 v200, v7, v11
	v_cvt_pk_bf16_f32 v201, v15, v19
	v_cvt_pk_bf16_f32 v202, v23, v27
	v_cvt_pk_bf16_f32 v203, v31, v35
	global_store_dwordx4 v185, v[200:203], s[62:63] sc1
	global_load_dwordx4 v[4:7], v174, s[60:61] offset:0 sc1 nt
	global_load_dwordx4 v[8:11], v175, s[60:61] offset:0 sc1 nt
	global_load_dwordx4 v[12:15], v176, s[60:61] offset:0 sc1 nt
	global_load_dwordx4 v[16:19], v177, s[60:61] offset:0 sc1 nt
	global_load_dwordx4 v[20:23], v178, s[60:61] offset:0 sc1 nt
	global_load_dwordx4 v[24:27], v179, s[60:61] offset:0 sc1 nt
	global_load_dwordx4 v[28:31], v180, s[60:61] offset:0 sc1 nt
	global_load_dwordx4 v[32:35], v181, s[60:61] offset:0 sc1 nt
	s_add_u32 s62, s62, s72
	s_addc_u32 s63, s63, s73
	s_waitcnt vmcnt(28)
; #define LAS __attribute__((address_space(3)))
; __device__ __forceinline__ unsigned cvt_pk_bf16(float lo, float hi) { unsigned r; asm volatile("v_cvt_pk_bf16_f32 %0, %1, %2" : "=v"(r) : "v"(lo), "v"(hi)); return r; }
; #define LDS_WAIT() asm volatile("s_waitcnt lgkmcnt(0)" ::: "memory")
; __device__ __forceinline__ unsigned cvt_pk_bf16(float lo, float hi) { unsigned r; asm volatile("v_cvt_pk_bf16_f32 %0, %1, %2" : "=v"(r) : "v"(lo), "v"(hi)); return r; }
; template <bool NT = true> __device__ __forceinline__ void tr_load(const TrDesc& d, f32x4 (&v)[8], int lane) {
;     const float* sp = d.src + (size_t)(lane >> 3) * d.ldn + 4 * (lane & 7);
; #pragma unroll
;     for (int i = 0; i < 8; ++i) v[i] = NT ? __builtin_nontemporal_load((const f32x4*)(sp + (size_t)(8 * i) * d.ldn)) : *(const f32x4*)(sp + (size_t)(8 * i) * d.ldn);
; }
; template <bool NT = true> __device__ __forceinline__ void tr_finish(const TrDesc& d, const f32x4 (&v)[8], LAS float* scr, int lane) {
;     const int c = lane & 7;
;     f32x4 g0 = {1.f, 1.f, 1.f, 1.f}, g1 = {1.f, 1.f, 1.f, 1.f};
;     if (d.gain) { g0 = *(const f32x4*)(d.gain + 8 * c); g1 = *(const f32x4*)(d.gain + 8 * c + 4); }
; #pragma unroll
;     for (int i = 0; i < 8; ++i) { LAS float* w = scr + (8 * i + (lane >> 3)) * 33 + 4 * c; w[0] = v[i].x; w[1] = v[i].y; w[2] = v[i].z; w[3] = v[i].w; }
;     LDS_WAIT(); asm volatile("" ::: "memory");
; #pragma unroll
;     for (int j = 0; j < 4; ++j) { const int n = (lane >> 3) + 8 * j; const LAS float* s = scr + (8 * c) * 33 + n;
;         u32x4 o; o.x = cvt_pk_bf16(s[0 * 33] * g0.x, s[1 * 33] * g0.y); o.y = cvt_pk_bf16(s[2 * 33] * g0.z, s[3 * 33] * g0.w); o.z = cvt_pk_bf16(s[4 * 33] * g1.x, s[5 * 33] * g1.y); o.w = cvt_pk_bf16(s[6 * 33] * g1.z, s[7 * 33] * g1.w);
;         if (NT) __builtin_nontemporal_store(o, (u32x4*)(d.dst + (size_t)n * d.K + 8 * c)); else *(u32x4*)(d.dst + (size_t)n * d.K + 8 * c) = o; }
	v_mul_f32_e32 v36, v166, v36
	v_mul_f32_e32 v37, v166, v37
	v_mul_f32_e32 v38, v166, v38
	v_mul_f32_e32 v39, v166, v39
	v_mul_f32_e32 v40, v167, v40
	v_mul_f32_e32 v41, v167, v41
	v_mul_f32_e32 v42, v167, v42
	v_mul_f32_e32 v43, v167, v43
	v_mul_f32_e32 v44, v168, v44
	v_mul_f32_e32 v45, v168, v45
	v_mul_f32_e32 v46, v168, v46
	v_mul_f32_e32 v47, v168, v47
	v_mul_f32_e32 v48, v169, v48
	v_mul_f32_e32 v49, v169, v49
	v_mul_f32_e32 v50, v169, v50
	v_mul_f32_e32 v51, v169, v51
	v_mul_f32_e32 v52, v170, v52
	v_mul_f32_e32 v53, v170, v53
	v_mul_f32_e32 v54, v170, v54
	v_mul_f32_e32 v55, v170, v55
	v_mul_f32_e32 v56, v171, v56
	v_mul_f32_e32 v57, v171, v57
	v_mul_f32_e32 v58, v171, v58
	v_mul_f32_e32 v59, v171, v59
	v_mul_f32_e32 v60, v172, v60
	v_mul_f32_e32 v61, v172, v61
	v_mul_f32_e32 v62, v172, v62
	v_mul_f32_e32 v63, v172, v63
	v_mul_f32_e32 v64, v173, v64
	v_mul_f32_e32 v65, v173, v65
	v_mul_f32_e32 v66, v173, v66
	v_mul_f32_e32 v67, v173, v67
	v_cvt_pk_bf16_f32 v188, v36, v40
	v_cvt_pk_bf16_f32 v189, v44, v48
	v_cvt_pk_bf16_f32 v190, v52, v56
	v_cvt_pk_bf16_f32 v191, v60, v64
	global_store_dwordx4 v182, v[188:191], s[64:65] sc1
	v_cvt_pk_bf16_f32 v192, v37, v41
	v_cvt_pk_bf16_f32 v193, v45, v49
	v_cvt_pk_bf16_f32 v194, v53, v57
	v_cvt_pk_bf16_f32 v195, v61, v65
	global_store_dwordx4 v183, v[192:195], s[64:65] sc1
	v_cvt_pk_bf16_f32 v196, v38, v42
	v_cvt_pk_bf16_f32 v197, v46, v50
	v_cvt_pk_bf16_f32 v198, v54, v58
	v_cvt_pk_bf16_f32 v199, v62, v66
	global_store_dwordx4 v184, v[196:199], s[64:65] sc1
	v_cvt_pk_bf16_f32 v200, v39, v43
	v_cvt_pk_bf16_f32 v201, v47, v51
	v_cvt_pk_bf16_f32 v202, v55, v59
	v_cvt_pk_bf16_f32 v203, v63, v67
	global_store_dwordx4 v185, v[200:203], s[64:65] sc1
	global_load_dwordx4 v[36:39], v174, s[60:61] offset:128 sc1 nt
	global_load_dwordx4 v[40:43], v175, s[60:61] offset:128 sc1 nt
	global_load_dwordx4 v[44:47], v176, s[60:61] offset:128 sc1 nt
	global_load_dwordx4 v[48:51], v177, s[60:61] offset:128 sc1 nt
	global_load_dwordx4 v[52:55], v178, s[60:61] offset:128 sc1 nt
	global_load_dwordx4 v[56:59], v179, s[60:61] offset:128 sc1 nt
	global_load_dwordx4 v[60:63], v180, s[60:61] offset:128 sc1 nt
	global_load_dwordx4 v[64:67], v181, s[60:61] offset:128 sc1 nt
	s_add_u32 s64, s64, s72
	s_addc_u32 s65, s65, s73
	s_waitcnt vmcnt(32)
	v_mul_f32_e32 v68, v166, v68
	v_mul_f32_e32 v69, v166, v69
	v_mul_f32_e32 v70, v166, v70
	v_mul_f32_e32 v71, v166, v71
	v_mul_f32_e32 v72, v167, v72
	v_mul_f32_e32 v73, v167, v73
	v_mul_f32_e32 v74, v167, v74
	v_mul_f32_e32 v75, v167, v75
	v_mul_f32_e32 v76, v168, v76
	v_mul_f32_e32 v77, v168, v77
	v_mul_f32_e32 v78, v168, v78
	v_mul_f32_e32 v79, v168, v79
	v_mul_f32_e32 v80, v169, v80
	v_mul_f32_e32 v81, v169, v81
	v_mul_f32_e32 v82, v169, v82
	v_mul_f32_e32 v83, v169, v83
	v_mul_f32_e32 v84, v170, v84
	v_mul_f32_e32 v85, v170, v85
	v_mul_f32_e32 v86, v170, v86
	v_mul_f32_e32 v87, v170, v87
	v_mul_f32_e32 v88, v171, v88
	v_mul_f32_e32 v89, v171, v89
	v_mul_f32_e32 v90, v171, v90
	v_mul_f32_e32 v91, v171, v91
	v_mul_f32_e32 v92, v172, v92
	v_mul_f32_e32 v93, v172, v93
	v_mul_f32_e32 v94, v172, v94
	v_mul_f32_e32 v95, v172, v95
	v_mul_f32_e32 v96, v173, v96
	v_mul_f32_e32 v97, v173, v97
	v_mul_f32_e32 v98, v173, v98
	v_mul_f32_e32 v99, v173, v99
	v_cvt_pk_bf16_f32 v188, v68, v72
	v_cvt_pk_bf16_f32 v189, v76, v80
	v_cvt_pk_bf16_f32 v190, v84, v88
	v_cvt_pk_bf16_f32 v191, v92, v96
	global_store_dwordx4 v182, v[188:191], s[66:67] sc1
	v_cvt_pk_bf16_f32 v192, v69, v73
	v_cvt_pk_bf16_f32 v193, v77, v81
	v_cvt_pk_bf16_f32 v194, v85, v89
	v_cvt_pk_bf16_f32 v195, v93, v97
	global_store_dwordx4 v183, v[192:195], s[66:67] sc1
	v_cvt_pk_bf16_f32 v196, v70, v74
	v_cvt_pk_bf16_f32 v197, v78, v82
	v_cvt_pk_bf16_f32 v198, v86, v90
	v_cvt_pk_bf16_f32 v199, v94, v98
	global_store_dwordx4 v184, v[196:199], s[66:67] sc1
	v_cvt_pk_bf16_f32 v200, v71, v75
	v_cvt_pk_bf16_f32 v201, v79, v83
	v_cvt_pk_bf16_f32 v202, v87, v91
	v_cvt_pk_bf16_f32 v203, v95, v99
	global_store_dwordx4 v185, v[200:203], s[66:67] sc1
	global_load_dwordx4 v[68:71], v174, s[60:61] offset:256 sc1 nt
	global_load_dwordx4 v[72:75], v175, s[60:61] offset:256 sc1 nt
	global_load_dwordx4 v[76:79], v176, s[60:61] offset:256 sc1 nt
	global_load_dwordx4 v[80:83], v177, s[60:61] offset:256 sc1 nt
	global_load_dwordx4 v[84:87], v178, s[60:61] offset:256 sc1 nt
	global_load_dwordx4 v[88:91], v179, s[60:61] offset:256 sc1 nt
	global_load_dwordx4 v[92:95], v180, s[60:61] offset:256 sc1 nt
	global_load_dwordx4 v[96:99], v181, s[60:61] offset:256 sc1 nt
	s_add_u32 s66, s66, s72
	s_addc_u32 s67, s67, s73
	s_waitcnt vmcnt(36)
; #define LAS __attribute__((address_space(3)))
; __device__ __forceinline__ unsigned cvt_pk_bf16(float lo, float hi) { unsigned r; asm volatile("v_cvt_pk_bf16_f32 %0, %1, %2" : "=v"(r) : "v"(lo), "v"(hi)); return r; }
; #define LDS_WAIT() asm volatile("s_waitcnt lgkmcnt(0)" ::: "memory")
; __device__ __forceinline__ unsigned cvt_pk_bf16(float lo, float hi) { unsigned r; asm volatile("v_cvt_pk_bf16_f32 %0, %1, %2" : "=v"(r) : "v"(lo), "v"(hi)); return r; }
; template <bool NT = true> __device__ __forceinline__ void tr_load(const TrDesc& d, f32x4 (&v)[8], int lane) {
;     const float* sp = d.src + (size_t)(lane >> 3) * d.ldn + 4 * (lane & 7);
; #pragma unroll
;     for (int i = 0; i < 8; ++i) v[i] = NT ? __builtin_nontemporal_load((const f32x4*)(sp + (size_t)(8 * i) * d.ldn)) : *(const f32x4*)(sp + (size_t)(8 * i) * d.ldn);
; }
; template <bool NT = true> __device__ __forceinline__ void tr_finish(const TrDesc& d, const f32x4 (&v)[8], LAS float* scr, int lane) {
;     const int c = lane & 7;
;     f32x4 g0 = {1.f, 1.f, 1.f, 1.f}, g1 = {1.f, 1.f, 1.f, 1.f};
;     if (d.gain) { g0 = *(const f32x4*)(d.gain + 8 * c); g1 = *(const f32x4*)(d.gain + 8 * c + 4); }
; #pragma unroll
;     for (int i = 0; i < 8; ++i) { LAS float* w = scr + (8 * i + (lane >> 3)) * 33 + 4 * c; w[0] = v[i].x; w[1] = v[i].y; w[2] = v[i].z; w[3] = v[i].w; }
;     LDS_WAIT(); asm volatile("" ::: "memory");
; #pragma unroll
;     for (int j = 0; j < 4; ++j) { const int n = (lane >> 3) + 8 * j; const LAS float* s = scr + (8 * c) * 33 + n;
;         u32x4 o; o.x = cvt_pk_bf16(s[0 * 33] * g0.x, s[1 * 33] * g0.y); o.y = cvt_pk_bf16(s[2 * 33] * g0.z, s[3 * 33] * g0.w); o.z = cvt_pk_bf16(s[4 * 33] * g1.x, s[5 * 33] * g1.y); o.w = cvt_pk_bf16(s[6 * 33] * g1.z, s[7 * 33] * g1.w);
;         if (NT) __builtin_nontemporal_store(o, (u32x4*)(d.dst + (size_t)n * d.K + 8 * c)); else *(u32x4*)(d.dst + (size_t)n * d.K + 8 * c) = o; }
	v_mul_f32_e32 v100, v166, v100
	v_mul_f32_e32 v101, v166, v101
	v_mul_f32_e32 v102, v166, v102
	v_mul_f32_e32 v103, v166, v103
	v_mul_f32_e32 v104, v167, v104
	v_mul_f32_e32 v105, v167, v105
	v_mul_f32_e32 v106, v167, v106
	v_mul_f32_e32 v107, v167, v107
	v_mul_f32_e32 v108, v168, v108
	v_mul_f32_e32 v109, v168, v109
	v_mul_f32_e32 v110, v168, v110
	v_mul_f32_e32 v111, v168, v111
	v_mul_f32_e32 v112, v169, v112
	v_mul_f32_e32 v113, v169, v113
	v_mul_f32_e32 v114, v169, v114
	v_mul_f32_e32 v115, v169, v115
	v_mul_f32_e32 v116, v170, v116
	v_mul_f32_e32 v117, v170, v117
	v_mul_f32_e32 v118, v170, v118
	v_mul_f32_e32 v119, v170, v119
	v_mul_f32_e32 v120, v171, v120
	v_mul_f32_e32 v121, v171, v121
	v_mul_f32_e32 v122, v171, v122
	v_mul_f32_e32 v123, v171, v123
	v_mul_f32_e32 v124, v172, v124
	v_mul_f32_e32 v125, v172, v125
	v_mul_f32_e32 v126, v172, v126
	v_mul_f32_e32 v127, v172, v127
	v_mul_f32_e32 v128, v173, v128
	v_mul_f32_e32 v129, v173, v129
	v_mul_f32_e32 v130, v173, v130
	v_mul_f32_e32 v131, v173, v131
	v_cvt_pk_bf16_f32 v188, v100, v104
	v_cvt_pk_bf16_f32 v189, v108, v112
	v_cvt_pk_bf16_f32 v190, v116, v120
	v_cvt_pk_bf16_f32 v191, v124, v128
	global_store_dwordx4 v182, v[188:191], s[68:69] sc1
	v_cvt_pk_bf16_f32 v192, v101, v105
	v_cvt_pk_bf16_f32 v193, v109, v113
	v_cvt_pk_bf16_f32 v194, v117, v121
	v_cvt_pk_bf16_f32 v195, v125, v129
	global_store_dwordx4 v183, v[192:195], s[68:69] sc1
	v_cvt_pk_bf16_f32 v196, v102, v106
	v_cvt_pk_bf16_f32 v197, v110, v114
	v_cvt_pk_bf16_f32 v198, v118, v122
	v_cvt_pk_bf16_f32 v199, v126, v130
	global_store_dwordx4 v184, v[196:199], s[68:69] sc1
	v_cvt_pk_bf16_f32 v200, v103, v107
	v_cvt_pk_bf16_f32 v201, v111, v115
	v_cvt_pk_bf16_f32 v202, v119, v123
	v_cvt_pk_bf16_f32 v203, v127, v131
	global_store_dwordx4 v185, v[200:203], s[68:69] sc1
	global_load_dwordx4 v[100:103], v174, s[60:61] offset:384 sc1 nt
	global_load_dwordx4 v[104:107], v175, s[60:61] offset:384 sc1 nt
	global_load_dwordx4 v[108:111], v176, s[60:61] offset:384 sc1 nt
	global_load_dwordx4 v[112:115], v177, s[60:61] offset:384 sc1 nt
	global_load_dwordx4 v[116:119], v178, s[60:61] offset:384 sc1 nt
	global_load_dwordx4 v[120:123], v179, s[60:61] offset:384 sc1 nt
	global_load_dwordx4 v[124:127], v180, s[60:61] offset:384 sc1 nt
	global_load_dwordx4 v[128:131], v181, s[60:61] offset:384 sc1 nt
	s_add_u32 s68, s68, s72
	s_addc_u32 s69, s69, s73
	s_add_u32 s60, s60, s70
	s_addc_u32 s61, s61, s71
	s_sub_i32 s74, s74, 1
	s_cmp_eq_u32 s74, 1
	s_cbranch_scc1 .Lcv_g_last
.Lcv_g_steady:
	s_waitcnt vmcnt(36)
	v_mul_f32_e32 v4, v166, v4
	v_mul_f32_e32 v5, v166, v5
	v_mul_f32_e32 v6, v166, v6
	v_mul_f32_e32 v7, v166, v7
	v_mul_f32_e32 v8, v167, v8
	v_mul_f32_e32 v9, v167, v9
	v_mul_f32_e32 v10, v167, v10
	v_mul_f32_e32 v11, v167, v11
	v_mul_f32_e32 v12, v168, v12
	v_mul_f32_e32 v13, v168, v13
	v_mul_f32_e32 v14, v168, v14
	v_mul_f32_e32 v15, v168, v15
	v_mul_f32_e32 v16, v169, v16
	v_mul_f32_e32 v17, v169, v17
	v_mul_f32_e32 v18, v169, v18
	v_mul_f32_e32 v19, v169, v19
	v_mul_f32_e32 v20, v170, v20
	v_mul_f32_e32 v21, v170, v21
	v_mul_f32_e32 v22, v170, v22
	v_mul_f32_e32 v23, v170, v23
	v_mul_f32_e32 v24, v171, v24
	v_mul_f32_e32 v25, v171, v25
	v_mul_f32_e32 v26, v171, v26
	v_mul_f32_e32 v27, v171, v27
	v_mul_f32_e32 v28, v172, v28
	v_mul_f32_e32 v29, v172, v29
	v_mul_f32_e32 v30, v172, v30
	v_mul_f32_e32 v31, v172, v31
	v_mul_f32_e32 v32, v173, v32
	v_mul_f32_e32 v33, v173, v33
	v_mul_f32_e32 v34, v173, v34
	v_mul_f32_e32 v35, v173, v35
	v_cvt_pk_bf16_f32 v188, v4, v8
	v_cvt_pk_bf16_f32 v189, v12, v16
	v_cvt_pk_bf16_f32 v190, v20, v24
	v_cvt_pk_bf16_f32 v191, v28, v32
	global_store_dwordx4 v182, v[188:191], s[62:63] sc1
	v_cvt_pk_bf16_f32 v192, v5, v9
	v_cvt_pk_bf16_f32 v193, v13, v17
	v_cvt_pk_bf16_f32 v194, v21, v25
	v_cvt_pk_bf16_f32 v195, v29, v33
	global_store_dwordx4 v183, v[192:195], s[62:63] sc1
	v_cvt_pk_bf16_f32 v196, v6, v10
	v_cvt_pk_bf16_f32 v197, v14, v18
	v_cvt_pk_bf16_f32 v198, v22, v26
	v_cvt_pk_bf16_f32 v199, v30, v34
	global_store_dwordx4 v184, v[196:199], s[62:63] sc1
	v_cvt_pk_bf16_f32 v200, v7, v11
	v_cvt_pk_bf16_f32 v201, v15, v19
	v_cvt_pk_bf16_f32 v202, v23, v27
	v_cvt_pk_bf16_f32 v203, v31, v35
	global_store_dwordx4 v185, v[200:203], s[62:63] sc1
	global_load_dwordx4 v[4:7], v174, s[60:61] offset:0 sc1 nt
	global_load_dwordx4 v[8:11], v175, s[60:61] offset:0 sc1 nt
	global_load_dwordx4 v[12:15], v176, s[60:61] offset:0 sc1 nt
	global_load_dwordx4 v[16:19], v177, s[60:61] offset:0 sc1 nt
	global_load_dwordx4 v[20:23], v178, s[60:61] offset:0 sc1 nt
	global_load_dwordx4 v[24:27], v179, s[60:61] offset:0 sc1 nt
	global_load_dwordx4 v[28:31], v180, s[60:61] offset:0 sc1 nt
	global_load_dwordx4 v[32:35], v181, s[60:61] offset:0 sc1 nt
	s_add_u32 s62, s62, s72
	s_addc_u32 s63, s63, s73
	s_waitcnt vmcnt(36)
; #define LAS __attribute__((address_space(3)))
; __device__ __forceinline__ unsigned cvt_pk_bf16(float lo, float hi) { unsigned r; asm volatile("v_cvt_pk_bf16_f32 %0, %1, %2" : "=v"(r) : "v"(lo), "v"(hi)); return r; }
; #define LDS_WAIT() asm volatile("s_waitcnt lgkmcnt(0)" ::: "memory")
; __device__ __forceinline__ unsigned cvt_pk_bf16(float lo, float hi) { unsigned r; asm volatile("v_cvt_pk_bf16_f32 %0, %1, %2" : "=v"(r) : "v"(lo), "v"(hi)); return r; }
; template <bool NT = true> __device__ __forceinline__ void tr_load(const TrDesc& d, f32x4 (&v)[8], int lane) {
;     const float* sp = d.src + (size_t)(lane >> 3) * d.ldn + 4 * (lane & 7);
; #pragma unroll
;     for (int i = 0; i < 8; ++i) v[i] = NT ? __builtin_nontemporal_load((const f32x4*)(sp + (size_t)(8 * i) * d.ldn)) : *(const f32x4*)(sp + (size_t)(8 * i) * d.ldn);
; }
; template <bool NT = true> __device__ __forceinline__ void tr_finish(const TrDesc& d, const f32x4 (&v)[8], LAS float* scr, int lane) {
;     const int c = lane & 7;
;     f32x4 g0 = {1.f, 1.f, 1.f, 1.f}, g1 = {1.f, 1.f, 1.f, 1.f};
;     if (d.gain) { g0 = *(const f32x4*)(d.gain + 8 * c); g1 = *(const f32x4*)(d.gain + 8 * c + 4); }
; #pragma unroll
;     for (int i = 0; i < 8; ++i) { LAS float* w = scr + (8 * i + (lane >> 3)) * 33 + 4 * c; w[0] = v[i].x; w[1] = v[i].y; w[2] = v[i].z; w[3] = v[i].w; }
;     LDS_WAIT(); asm volatile("" ::: "memory");
; #pragma unroll
;     for (int j = 0; j < 4; ++j) { const int n = (lane >> 3) + 8 * j; const LAS float* s = scr + (8 * c) * 33 + n;
;         u32x4 o; o.x = cvt_pk_bf16(s[0 * 33] * g0.x, s[1 * 33] * g0.y); o.y = cvt_pk_bf16(s[2 * 33] * g0.z, s[3 * 33] * g0.w); o.z = cvt_pk_bf16(s[4 * 33] * g1.x, s[5 * 33] * g1.y); o.w = cvt_pk_bf16(s[6 * 33] * g1.z, s[7 * 33] * g1.w);
;         if (NT) __builtin_nontemporal_store(o, (u32x4*)(d.dst + (size_t)n * d.K + 8 * c)); else *(u32x4*)(d.dst + (size_t)n * d.K + 8 * c) = o; }
	v_mul_f32_e32 v36, v166, v36
	v_mul_f32_e32 v37, v166, v37
	v_mul_f32_e32 v38, v166, v38
	v_mul_f32_e32 v39, v166, v39
	v_mul_f32_e32 v40, v167, v40
	v_mul_f32_e32 v41, v167, v41
	v_mul_f32_e32 v42, v167, v42
	v_mul_f32_e32 v43, v167, v43
	v_mul_f32_e32 v44, v168, v44
	v_mul_f32_e32 v45, v168, v45
	v_mul_f32_e32 v46, v168, v46
	v_mul_f32_e32 v47, v168, v47
	v_mul_f32_e32 v48, v169, v48
	v_mul_f32_e32 v49, v169, v49
	v_mul_f32_e32 v50, v169, v50
	v_mul_f32_e32 v51, v169, v51
	v_mul_f32_e32 v52, v170, v52
	v_mul_f32_e32 v53, v170, v53
	v_mul_f32_e32 v54, v170, v54
	v_mul_f32_e32 v55, v170, v55
	v_mul_f32_e32 v56, v171, v56
	v_mul_f32_e32 v57, v171, v57
	v_mul_f32_e32 v58, v171, v58
	v_mul_f32_e32 v59, v171, v59
	v_mul_f32_e32 v60, v172, v60
	v_mul_f32_e32 v61, v172, v61
	v_mul_f32_e32 v62, v172, v62
	v_mul_f32_e32 v63, v172, v63
	v_mul_f32_e32 v64, v173, v64
	v_mul_f32_e32 v65, v173, v65
	v_mul_f32_e32 v66, v173, v66
	v_mul_f32_e32 v67, v173, v67
	v_cvt_pk_bf16_f32 v188, v36, v40
	v_cvt_pk_bf16_f32 v189, v44, v48
	v_cvt_pk_bf16_f32 v190, v52, v56
	v_cvt_pk_bf16_f32 v191, v60, v64
	global_store_dwordx4 v182, v[188:191], s[64:65] sc1
	v_cvt_pk_bf16_f32 v192, v37, v41
	v_cvt_pk_bf16_f32 v193, v45, v49
	v_cvt_pk_bf16_f32 v194, v53, v57
	v_cvt_pk_bf16_f32 v195, v61, v65
	global_store_dwordx4 v183, v[192:195], s[64:65] sc1
	v_cvt_pk_bf16_f32 v196, v38, v42
	v_cvt_pk_bf16_f32 v197, v46, v50
	v_cvt_pk_bf16_f32 v198, v54, v58
	v_cvt_pk_bf16_f32 v199, v62, v66
	global_store_dwordx4 v184, v[196:199], s[64:65] sc1
	v_cvt_pk_bf16_f32 v200, v39, v43
	v_cvt_pk_bf16_f32 v201, v47, v51
	v_cvt_pk_bf16_f32 v202, v55, v59
	v_cvt_pk_bf16_f32 v203, v63, v67
	global_store_dwordx4 v185, v[200:203], s[64:65] sc1
	global_load_dwordx4 v[36:39], v174, s[60:61] offset:128 sc1 nt
	global_load_dwordx4 v[40:43], v175, s[60:61] offset:128 sc1 nt
	global_load_dwordx4 v[44:47], v176, s[60:61] offset:128 sc1 nt
	global_load_dwordx4 v[48:51], v177, s[60:61] offset:128 sc1 nt
	global_load_dwordx4 v[52:55], v178, s[60:61] offset:128 sc1 nt
	global_load_dwordx4 v[56:59], v179, s[60:61] offset:128 sc1 nt
	global_load_dwordx4 v[60:63], v180, s[60:61] offset:128 sc1 nt
	global_load_dwordx4 v[64:67], v181, s[60:61] offset:128 sc1 nt
	s_add_u32 s64, s64, s72
	s_addc_u32 s65, s65, s73
	s_waitcnt vmcnt(36)
	v_mul_f32_e32 v68, v166, v68
	v_mul_f32_e32 v69, v166, v69
	v_mul_f32_e32 v70, v166, v70
	v_mul_f32_e32 v71, v166, v71
	v_mul_f32_e32 v72, v167, v72
	v_mul_f32_e32 v73, v167, v73
	v_mul_f32_e32 v74, v167, v74
	v_mul_f32_e32 v75, v167, v75
	v_mul_f32_e32 v76, v168, v76
	v_mul_f32_e32 v77, v168, v77
	v_mul_f32_e32 v78, v168, v78
	v_mul_f32_e32 v79, v168, v79
	v_mul_f32_e32 v80, v169, v80
	v_mul_f32_e32 v81, v169, v81
	v_mul_f32_e32 v82, v169, v82
	v_mul_f32_e32 v83, v169, v83
	v_mul_f32_e32 v84, v170, v84
	v_mul_f32_e32 v85, v170, v85
	v_mul_f32_e32 v86, v170, v86
	v_mul_f32_e32 v87, v170, v87
	v_mul_f32_e32 v88, v171, v88
	v_mul_f32_e32 v89, v171, v89
	v_mul_f32_e32 v90, v171, v90
	v_mul_f32_e32 v91, v171, v91
	v_mul_f32_e32 v92, v172, v92
	v_mul_f32_e32 v93, v172, v93
	v_mul_f32_e32 v94, v172, v94
	v_mul_f32_e32 v95, v172, v95
	v_mul_f32_e32 v96, v173, v96
	v_mul_f32_e32 v97, v173, v97
	v_mul_f32_e32 v98, v173, v98
	v_mul_f32_e32 v99, v173, v99
	v_cvt_pk_bf16_f32 v188, v68, v72
	v_cvt_pk_bf16_f32 v189, v76, v80
	v_cvt_pk_bf16_f32 v190, v84, v88
	v_cvt_pk_bf16_f32 v191, v92, v96
	global_store_dwordx4 v182, v[188:191], s[66:67] sc1
	v_cvt_pk_bf16_f32 v192, v69, v73
	v_cvt_pk_bf16_f32 v193, v77, v81
	v_cvt_pk_bf16_f32 v194, v85, v89
	v_cvt_pk_bf16_f32 v195, v93, v97
	global_store_dwordx4 v183, v[192:195], s[66:67] sc1
	v_cvt_pk_bf16_f32 v196, v70, v74
	v_cvt_pk_bf16_f32 v197, v78, v82
	v_cvt_pk_bf16_f32 v198, v86, v90
	v_cvt_pk_bf16_f32 v199, v94, v98
	global_store_dwordx4 v184, v[196:199], s[66:67] sc1
	v_cvt_pk_bf16_f32 v200, v71, v75
	v_cvt_pk_bf16_f32 v201, v79, v83
	v_cvt_pk_bf16_f32 v202, v87, v91
	v_cvt_pk_bf16_f32 v203, v95, v99
	global_store_dwordx4 v185, v[200:203], s[66:67] sc1
	global_load_dwordx4 v[68:71], v174, s[60:61] offset:256 sc1 nt
	global_load_dwordx4 v[72:75], v175, s[60:61] offset:256 sc1 nt
	global_load_dwordx4 v[76:79], v176, s[60:61] offset:256 sc1 nt
	global_load_dwordx4 v[80:83], v177, s[60:61] offset:256 sc1 nt
	global_load_dwordx4 v[84:87], v178, s[60:61] offset:256 sc1 nt
	global_load_dwordx4 v[88:91], v179, s[60:61] offset:256 sc1 nt
	global_load_dwordx4 v[92:95], v180, s[60:61] offset:256 sc1 nt
	global_load_dwordx4 v[96:99], v181, s[60:61] offset:256 sc1 nt
	s_add_u32 s66, s66, s72
	s_addc_u32 s67, s67, s73
	s_waitcnt vmcnt(36)
; #define LAS __attribute__((address_space(3)))
; __device__ __forceinline__ unsigned cvt_pk_bf16(float lo, float hi) { unsigned r; asm volatile("v_cvt_pk_bf16_f32 %0, %1, %2" : "=v"(r) : "v"(lo), "v"(hi)); return r; }
; #define LDS_WAIT() asm volatile("s_waitcnt lgkmcnt(0)" ::: "memory")
; __device__ __forceinline__ unsigned cvt_pk_bf16(float lo, float hi) { unsigned r; asm volatile("v_cvt_pk_bf16_f32 %0, %1, %2" : "=v"(r) : "v"(lo), "v"(hi)); return r; }
; template <bool NT = true> __device__ __forceinline__ void tr_load(const TrDesc& d, f32x4 (&v)[8], int lane) {
;     const float* sp = d.src + (size_t)(lane >> 3) * d.ldn + 4 * (lane & 7);
; #pragma unroll
;     for (int i = 0; i < 8; ++i) v[i] = NT ? __builtin_nontemporal_load((const f32x4*)(sp + (size_t)(8 * i) * d.ldn)) : *(const f32x4*)(sp + (size_t)(8 * i) * d.ldn);
; }
; template <bool NT = true> __device__ __forceinline__ void tr_finish(const TrDesc& d, const f32x4 (&v)[8], LAS float* scr, int lane) {
;     const int c = lane & 7;
;     f32x4 g0 = {1.f, 1.f, 1.f, 1.f}, g1 = {1.f, 1.f, 1.f, 1.f};
;     if (d.gain) { g0 = *(const f32x4*)(d.gain + 8 * c); g1 = *(const f32x4*)(d.gain + 8 * c + 4); }
; #pragma unroll
;     for (int i = 0; i < 8; ++i) { LAS float* w = scr + (8 * i + (lane >> 3)) * 33 + 4 * c; w[0] = v[i].x; w[1] = v[i].y; w[2] = v[i].z; w[3] = v[i].w; }
;     LDS_WAIT(); asm volatile("" ::: "memory");
; #pragma unroll
;     for (int j = 0; j < 4; ++j) { const int n = (lane >> 3) + 8 * j; const LAS float* s = scr + (8 * c) * 33 + n;
;         u32x4 o; o.x = cvt_pk_bf16(s[0 * 33] * g0.x, s[1 * 33] * g0.y); o.y = cvt_pk_bf16(s[2 * 33] * g0.z, s[3 * 33] * g0.w); o.z = cvt_pk_bf16(s[4 * 33] * g1.x, s[5 * 33] * g1.y); o.w = cvt_pk_bf16(s[6 * 33] * g1.z, s[7 * 33] * g1.w);
;         if (NT) __builtin_nontemporal_store(o, (u32x4*)(d.dst + (size_t)n * d.K + 8 * c)); else *(u32x4*)(d.dst + (size_t)n * d.K + 8 * c) = o; }
	v_mul_f32_e32 v100, v166, v100
	v_mul_f32_e32 v101, v166, v101
	v_mul_f32_e32 v102, v166, v102
	v_mul_f32_e32 v103, v166, v103
	v_mul_f32_e32 v104, v167, v104
	v_mul_f32_e32 v105, v167, v105
	v_mul_f32_e32 v106, v167, v106
	v_mul_f32_e32 v107, v167, v107
	v_mul_f32_e32 v108, v168, v108
	v_mul_f32_e32 v109, v168, v109
	v_mul_f32_e32 v110, v168, v110
	v_mul_f32_e32 v111, v168, v111
	v_mul_f32_e32 v112, v169, v112
	v_mul_f32_e32 v113, v169, v113
	v_mul_f32_e32 v114, v169, v114
	v_mul_f32_e32 v115, v169, v115
	v_mul_f32_e32 v116, v170, v116
	v_mul_f32_e32 v117, v170, v117
	v_mul_f32_e32 v118, v170, v118
	v_mul_f32_e32 v119, v170, v119
	v_mul_f32_e32 v120, v171, v120
	v_mul_f32_e32 v121, v171, v121
	v_mul_f32_e32 v122, v171, v122
	v_mul_f32_e32 v123, v171, v123
	v_mul_f32_e32 v124, v172, v124
	v_mul_f32_e32 v125, v172, v125
	v_mul_f32_e32 v126, v172, v126
	v_mul_f32_e32 v127, v172, v127
	v_mul_f32_e32 v128, v173, v128
	v_mul_f32_e32 v129, v173, v129
	v_mul_f32_e32 v130, v173, v130
	v_mul_f32_e32 v131, v173, v131
	v_cvt_pk_bf16_f32 v188, v100, v104
	v_cvt_pk_bf16_f32 v189, v108, v112
	v_cvt_pk_bf16_f32 v190, v116, v120
	v_cvt_pk_bf16_f32 v191, v124, v128
	global_store_dwordx4 v182, v[188:191], s[68:69] sc1
	v_cvt_pk_bf16_f32 v192, v101, v105
	v_cvt_pk_bf16_f32 v193, v109, v113
	v_cvt_pk_bf16_f32 v194, v117, v121
	v_cvt_pk_bf16_f32 v195, v125, v129
	global_store_dwordx4 v183, v[192:195], s[68:69] sc1
	v_cvt_pk_bf16_f32 v196, v102, v106
	v_cvt_pk_bf16_f32 v197, v110, v114
	v_cvt_pk_bf16_f32 v198, v118, v122
	v_cvt_pk_bf16_f32 v199, v126, v130
	global_store_dwordx4 v184, v[196:199], s[68:69] sc1
	v_cvt_pk_bf16_f32 v200, v103, v107
	v_cvt_pk_bf16_f32 v201, v111, v115
	v_cvt_pk_bf16_f32 v202, v119, v123
	v_cvt_pk_bf16_f32 v203, v127, v131
	global_store_dwordx4 v185, v[200:203], s[68:69] sc1
	global_load_dwordx4 v[100:103], v174, s[60:61] offset:384 sc1 nt
	global_load_dwordx4 v[104:107], v175, s[60:61] offset:384 sc1 nt
	global_load_dwordx4 v[108:111], v176, s[60:61] offset:384 sc1 nt
	global_load_dwordx4 v[112:115], v177, s[60:61] offset:384 sc1 nt
	global_load_dwordx4 v[116:119], v178, s[60:61] offset:384 sc1 nt
	global_load_dwordx4 v[120:123], v179, s[60:61] offset:384 sc1 nt
	global_load_dwordx4 v[124:127], v180, s[60:61] offset:384 sc1 nt
	global_load_dwordx4 v[128:131], v181, s[60:61] offset:384 sc1 nt
	s_add_u32 s68, s68, s72
	s_addc_u32 s69, s69, s73
	s_add_u32 s60, s60, s70
	s_addc_u32 s61, s61, s71
	s_sub_i32 s74, s74, 1
	s_cmp_eq_u32 s74, 1
	s_cbranch_scc0 .Lcv_g_steady

; #define LAS __attribute__((address_space(3)))
; __device__ __forceinline__ unsigned cvt_pk_bf16(float lo, float hi) { unsigned r; asm volatile("v_cvt_pk_bf16_f32 %0, %1, %2" : "=v"(r) : "v"(lo), "v"(hi)); return r; }
; #define LDS_WAIT() asm volatile("s_waitcnt lgkmcnt(0)" ::: "memory")
; __device__ __forceinline__ unsigned cvt_pk_bf16(float lo, float hi) { unsigned r; asm volatile("v_cvt_pk_bf16_f32 %0, %1, %2" : "=v"(r) : "v"(lo), "v"(hi)); return r; }
; template <bool NT = true> __device__ __forceinline__ void tr_load(const TrDesc& d, f32x4 (&v)[8], int lane) {
;     const float* sp = d.src + (size_t)(lane >> 3) * d.ldn + 4 * (lane & 7);
; #pragma unroll
;     for (int i = 0; i < 8; ++i) v[i] = NT ? __builtin_nontemporal_load((const f32x4*)(sp + (size_t)(8 * i) * d.ldn)) : *(const f32x4*)(sp + (size_t)(8 * i) * d.ldn);
; }
; template <bool NT = true> __device__ __forceinline__ void tr_finish(const TrDesc& d, const f32x4 (&v)[8], LAS float* scr, int lane) {
;     const int c = lane & 7;
;     f32x4 g0 = {1.f, 1.f, 1.f, 1.f}, g1 = {1.f, 1.f, 1.f, 1.f};
;     if (d.gain) { g0 = *(const f32x4*)(d.gain + 8 * c); g1 = *(const f32x4*)(d.gain + 8 * c + 4); }
; #pragma unroll
;     for (int i = 0; i < 8; ++i) { LAS float* w = scr + (8 * i + (lane >> 3)) * 33 + 4 * c; w[0] = v[i].x; w[1] = v[i].y; w[2] = v[i].z; w[3] = v[i].w; }
;     LDS_WAIT(); asm volatile("" ::: "memory");
; #pragma unroll
;     for (int j = 0; j < 4; ++j) { const int n = (lane >> 3) + 8 * j; const LAS float* s = scr + (8 * c) * 33 + n;
;         u32x4 o; o.x = cvt_pk_bf16(s[0 * 33] * g0.x, s[1 * 33] * g0.y); o.y = cvt_pk_bf16(s[2 * 33] * g0.z, s[3 * 33] * g0.w); o.z = cvt_pk_bf16(s[4 * 33] * g1.x, s[5 * 33] * g1.y); o.w = cvt_pk_bf16(s[6 * 33] * g1.z, s[7 * 33] * g1.w);
;         if (NT) __builtin_nontemporal_store(o, (u32x4*)(d.dst + (size_t)n * d.K + 8 * c)); else *(u32x4*)(d.dst + (size_t)n * d.K + 8 * c) = o; }
.Lcv_nogain:
	global_load_dwordx4 v[4:7], v174, s[60:61] offset:0 sc1 nt
	global_load_dwordx4 v[8:11], v175, s[60:61] offset:0 sc1 nt
	global_load_dwordx4 v[12:15], v176, s[60:61] offset:0 sc1 nt
	global_load_dwordx4 v[16:19], v177, s[60:61] offset:0 sc1 nt
	global_load_dwordx4 v[20:23], v178, s[60:61] offset:0 sc1 nt
	global_load_dwordx4 v[24:27], v179, s[60:61] offset:0 sc1 nt
	global_load_dwordx4 v[28:31], v180, s[60:61] offset:0 sc1 nt
	global_load_dwordx4 v[32:35], v181, s[60:61] offset:0 sc1 nt
	global_load_dwordx4 v[36:39], v174, s[60:61] offset:128 sc1 nt
	global_load_dwordx4 v[40:43], v175, s[60:61] offset:128 sc1 nt
	global_load_dwordx4 v[44:47], v176, s[60:61] offset:128 sc1 nt
	global_load_dwordx4 v[48:51], v177, s[60:61] offset:128 sc1 nt
	global_load_dwordx4 v[52:55], v178, s[60:61] offset:128 sc1 nt
	global_load_dwordx4 v[56:59], v179, s[60:61] offset:128 sc1 nt
	global_load_dwordx4 v[60:63], v180, s[60:61] offset:128 sc1 nt
	global_load_dwordx4 v[64:67], v181, s[60:61] offset:128 sc1 nt
	global_load_dwordx4 v[68:71], v174, s[60:61] offset:256 sc1 nt
	global_load_dwordx4 v[72:75], v175, s[60:61] offset:256 sc1 nt
	global_load_dwordx4 v[76:79], v176, s[60:61] offset:256 sc1 nt
	global_load_dwordx4 v[80:83], v177, s[60:61] offset:256 sc1 nt
	global_load_dwordx4 v[84:87], v178, s[60:61] offset:256 sc1 nt
	global_load_dwordx4 v[88:91], v179, s[60:61] offset:256 sc1 nt
	global_load_dwordx4 v[92:95], v180, s[60:61] offset:256 sc1 nt
	global_load_dwordx4 v[96:99], v181, s[60:61] offset:256 sc1 nt
	global_load_dwordx4 v[100:103], v174, s[60:61] offset:384 sc1 nt
	global_load_dwordx4 v[104:107], v175, s[60:61] offset:384 sc1 nt
	global_load_dwordx4 v[108:111], v176, s[60:61] offset:384 sc1 nt
	global_load_dwordx4 v[112:115], v177, s[60:61] offset:384 sc1 nt
	global_load_dwordx4 v[116:119], v178, s[60:61] offset:384 sc1 nt
	global_load_dwordx4 v[120:123], v179, s[60:61] offset:384 sc1 nt
	global_load_dwordx4 v[124:127], v180, s[60:61] offset:384 sc1 nt
	global_load_dwordx4 v[128:131], v181, s[60:61] offset:384 sc1 nt
	s_add_u32 s60, s60, s70
	s_addc_u32 s61, s61, s71
	s_cmp_eq_u32 s74, 1
	s_cbranch_scc1 .Lcv_n_last
	s_waitcnt vmcnt(24)
	v_cvt_pk_bf16_f32 v188, v4, v8
	v_cvt_pk_bf16_f32 v189, v12, v16
	v_cvt_pk_bf16_f32 v190, v20, v24
	v_cvt_pk_bf16_f32 v191, v28, v32
	global_store_dwordx4 v182, v[188:191], s[62:63] sc1
	v_cvt_pk_bf16_f32 v192, v5, v9
	v_cvt_pk_bf16_f32 v193, v13, v17
	v_cvt_pk_bf16_f32 v194, v21, v25
	v_cvt_pk_bf16_f32 v195, v29, v33
	global_store_dwordx4 v183, v[192:195], s[62:63] sc1
	v_cvt_pk_bf16_f32 v196, v6, v10
	v_cvt_pk_bf16_f32 v197, v14, v18
	v_cvt_pk_bf16_f32 v198, v22, v26
	v_cvt_pk_bf16_f32 v199, v30, v34
	global_store_dwordx4 v184, v[196:199], s[62:63] sc1
	v_cvt_pk_bf16_f32 v200, v7, v11
	v_cvt_pk_bf16_f32 v201, v15, v19
	v_cvt_pk_bf16_f32 v202, v23, v27
	v_cvt_pk_bf16_f32 v203, v31, v35
	global_store_dwordx4 v185, v[200:203], s[62:63] sc1
	global_load_dwordx4 v[4:7], v174, s[60:61] offset:0 sc1 nt
	global_load_dwordx4 v[8:11], v175, s[60:61] offset:0 sc1 nt
	global_load_dwordx4 v[12:15], v176, s[60:61] offset:0 sc1 nt
	global_load_dwordx4 v[16:19], v177, s[60:61] offset:0 sc1 nt
	global_load_dwordx4 v[20:23], v178, s[60:61] offset:0 sc1 nt
	global_load_dwordx4 v[24:27], v179, s[60:61] offset:0 sc1 nt
	global_load_dwordx4 v[28:31], v180, s[60:61] offset:0 sc1 nt
	global_load_dwordx4 v[32:35], v181, s[60:61] offset:0 sc1 nt
	s_add_u32 s62, s62, s72
	s_addc_u32 s63, s63, s73
	s_waitcnt vmcnt(28)
	v_cvt_pk_bf16_f32 v188, v36, v40
	v_cvt_pk_bf16_f32 v189, v44, v48
	v_cvt_pk_bf16_f32 v190, v52, v56
	v_cvt_pk_bf16_f32 v191, v60, v64
	global_store_dwordx4 v182, v[188:191], s[64:65] sc1
	v_cvt_pk_bf16_f32 v192, v37, v41
	v_cvt_pk_bf16_f32 v193, v45, v49
	v_cvt_pk_bf16_f32 v194, v53, v57
	v_cvt_pk_bf16_f32 v195, v61, v65
	global_store_dwordx4 v183, v[192:195], s[64:65] sc1
	v_cvt_pk_bf16_f32 v196, v38, v42
	v_cvt_pk_bf16_f32 v197, v46, v50
	v_cvt_pk_bf16_f32 v198, v54, v58
	v_cvt_pk_bf16_f32 v199, v62, v66
	global_store_dwordx4 v184, v[196:199], s[64:65] sc1
	v_cvt_pk_bf16_f32 v200, v39, v43
	v_cvt_pk_bf16_f32 v201, v47, v51
	v_cvt_pk_bf16_f32 v202, v55, v59
	v_cvt_pk_bf16_f32 v203, v63, v67
	global_store_dwordx4 v185, v[200:203], s[64:65] sc1
	global_load_dwordx4 v[36:39], v174, s[60:61] offset:128 sc1 nt
	global_load_dwordx4 v[40:43], v175, s[60:61] offset:128 sc1 nt
	global_load_dwordx4 v[44:47], v176, s[60:61] offset:128 sc1 nt
	global_load_dwordx4 v[48:51], v177, s[60:61] offset:128 sc1 nt
	global_load_dwordx4 v[52:55], v178, s[60:61] offset:128 sc1 nt
	global_load_dwordx4 v[56:59], v179, s[60:61] offset:128 sc1 nt
	global_load_dwordx4 v[60:63], v180, s[60:61] offset:128 sc1 nt
	global_load_dwordx4 v[64:67], v181, s[60:61] offset:128 sc1 nt
	s_add_u32 s64, s64, s72
	s_addc_u32 s65, s65, s73
	s_waitcnt vmcnt(32)
	v_cvt_pk_bf16_f32 v188, v68, v72
	v_cvt_pk_bf16_f32 v189, v76, v80
	v_cvt_pk_bf16_f32 v190, v84, v88
	v_cvt_pk_bf16_f32 v191, v92, v96
	global_store_dwordx4 v182, v[188:191], s[66:67] sc1
	v_cvt_pk_bf16_f32 v192, v69, v73
	v_cvt_pk_bf16_f32 v193, v77, v81
	v_cvt_pk_bf16_f32 v194, v85, v89
	v_cvt_pk_bf16_f32 v195, v93, v97
	global_store_dwordx4 v183, v[192:195], s[66:67] sc1
	v_cvt_pk_bf16_f32 v196, v70, v74
	v_cvt_pk_bf16_f32 v197, v78, v82
	v_cvt_pk_bf16_f32 v198, v86, v90
	v_cvt_pk_bf16_f32 v199, v94, v98
	global_store_dwordx4 v184, v[196:199], s[66:67] sc1
	v_cvt_pk_bf16_f32 v200, v71, v75
	v_cvt_pk_bf16_f32 v201, v79, v83
	v_cvt_pk_bf16_f32 v202, v87, v91
	v_cvt_pk_bf16_f32 v203, v95, v99
	global_store_dwordx4 v185, v[200:203], s[66:67] sc1
	global_load_dwordx4 v[68:71], v174, s[60:61] offset:256 sc1 nt
	global_load_dwordx4 v[72:75], v175, s[60:61] offset:256 sc1 nt
	global_load_dwordx4 v[76:79], v176, s[60:61] offset:256 sc1 nt
	global_load_dwordx4 v[80:83], v177, s[60:61] offset:256 sc1 nt
	global_load_dwordx4 v[84:87], v178, s[60:61] offset:256 sc1 nt
	global_load_dwordx4 v[88:91], v179, s[60:61] offset:256 sc1 nt
	global_load_dwordx4 v[92:95], v180, s[60:61] offset:256 sc1 nt
	global_load_dwordx4 v[96:99], v181, s[60:61] offset:256 sc1 nt
	s_add_u32 s66, s66, s72
	s_addc_u32 s67, s67, s73
	s_waitcnt vmcnt(36)
; #define LAS __attribute__((address_space(3)))
; __device__ __forceinline__ unsigned cvt_pk_bf16(float lo, float hi) { unsigned r; asm volatile("v_cvt_pk_bf16_f32 %0, %1, %2" : "=v"(r) : "v"(lo), "v"(hi)); return r; }
; #define LDS_WAIT() asm volatile("s_waitcnt lgkmcnt(0)" ::: "memory")
; __device__ __forceinline__ unsigned cvt_pk_bf16(float lo, float hi) { unsigned r; asm volatile("v_cvt_pk_bf16_f32 %0, %1, %2" : "=v"(r) : "v"(lo), "v"(hi)); return r; }
; template <bool NT = true> __device__ __forceinline__ void tr_load(const TrDesc& d, f32x4 (&v)[8], int lane) {
;     const float* sp = d.src + (size_t)(lane >> 3) * d.ldn + 4 * (lane & 7);
; #pragma unroll
;     for (int i = 0; i < 8; ++i) v[i] = NT ? __builtin_nontemporal_load((const f32x4*)(sp + (size_t)(8 * i) * d.ldn)) : *(const f32x4*)(sp + (size_t)(8 * i) * d.ldn);
; }
; template <bool NT = true> __device__ __forceinline__ void tr_finish(const TrDesc& d, const f32x4 (&v)[8], LAS float* scr, int lane) {
;     const int c = lane & 7;
;     f32x4 g0 = {1.f, 1.f, 1.f, 1.f}, g1 = {1.f, 1.f, 1.f, 1.f};
;     if (d.gain) { g0 = *(const f32x4*)(d.gain + 8 * c); g1 = *(const f32x4*)(d.gain + 8 * c + 4); }
; #pragma unroll
;     for (int i = 0; i < 8; ++i) { LAS float* w = scr + (8 * i + (lane >> 3)) * 33 + 4 * c; w[0] = v[i].x; w[1] = v[i].y; w[2] = v[i].z; w[3] = v[i].w; }
;     LDS_WAIT(); asm volatile("" ::: "memory");
; #pragma unroll
;     for (int j = 0; j < 4; ++j) { const int n = (lane >> 3) + 8 * j; const LAS float* s = scr + (8 * c) * 33 + n;
;         u32x4 o; o.x = cvt_pk_bf16(s[0 * 33] * g0.x, s[1 * 33] * g0.y); o.y = cvt_pk_bf16(s[2 * 33] * g0.z, s[3 * 33] * g0.w); o.z = cvt_pk_bf16(s[4 * 33] * g1.x, s[5 * 33] * g1.y); o.w = cvt_pk_bf16(s[6 * 33] * g1.z, s[7 * 33] * g1.w);
;         if (NT) __builtin_nontemporal_store(o, (u32x4*)(d.dst + (size_t)n * d.K + 8 * c)); else *(u32x4*)(d.dst + (size_t)n * d.K + 8 * c) = o; }
	v_cvt_pk_bf16_f32 v188, v100, v104
	v_cvt_pk_bf16_f32 v189, v108, v112
	v_cvt_pk_bf16_f32 v190, v116, v120
	v_cvt_pk_bf16_f32 v191, v124, v128
	global_store_dwordx4 v182, v[188:191], s[68:69] sc1
	v_cvt_pk_bf16_f32 v192, v101, v105
	v_cvt_pk_bf16_f32 v193, v109, v113
	v_cvt_pk_bf16_f32 v194, v117, v121
	v_cvt_pk_bf16_f32 v195, v125, v129
	global_store_dwordx4 v183, v[192:195], s[68:69] sc1
	v_cvt_pk_bf16_f32 v196, v102, v106
	v_cvt_pk_bf16_f32 v197, v110, v114
	v_cvt_pk_bf16_f32 v198, v118, v122
	v_cvt_pk_bf16_f32 v199, v126, v130
	global_store_dwordx4 v184, v[196:199], s[68:69] sc1
	v_cvt_pk_bf16_f32 v200, v103, v107
	v_cvt_pk_bf16_f32 v201, v111, v115
	v_cvt_pk_bf16_f32 v202, v119, v123
	v_cvt_pk_bf16_f32 v203, v127, v131
	global_store_dwordx4 v185, v[200:203], s[68:69] sc1
	global_load_dwordx4 v[100:103], v174, s[60:61] offset:384 sc1 nt
	global_load_dwordx4 v[104:107], v175, s[60:61] offset:384 sc1 nt
	global_load_dwordx4 v[108:111], v176, s[60:61] offset:384 sc1 nt
	global_load_dwordx4 v[112:115], v177, s[60:61] offset:384 sc1 nt
	global_load_dwordx4 v[116:119], v178, s[60:61] offset:384 sc1 nt
	global_load_dwordx4 v[120:123], v179, s[60:61] offset:384 sc1 nt
	global_load_dwordx4 v[124:127], v180, s[60:61] offset:384 sc1 nt
	global_load_dwordx4 v[128:131], v181, s[60:61] offset:384 sc1 nt
	s_add_u32 s68, s68, s72
	s_addc_u32 s69, s69, s73
	s_add_u32 s60, s60, s70
	s_addc_u32 s61, s61, s71
	s_sub_i32 s74, s74, 1
	s_cmp_eq_u32 s74, 1
	s_cbranch_scc1 .Lcv_n_last
.Lcv_n_steady:
	s_waitcnt vmcnt(36)
	v_cvt_pk_bf16_f32 v188, v4, v8
	v_cvt_pk_bf16_f32 v189, v12, v16
	v_cvt_pk_bf16_f32 v190, v20, v24
	v_cvt_pk_bf16_f32 v191, v28, v32
	global_store_dwordx4 v182, v[188:191], s[62:63] sc1
	v_cvt_pk_bf16_f32 v192, v5, v9
	v_cvt_pk_bf16_f32 v193, v13, v17
	v_cvt_pk_bf16_f32 v194, v21, v25
	v_cvt_pk_bf16_f32 v195, v29, v33
	global_store_dwordx4 v183, v[192:195], s[62:63] sc1
	v_cvt_pk_bf16_f32 v196, v6, v10
	v_cvt_pk_bf16_f32 v197, v14, v18
	v_cvt_pk_bf16_f32 v198, v22, v26
	v_cvt_pk_bf16_f32 v199, v30, v34
	global_store_dwordx4 v184, v[196:199], s[62:63] sc1
	v_cvt_pk_bf16_f32 v200, v7, v11
	v_cvt_pk_bf16_f32 v201, v15, v19
	v_cvt_pk_bf16_f32 v202, v23, v27
	v_cvt_pk_bf16_f32 v203, v31, v35
	global_store_dwordx4 v185, v[200:203], s[62:63] sc1
	global_load_dwordx4 v[4:7], v174, s[60:61] offset:0 sc1 nt
	global_load_dwordx4 v[8:11], v175, s[60:61] offset:0 sc1 nt
	global_load_dwordx4 v[12:15], v176, s[60:61] offset:0 sc1 nt
	global_load_dwordx4 v[16:19], v177, s[60:61] offset:0 sc1 nt
	global_load_dwordx4 v[20:23], v178, s[60:61] offset:0 sc1 nt
	global_load_dwordx4 v[24:27], v179, s[60:61] offset:0 sc1 nt
	global_load_dwordx4 v[28:31], v180, s[60:61] offset:0 sc1 nt
	global_load_dwordx4 v[32:35], v181, s[60:61] offset:0 sc1 nt
	s_add_u32 s62, s62, s72
	s_addc_u32 s63, s63, s73
	s_waitcnt vmcnt(36)
	v_cvt_pk_bf16_f32 v188, v36, v40
	v_cvt_pk_bf16_f32 v189, v44, v48
	v_cvt_pk_bf16_f32 v190, v52, v56
	v_cvt_pk_bf16_f32 v191, v60, v64
	global_store_dwordx4 v182, v[188:191], s[64:65] sc1
	v_cvt_pk_bf16_f32 v192, v37, v41
	v_cvt_pk_bf16_f32 v193, v45, v49
	v_cvt_pk_bf16_f32 v194, v53, v57
	v_cvt_pk_bf16_f32 v195, v61, v65
	global_store_dwordx4 v183, v[192:195], s[64:65] sc1
	v_cvt_pk_bf16_f32 v196, v38, v42
	v_cvt_pk_bf16_f32 v197, v46, v50
	v_cvt_pk_bf16_f32 v198, v54, v58
	v_cvt_pk_bf16_f32 v199, v62, v66
	global_store_dwordx4 v184, v[196:199], s[64:65] sc1
	v_cvt_pk_bf16_f32 v200, v39, v43
	v_cvt_pk_bf16_f32 v201, v47, v51
	v_cvt_pk_bf16_f32 v202, v55, v59
	v_cvt_pk_bf16_f32 v203, v63, v67
	global_store_dwordx4 v185, v[200:203], s[64:65] sc1
	global_load_dwordx4 v[36:39], v174, s[60:61] offset:128 sc1 nt
	global_load_dwordx4 v[40:43], v175, s[60:61] offset:128 sc1 nt
	global_load_dwordx4 v[44:47], v176, s[60:61] offset:128 sc1 nt
	global_load_dwordx4 v[48:51], v177, s[60:61] offset:128 sc1 nt
	global_load_dwordx4 v[52:55], v178, s[60:61] offset:128 sc1 nt
	global_load_dwordx4 v[56:59], v179, s[60:61] offset:128 sc1 nt
	global_load_dwordx4 v[60:63], v180, s[60:61] offset:128 sc1 nt
	global_load_dwordx4 v[64:67], v181, s[60:61] offset:128 sc1 nt
	s_add_u32 s64, s64, s72
	s_addc_u32 s65, s65, s73
	s_waitcnt vmcnt(36)
	v_cvt_pk_bf16_f32 v188, v68, v72
	v_cvt_pk_bf16_f32 v189, v76, v80
	v_cvt_pk_bf16_f32 v190, v84, v88
	v_cvt_pk_bf16_f32 v191, v92, v96
	global_store_dwordx4 v182, v[188:191], s[66:67] sc1
	v_cvt_pk_bf16_f32 v192, v69, v73
	v_cvt_pk_bf16_f32 v193, v77, v81
	v_cvt_pk_bf16_f32 v194, v85, v89
	v_cvt_pk_bf16_f32 v195, v93, v97
	global_store_dwordx4 v183, v[192:195], s[66:67] sc1
	v_cvt_pk_bf16_f32 v196, v70, v74
	v_cvt_pk_bf16_f32 v197, v78, v82
	v_cvt_pk_bf16_f32 v198, v86, v90
	v_cvt_pk_bf16_f32 v199, v94, v98
	global_store_dwordx4 v184, v[196:199], s[66:67] sc1
	v_cvt_pk_bf16_f32 v200, v71, v75
	v_cvt_pk_bf16_f32 v201, v79, v83
	v_cvt_pk_bf16_f32 v202, v87, v91
	v_cvt_pk_bf16_f32 v203, v95, v99
	global_store_dwordx4 v185, v[200:203], s[66:67] sc1
	global_load_dwordx4 v[68:71], v174, s[60:61] offset:256 sc1 nt
	global_load_dwordx4 v[72:75], v175, s[60:61] offset:256 sc1 nt
	global_load_dwordx4 v[76:79], v176, s[60:61] offset:256 sc1 nt
	global_load_dwordx4 v[80:83], v177, s[60:61] offset:256 sc1 nt
	global_load_dwordx4 v[84:87], v178, s[60:61] offset:256 sc1 nt
	global_load_dwordx4 v[88:91], v179, s[60:61] offset:256 sc1 nt
	global_load_dwordx4 v[92:95], v180, s[60:61] offset:256 sc1 nt
	global_load_dwordx4 v[96:99], v181, s[60:61] offset:256 sc1 nt
	s_add_u32 s66, s66, s72
	s_addc_u32 s67, s67, s73
	s_waitcnt vmcnt(36)
	v_cvt_pk_bf16_f32 v188, v100, v104
	v_cvt_pk_bf16_f32 v189, v108, v112
	v_cvt_pk_bf16_f32 v190, v116, v120
	v_cvt_pk_bf16_f32 v191, v124, v128
	global_store_dwordx4 v182, v[188:191], s[68:69] sc1
	v_cvt_pk_bf16_f32 v192, v101, v105
	v_cvt_pk_bf16_f32 v193, v109, v113
	v_cvt_pk_bf16_f32 v194, v117, v121
	v_cvt_pk_bf16_f32 v195, v125, v129
	global_store_dwordx4 v183, v[192:195], s[68:69] sc1
	v_cvt_pk_bf16_f32 v196, v102, v106
	v_cvt_pk_bf16_f32 v197, v110, v114
	v_cvt_pk_bf16_f32 v198, v118, v122
	v_cvt_pk_bf16_f32 v199, v126, v130
	global_store_dwordx4 v184, v[196:199], s[68:69] sc1
	v_cvt_pk_bf16_f32 v200, v103, v107
	v_cvt_pk_bf16_f32 v201, v111, v115
	v_cvt_pk_bf16_f32 v202, v119, v123
	v_cvt_pk_bf16_f32 v203, v127, v131
	global_store_dwordx4 v185, v[200:203], s[68:69] sc1
	global_load_dwordx4 v[100:103], v174, s[60:61] offset:384 sc1 nt
	global_load_dwordx4 v[104:107], v175, s[60:61] offset:384 sc1 nt
	global_load_dwordx4 v[108:111], v176, s[60:61] offset:384 sc1 nt
	global_load_dwordx4 v[112:115], v177, s[60:61] offset:384 sc1 nt
	global_load_dwordx4 v[116:119], v178, s[60:61] offset:384 sc1 nt
	global_load_dwordx4 v[120:123], v179, s[60:61] offset:384 sc1 nt
	global_load_dwordx4 v[124:127], v180, s[60:61] offset:384 sc1 nt
	global_load_dwordx4 v[128:131], v181, s[60:61] offset:384 sc1 nt
	s_add_u32 s68, s68, s72
	s_addc_u32 s69, s69, s73
	s_add_u32 s60, s60, s70
	s_addc_u32 s61, s61, s71
	s_sub_i32 s74, s74, 1
	s_cmp_eq_u32 s74, 1
	s_cbranch_scc0 .Lcv_n_steady

; #define LAS __attribute__((address_space(3)))
; template <bool NT = true> __device__ __forceinline__ void tr_load(const TrDesc& d, f32x4 (&v)[8], int lane) {
;     const float* sp = d.src + (size_t)(lane >> 3) * d.ldn + 4 * (lane & 7);
; #pragma unroll
;     for (int i = 0; i < 8; ++i) v[i] = NT ? __builtin_nontemporal_load((const f32x4*)(sp + (size_t)(8 * i) * d.ldn)) : *(const f32x4*)(sp + (size_t)(8 * i) * d.ldn);
; template <class F, bool NT = true> __device__ __forceinline__ void tr_run(F item, int first, int step, int n, LAS float* scr, int lane) {
;     if (first >= n) return;
;     TrDesc da = item(first), db = da, dc = da; f32x4 va[8], vb[8], vc[8];
;     tr_load<NT>(da, va, lane);
;     if (first + step < n) { db = item(first + step); tr_load<NT>(db, vb, lane); }
; __device__ __forceinline__ void tail_convert(const Params& p, LAS unsigned char* lds, int tw, int ntw, int wave, int lane) {
;     TailItem ti{p.ffn_w_down + (size_t)DFF * DM, (bf16_t*)(p.ws + WS_WDN1), p.cd_w_out, (bf16_t*)(p.ws + WS_WCD_OUT)};
;     tr_run(ti, tw, ntw, TAIL_ITEMS, (LAS float*)(lds + wave * 8704), lane);
; }
.LBB0_1133:
	s_abs_i32 s0, s92
	s_waitcnt vmcnt(7)
	v_cvt_f32_u32_e32 v2, s0
	s_sub_i32 s1, 0, s0
	s_waitcnt lgkmcnt(0)
	s_barrier
	v_rcp_iflag_f32_e32 v2, v2
	s_nop 0
	v_mul_f32_e32 v2, 0x4f7ffffe, v2
	v_cvt_u32_f32_e32 v2, v2
	s_nop 0
	v_readfirstlane_b32 s2, v2
	s_mul_i32 s1, s1, s2
	s_mul_hi_u32 s1, s2, s1
	s_add_i32 s2, s2, s1
	s_mul_hi_u32 s1, s2, 0xac0
	s_mul_i32 s1, s1, s0
	s_sub_i32 s1, 0xac0, s1
	s_sub_i32 s2, s1, s0
	s_cmp_ge_u32 s1, s0
	s_cselect_b32 s1, s2, s1
	s_sub_i32 s2, s1, s0
	s_cmp_ge_u32 s1, s0
	s_cselect_b32 s4, s2, s1
	s_cmp_lg_u32 s4, 0
	s_cbranch_scc0 .LBB0_1151
	v_readlane_b32 s0, v240, 0
	s_cmp_lt_i32 s0, s4
	s_cbranch_scc1 .LBB0_1150
	v_readlane_b32 s0, v240, 0
	s_sub_i32 s0, s0, s4
	s_lshl_b32 s2, s0, 3
	v_readlane_b32 s0, v240, 25
	s_add_i32 s2, s2, s0
	s_cmpk_gt_u32 s2, 0x3fff
	v_readlane_b32 s1, v240, 26
	s_cbranch_scc1 .LBB0_1150
	v_readlane_b32 s8, v240, 4
	s_sub_i32 s0, s92, s4
	v_readlane_b32 s10, v240, 6
	v_readlane_b32 s11, v240, 7
	v_readlane_b32 s18, v240, 14
	v_readlane_b32 s19, v240, 15
	s_lshl_b32 s3, s0, 3
	s_mov_b64 s[10:11], s[18:19]
	v_readlane_b32 s9, v240, 5
	s_add_u32 s8, s10, 0xac00000
	s_addc_u32 s9, s11, 0
	s_add_u32 s10, s58, 0x29f00000
	s_addc_u32 s11, s59, 0
	s_lshl_b32 s0, s2, 5
	s_and_b32 s5, s0, 0xfe0
	s_mul_i32 s0, s5, 0x5600
	s_add_u32 s0, s10, s0
	s_addc_u32 s1, s11, 0
	s_lshr_b32 s6, s2, 1
	s_and_b32 s6, s6, 0x1fc0
	s_lshl_b32 s7, s6, 1
	s_add_u32 s0, s0, s7
	s_addc_u32 s1, s1, 0
	s_lshl_b32 s6, s6, 14
	s_add_u32 s6, s8, s6
	s_addc_u32 s7, s9, 0
	s_lshl_b32 s5, s5, 2
	s_add_u32 s6, s6, s5
	v_lshrrev_b32_e32 v66, 3, v164
	s_addc_u32 s7, s7, 0
	v_mov_b32_e32 v99, 0
	v_lshlrev_b32_e32 v98, 14, v66
	v_and_b32_e32 v4, 28, v1
	v_readlane_b32 s12, v240, 8
	v_lshl_add_u64 v[2:3], s[6:7], 0, v[98:99]
	v_lshlrev_b32_e32 v100, 2, v4
	v_mov_b32_e32 v101, v99
	s_waitcnt vmcnt(1)
	v_lshl_add_u64 v[26:27], v[2:3], 0, v[100:101]
	s_mov_b32 s12, 0x20000
	v_readlane_b32 s13, v240, 9
	v_add_co_u32_e32 v10, vcc, s12, v26
	s_mov_b32 s13, 0x40000
	s_nop 0
	v_addc_co_u32_e32 v11, vcc, 0, v27, vcc
	v_readlane_b32 s14, v240, 10
	global_load_dwordx4 v[2:5], v[26:27], off sc1 nt
	global_load_dwordx4 v[6:9], v[10:11], off sc1 nt
	v_add_co_u32_e32 v10, vcc, s13, v26
	s_mov_b32 s14, 0x60000
	s_nop 0
	v_addc_co_u32_e32 v11, vcc, 0, v27, vcc
	v_readlane_b32 s15, v240, 11
	v_add_co_u32_e32 v14, vcc, s14, v26
	s_mov_b32 s15, 0x80000
	s_nop 0
	v_addc_co_u32_e32 v15, vcc, 0, v27, vcc
	v_readlane_b32 s16, v240, 12
	v_add_co_u32_e32 v18, vcc, s15, v26
	s_mov_b32 s16, 0xa0000
	s_nop 0
	v_addc_co_u32_e32 v19, vcc, 0, v27, vcc
	v_add_co_u32_e32 v22, vcc, s16, v26
	global_load_dwordx4 v[10:13], v[10:11], off sc1 nt
	s_nop 0
	global_load_dwordx4 v[14:17], v[14:15], off sc1 nt
	v_addc_co_u32_e32 v23, vcc, 0, v27, vcc
	v_add_co_u32_e32 v28, vcc, 0xc0000, v26
	global_load_dwordx4 v[18:21], v[18:19], off sc1 nt
	s_nop 0
	global_load_dwordx4 v[22:25], v[22:23], off sc1 nt
	v_addc_co_u32_e32 v29, vcc, 0, v27, vcc
	s_waitcnt vmcnt(6)
	v_add_co_u32_e32 v30, vcc, 0xe0000, v26
	v_readlane_b32 s17, v240, 13
	s_nop 0
	v_addc_co_u32_e32 v31, vcc, 0, v27, vcc
	global_load_dwordx4 v[26:29], v[28:29], off sc1 nt
	s_nop 0
	global_load_dwordx4 v[30:33], v[30:31], off sc1 nt
	v_lshlrev_b32_e32 v34, 12, v66
	s_add_i32 s5, s2, s3
	s_mov_b32 s17, 0xc0000
	s_mov_b32 s18, 0xe0000
	s_cmpk_gt_i32 s5, 0x3fff
	v_lshlrev_b32_e32 v102, 2, v34
	s_mov_b64 s[2:3], s[0:1]
	v_readlane_b32 s20, v240, 16
	v_readlane_b32 s21, v240, 17
	v_readlane_b32 s22, v240, 18
	v_readlane_b32 s23, v240, 19
	s_cbranch_scc1 .LBB0_1138
	s_ashr_i32 s2, s5, 31
	s_lshr_b32 s2, s2, 25
	s_add_i32 s2, s5, s2
	s_ashr_i32 s3, s2, 7
	s_and_b32 s2, s2, 0xffffff80
	s_sub_i32 s2, s5, s2
	s_lshl_b32 s6, s2, 5
	s_ashr_i32 s7, s6, 31
	s_mul_i32 s2, s2, 0xac000
	s_mul_hi_i32 s5, s6, 0x5600
	s_add_u32 s19, s10, s2
	s_addc_u32 s5, s11, s5
	s_lshl_b32 s20, s3, 6
	s_ashr_i32 s21, s20, 31
	s_lshl_b64 s[2:3], s[20:21], 1
	s_add_u32 s2, s19, s2
	s_addc_u32 s3, s5, s3
	s_lshl_b64 s[20:21], s[20:21], 14
	s_add_u32 s5, s8, s20
	s_addc_u32 s19, s9, s21
	s_lshl_b64 s[6:7], s[6:7], 2
	s_add_u32 s6, s5, s6
	s_addc_u32 s7, s19, s7
	v_mov_b32_e32 v103, v99
	v_lshl_add_u64 v[34:35], s[6:7], 0, v[102:103]
	v_lshl_add_u64 v[58:59], v[34:35], 0, v[100:101]
	v_add_co_u32_e32 v38, vcc, s12, v58
	s_nop 1
	v_addc_co_u32_e32 v39, vcc, 0, v59, vcc
	v_add_co_u32_e32 v42, vcc, s13, v58
	global_load_dwordx4 v[34:37], v[58:59], off sc1 nt
	s_nop 0
	global_load_dwordx4 v[38:41], v[38:39], off sc1 nt
	v_addc_co_u32_e32 v43, vcc, 0, v59, vcc
	v_add_co_u32_e32 v46, vcc, s14, v58
	s_nop 1
	v_addc_co_u32_e32 v47, vcc, 0, v59, vcc
	v_add_co_u32_e32 v50, vcc, s15, v58
	global_load_dwordx4 v[42:45], v[42:43], off sc1 nt
	s_nop 0
	global_load_dwordx4 v[46:49], v[46:47], off sc1 nt
	v_addc_co_u32_e32 v51, vcc, 0, v59, vcc
	v_add_co_u32_e32 v54, vcc, 0xa0000, v58
	s_nop 1
	v_addc_co_u32_e32 v55, vcc, 0, v59, vcc
	v_add_co_u32_e32 v60, vcc, 0xc0000, v58
	global_load_dwordx4 v[50:53], v[50:51], off sc1 nt
	s_nop 0
	global_load_dwordx4 v[54:57], v[54:55], off sc1 nt
	v_addc_co_u32_e32 v61, vcc, 0, v59, vcc
	v_add_co_u32_e32 v62, vcc, 0xe0000, v58
	s_nop 1
	v_addc_co_u32_e32 v63, vcc, 0, v59, vcc
	global_load_dwordx4 v[58:61], v[60:61], off sc1 nt
	s_nop 0
	global_load_dwordx4 v[62:65], v[62:63], off sc1 nt

; template <bool NT = true> __device__ __forceinline__ void tr_load(const TrDesc& d, f32x4 (&v)[8], int lane) {
;     const float* sp = d.src + (size_t)(lane >> 3) * d.ldn + 4 * (lane & 7);
; #pragma unroll
;     for (int i = 0; i < 8; ++i) v[i] = NT ? __builtin_nontemporal_load((const f32x4*)(sp + (size_t)(8 * i) * d.ldn)) : *(const f32x4*)(sp + (size_t)(8 * i) * d.ldn);
; template <class F, bool NT = true> __device__ __forceinline__ void tr_run(F item, int first, int step, int n, LAS float* scr, int lane) {
;     ...
;     for (int it = first; it < n; it += 3 * step) {
;         const bool h1 = it + step < n, h2 = it + 2 * step < n, h3 = it + 3 * step < n, h4 = it + 4 * step < n;
;         if (h2) { dc = item(it + 2 * step); tr_load<NT>(dc, vc, lane); }
.LBB0_1140:
	s_add_i32 s27, s19, s26
	s_cmpk_lt_i32 s27, 0x4000
	s_cselect_b64 s[6:7], -1, 0
	s_cmpk_gt_i32 s27, 0x3fff
	s_cbranch_scc1 .LBB0_1142
	s_ashr_i32 s0, s27, 31
	s_lshr_b32 s0, s0, 25
	s_add_i32 s0, s27, s0
	s_ashr_i32 s1, s0, 7
	s_and_b32 s0, s0, 0xffffff80
	s_sub_i32 s0, s27, s0
	s_lshl_b32 s28, s0, 5
	s_ashr_i32 s29, s28, 31
	s_mul_i32 s0, s0, 0xac000
	s_mul_hi_i32 s27, s28, 0x5600
	s_add_u32 s33, s10, s0
	s_addc_u32 s27, s11, s27
	s_lshl_b32 s34, s1, 6
	s_ashr_i32 s35, s34, 31
	s_lshl_b64 s[0:1], s[34:35], 1
	s_add_u32 s0, s33, s0
	s_addc_u32 s1, s27, s1
	s_lshl_b64 s[34:35], s[34:35], 14
	s_add_u32 s27, s8, s34
	s_addc_u32 s33, s9, s35
	s_lshl_b64 s[28:29], s[28:29], 2
	s_add_u32 s28, s27, s28
	s_addc_u32 s29, s33, s29
	v_mov_b32_e32 v103, v99
	v_lshl_add_u64 v[66:67], s[28:29], 0, v[102:103]
	v_mov_b32_e32 v101, v99
	v_lshl_add_u64 v[90:91], v[66:67], 0, v[100:101]
	v_add_co_u32_e32 v70, vcc, s12, v90
	s_nop 1
	v_addc_co_u32_e32 v71, vcc, 0, v91, vcc
	v_add_co_u32_e32 v74, vcc, s13, v90
	global_load_dwordx4 v[66:69], v[90:91], off sc1 nt
	s_nop 0
	global_load_dwordx4 v[70:73], v[70:71], off sc1 nt
	v_addc_co_u32_e32 v75, vcc, 0, v91, vcc
	v_add_co_u32_e32 v78, vcc, s14, v90
	s_nop 1
	v_addc_co_u32_e32 v79, vcc, 0, v91, vcc
	v_add_co_u32_e32 v82, vcc, 0x80000, v90
	global_load_dwordx4 v[74:77], v[74:75], off sc1 nt
	s_nop 0
	global_load_dwordx4 v[78:81], v[78:79], off sc1 nt
	v_addc_co_u32_e32 v83, vcc, 0, v91, vcc
	v_add_co_u32_e32 v86, vcc, 0xa0000, v90
	s_nop 1
	v_addc_co_u32_e32 v87, vcc, 0, v91, vcc
	v_add_co_u32_e32 v92, vcc, 0xc0000, v90
	global_load_dwordx4 v[82:85], v[82:83], off sc1 nt
	s_nop 0
	global_load_dwordx4 v[86:89], v[86:87], off sc1 nt
	v_addc_co_u32_e32 v93, vcc, 0, v91, vcc
	v_add_co_u32_e32 v94, vcc, 0xe0000, v90
	s_nop 1
	v_addc_co_u32_e32 v95, vcc, 0, v91, vcc
	global_load_dwordx4 v[90:93], v[92:93], off sc1 nt
	s_nop 0
	global_load_dwordx4 v[94:97], v[94:95], off sc1 nt

; template <bool NT = true> __device__ __forceinline__ void tr_load(const TrDesc& d, f32x4 (&v)[8], int lane) {
;     const float* sp = d.src + (size_t)(lane >> 3) * d.ldn + 4 * (lane & 7);
; #pragma unroll
;     for (int i = 0; i < 8; ++i) v[i] = NT ? __builtin_nontemporal_load((const f32x4*)(sp + (size_t)(8 * i) * d.ldn)) : *(const f32x4*)(sp + (size_t)(8 * i) * d.ldn);
; template <class F, bool NT = true> __device__ __forceinline__ void tr_run(F item, int first, int step, int n, LAS float* scr, int lane) {
;     ...
;         if (h3) { da = item(it + 3 * step); tr_load<NT>(da, va, lane); }
.LBB0_1146:
	s_ashr_i32 s4, s27, 31
	s_lshr_b32 s4, s4, 25
	s_add_i32 s4, s27, s4
	s_ashr_i32 s5, s4, 7
	s_and_b32 s4, s4, 0xffffff80
	s_sub_i32 s4, s27, s4
	s_lshl_b32 s28, s4, 5
	s_ashr_i32 s29, s28, 31
	s_mul_i32 s4, s4, 0xac000
	s_mul_hi_i32 s27, s28, 0x5600
	s_add_u32 s33, s10, s4
	s_addc_u32 s27, s11, s27
	s_lshl_b32 s34, s5, 6
	s_ashr_i32 s35, s34, 31
	s_lshl_b64 s[4:5], s[34:35], 1
	s_add_u32 s4, s33, s4
	s_addc_u32 s5, s27, s5
	s_lshl_b64 s[34:35], s[34:35], 14
	s_add_u32 s27, s8, s34
	s_addc_u32 s33, s9, s35
	s_lshl_b64 s[28:29], s[28:29], 2
	s_add_u32 s28, s27, s28
	s_addc_u32 s29, s33, s29
	v_mov_b32_e32 v103, v99
	v_lshl_add_u64 v[2:3], s[28:29], 0, v[102:103]
	v_mov_b32_e32 v101, v99
	v_lshl_add_u64 v[26:27], v[2:3], 0, v[100:101]
	v_add_co_u32_e32 v6, vcc, s12, v26
	s_nop 1
	v_addc_co_u32_e32 v7, vcc, 0, v27, vcc
	v_add_co_u32_e32 v10, vcc, s13, v26
	global_load_dwordx4 v[2:5], v[26:27], off sc1 nt
	s_nop 0
	global_load_dwordx4 v[6:9], v[6:7], off sc1 nt
	v_addc_co_u32_e32 v11, vcc, 0, v27, vcc
	v_add_co_u32_e32 v14, vcc, s14, v26
	s_nop 1
	v_addc_co_u32_e32 v15, vcc, 0, v27, vcc
	v_add_co_u32_e32 v18, vcc, s15, v26
	global_load_dwordx4 v[10:13], v[10:11], off sc1 nt
	s_nop 0
	global_load_dwordx4 v[14:17], v[14:15], off sc1 nt
	v_addc_co_u32_e32 v19, vcc, 0, v27, vcc
	v_add_co_u32_e32 v22, vcc, s16, v26
	s_nop 1
	v_addc_co_u32_e32 v23, vcc, 0, v27, vcc
	v_add_co_u32_e32 v28, vcc, s17, v26
	global_load_dwordx4 v[18:21], v[18:19], off sc1 nt
	s_nop 0
	global_load_dwordx4 v[22:25], v[22:23], off sc1 nt
	v_addc_co_u32_e32 v29, vcc, 0, v27, vcc
	v_add_co_u32_e32 v30, vcc, s18, v26
	s_nop 1
	v_addc_co_u32_e32 v31, vcc, 0, v27, vcc
	global_load_dwordx4 v[26:29], v[28:29], off sc1 nt
	s_nop 0
	global_load_dwordx4 v[30:33], v[30:31], off sc1 nt
	s_add_i32 s27, s23, s26
	s_cmpk_gt_i32 s27, 0x3fff
	s_cbranch_scc1 .LBB0_1144

; template <bool NT = true> __device__ __forceinline__ void tr_load(const TrDesc& d, f32x4 (&v)[8], int lane) {
;     const float* sp = d.src + (size_t)(lane >> 3) * d.ldn + 4 * (lane & 7);
; #pragma unroll
;     for (int i = 0; i < 8; ++i) v[i] = NT ? __builtin_nontemporal_load((const f32x4*)(sp + (size_t)(8 * i) * d.ldn)) : *(const f32x4*)(sp + (size_t)(8 * i) * d.ldn);
; template <class F, bool NT = true> __device__ __forceinline__ void tr_run(F item, int first, int step, int n, LAS float* scr, int lane) {
;     ...
;         if (h4) { db = item(it + 4 * step); tr_load<NT>(db, vb, lane); }
.LBB0_1148:
	s_ashr_i32 s2, s27, 31
	s_lshr_b32 s2, s2, 25
	s_add_i32 s2, s27, s2
	s_ashr_i32 s3, s2, 7
	s_and_b32 s2, s2, 0xffffff80
	s_sub_i32 s2, s27, s2
	s_lshl_b32 s28, s2, 5
	s_ashr_i32 s29, s28, 31
	s_mul_i32 s2, s2, 0xac000
	s_mul_hi_i32 s27, s28, 0x5600
	s_add_u32 s33, s10, s2
	s_addc_u32 s27, s11, s27
	s_lshl_b32 s34, s3, 6
	s_ashr_i32 s35, s34, 31
	s_lshl_b64 s[2:3], s[34:35], 1
	s_add_u32 s2, s33, s2
	s_addc_u32 s3, s27, s3
	s_lshl_b64 s[34:35], s[34:35], 14
	s_add_u32 s27, s8, s34
	s_addc_u32 s33, s9, s35
	s_lshl_b64 s[28:29], s[28:29], 2
	s_add_u32 s28, s27, s28
	s_addc_u32 s29, s33, s29
	v_mov_b32_e32 v103, v99
	v_lshl_add_u64 v[34:35], s[28:29], 0, v[102:103]
	v_mov_b32_e32 v101, v99
	v_lshl_add_u64 v[58:59], v[34:35], 0, v[100:101]
	v_add_co_u32_e32 v38, vcc, s12, v58
	s_nop 1
	v_addc_co_u32_e32 v39, vcc, 0, v59, vcc
	v_add_co_u32_e32 v42, vcc, s13, v58
	global_load_dwordx4 v[34:37], v[58:59], off sc1 nt
	s_nop 0
	global_load_dwordx4 v[38:41], v[38:39], off sc1 nt
	v_addc_co_u32_e32 v43, vcc, 0, v59, vcc
	v_add_co_u32_e32 v46, vcc, s14, v58
	s_nop 1
	v_addc_co_u32_e32 v47, vcc, 0, v59, vcc
	v_add_co_u32_e32 v50, vcc, 0x80000, v58
	global_load_dwordx4 v[42:45], v[42:43], off sc1 nt
	s_nop 0
	global_load_dwordx4 v[46:49], v[46:47], off sc1 nt
	v_addc_co_u32_e32 v51, vcc, 0, v59, vcc
	v_add_co_u32_e32 v54, vcc, 0xa0000, v58
	s_nop 1
	v_addc_co_u32_e32 v55, vcc, 0, v59, vcc
	v_add_co_u32_e32 v60, vcc, 0xc0000, v58
	global_load_dwordx4 v[50:53], v[50:51], off sc1 nt
	s_nop 0
	global_load_dwordx4 v[54:57], v[54:55], off sc1 nt
	v_addc_co_u32_e32 v61, vcc, 0, v59, vcc
	v_add_co_u32_e32 v62, vcc, 0xe0000, v58
	s_nop 1
	v_addc_co_u32_e32 v63, vcc, 0, v59, vcc
	global_load_dwordx4 v[58:61], v[60:61], off sc1 nt
	s_nop 0
	global_load_dwordx4 v[62:65], v[62:63], off sc1 nt
	s_andn2_b64 vcc, exec, s[6:7]
	s_cbranch_vccnz .LBB0_1139

; #define LAS __attribute__((address_space(3)))
; template <bool NT = true> __device__ __forceinline__ void tr_load(const TrDesc& d, f32x4 (&v)[8], int lane) {
;     const float* sp = d.src + (size_t)(lane >> 3) * d.ldn + 4 * (lane & 7);
; #pragma unroll
;     for (int i = 0; i < 8; ++i) v[i] = NT ? __builtin_nontemporal_load((const f32x4*)(sp + (size_t)(8 * i) * d.ldn)) : *(const f32x4*)(sp + (size_t)(8 * i) * d.ldn);
; template <class F, bool NT = true> __device__ __forceinline__ void tr_run(F item, int first, int step, int n, LAS float* scr, int lane) {
;     if (first >= n) return;
;     TrDesc da = item(first), db = da, dc = da; f32x4 va[8], vb[8], vc[8];
;     tr_load<NT>(da, va, lane);
;     if (first + step < n) { db = item(first + step); tr_load<NT>(db, vb, lane); }
; __device__ __forceinline__ void tail_convert(const Params& p, LAS unsigned char* lds, int tw, int ntw, int wave, int lane) {
;     TailItem ti{p.ffn_w_down + (size_t)DFF * DM, (bf16_t*)(p.ws + WS_WDN1), p.cd_w_out, (bf16_t*)(p.ws + WS_WCD_OUT)};
;     tr_run(ti, tw, ntw, TAIL_ITEMS, (LAS float*)(lds + wave * 8704), lane);
; }
.LBB0_1151:
.LBB0_1152:
	v_readlane_b32 s0, v240, 27
	s_cmpk_gt_i32 s0, 0x3fff
	v_readlane_b32 s1, v240, 28
	s_cbranch_scc1 .LBB0_1167
	v_readlane_b32 s0, v240, 4
	v_readlane_b32 s8, v240, 12
	v_readlane_b32 s10, v240, 14
	v_readlane_b32 s9, v240, 13
	v_readlane_b32 s11, v240, 15
	s_add_u32 s8, s10, 0xac00000
	s_addc_u32 s9, s11, 0
	s_add_u32 s10, s58, 0x29f00000
	v_readlane_b32 s20, v240, 27
	s_addc_u32 s11, s59, 0
	s_ashr_i32 s0, s20, 31
	s_lshr_b32 s0, s0, 25
	v_readlane_b32 s1, v240, 5
	s_add_i32 s0, s20, s0
	s_and_b32 s1, s0, 0x7ffff80
	v_readlane_b32 s2, v240, 6
	s_sub_i32 s1, s20, s1
	v_readlane_b32 s3, v240, 7
	s_lshl_b32 s2, s1, 5
	v_readlane_b32 s4, v240, 8
	v_readlane_b32 s6, v240, 10
	s_ashr_i32 s3, s2, 31
	s_mul_i32 s1, s1, 0xac000
	v_readlane_b32 s7, v240, 11
	s_mul_hi_i32 s4, s2, 0x5600
	s_add_u32 s6, s10, s1
	s_addc_u32 s7, s11, s4
	s_ashr_i32 s0, s0, 7
	v_readlane_b32 s5, v240, 9
	s_lshl_b32 s4, s0, 6
	s_ashr_i32 s5, s4, 31
	s_lshl_b64 s[0:1], s[4:5], 1
	s_add_u32 s0, s6, s0
	s_addc_u32 s1, s7, s1
	s_lshl_b64 s[4:5], s[4:5], 14
	s_add_u32 s4, s8, s4
	s_addc_u32 s5, s9, s5
	s_lshl_b64 s[2:3], s[2:3], 2
	s_add_u32 s2, s4, s2
	v_lshrrev_b32_e32 v66, 3, v164
	s_addc_u32 s3, s5, s3
	v_mov_b32_e32 v99, 0
	v_lshlrev_b32_e32 v98, 14, v66
	v_and_b32_e32 v1, 28, v1
	v_readlane_b32 s12, v240, 16
	s_waitcnt vmcnt(7)
	v_lshl_add_u64 v[2:3], s[2:3], 0, v[98:99]
	v_lshlrev_b32_e32 v100, 2, v1
	v_mov_b32_e32 v101, v99
	s_waitcnt vmcnt(1)
	v_lshl_add_u64 v[26:27], v[2:3], 0, v[100:101]
	s_mov_b32 s12, 0x20000
	v_readlane_b32 s13, v240, 17
	v_add_co_u32_e32 v10, vcc, s12, v26
	s_mov_b32 s13, 0x40000
	s_nop 0
	v_addc_co_u32_e32 v11, vcc, 0, v27, vcc
	v_readlane_b32 s14, v240, 18
	global_load_dwordx4 v[2:5], v[26:27], off sc1 nt
	global_load_dwordx4 v[6:9], v[10:11], off sc1 nt
	v_add_co_u32_e32 v10, vcc, s13, v26
	s_mov_b32 s14, 0x60000
	s_nop 0
	v_addc_co_u32_e32 v11, vcc, 0, v27, vcc
	v_readlane_b32 s15, v240, 19
	v_add_co_u32_e32 v14, vcc, s14, v26
	s_mov_b32 s15, 0x80000
	s_nop 0
	v_addc_co_u32_e32 v15, vcc, 0, v27, vcc
	v_add_co_u32_e32 v18, vcc, s15, v26
	s_mov_b32 s16, 0xa0000
	s_nop 0
	v_addc_co_u32_e32 v19, vcc, 0, v27, vcc
	v_add_co_u32_e32 v22, vcc, s16, v26
	global_load_dwordx4 v[10:13], v[10:11], off sc1 nt
	s_nop 0
	global_load_dwordx4 v[14:17], v[14:15], off sc1 nt
	v_addc_co_u32_e32 v23, vcc, 0, v27, vcc
	v_add_co_u32_e32 v28, vcc, 0xc0000, v26
	global_load_dwordx4 v[18:21], v[18:19], off sc1 nt
	s_nop 0
	global_load_dwordx4 v[22:25], v[22:23], off sc1 nt
	v_addc_co_u32_e32 v29, vcc, 0, v27, vcc
	s_waitcnt vmcnt(6)
	v_add_co_u32_e32 v30, vcc, 0xe0000, v26
	v_lshlrev_b32_e32 v1, 12, v66
	s_nop 0
	v_addc_co_u32_e32 v31, vcc, 0, v27, vcc
	global_load_dwordx4 v[26:29], v[28:29], off sc1 nt
	s_nop 0
	global_load_dwordx4 v[30:33], v[30:31], off sc1 nt
	s_add_i32 s4, s20, s74
	s_mov_b32 s17, 0xc0000
	s_mov_b32 s18, 0xe0000
	s_cmpk_gt_i32 s4, 0x3fff
	v_lshlrev_b32_e32 v102, 2, v1
	s_mov_b64 s[2:3], s[0:1]
	v_readlane_b32 s21, v240, 28
	s_cbranch_scc1 .LBB0_1155
	s_ashr_i32 s2, s4, 31
	s_lshr_b32 s2, s2, 25
	s_add_i32 s2, s4, s2
	s_ashr_i32 s3, s2, 7
	s_and_b32 s2, s2, 0xffffff80
	s_sub_i32 s2, s4, s2
	s_lshl_b32 s4, s2, 5
	s_ashr_i32 s5, s4, 31
	s_mul_i32 s2, s2, 0xac000
	s_mul_hi_i32 s6, s4, 0x5600
	s_add_u32 s19, s10, s2
	s_addc_u32 s20, s11, s6
	s_lshl_b32 s6, s3, 6
	s_ashr_i32 s7, s6, 31
	s_lshl_b64 s[2:3], s[6:7], 1
	s_add_u32 s2, s19, s2
	s_addc_u32 s3, s20, s3
	s_lshl_b64 s[6:7], s[6:7], 14
	s_add_u32 s6, s8, s6
	s_addc_u32 s7, s9, s7
	s_lshl_b64 s[4:5], s[4:5], 2
	s_add_u32 s4, s6, s4
	s_addc_u32 s5, s7, s5
	v_mov_b32_e32 v103, v99
	v_lshl_add_u64 v[34:35], s[4:5], 0, v[102:103]
	v_lshl_add_u64 v[58:59], v[34:35], 0, v[100:101]
	v_add_co_u32_e32 v38, vcc, s12, v58
	s_nop 1
	v_addc_co_u32_e32 v39, vcc, 0, v59, vcc
	v_add_co_u32_e32 v42, vcc, s13, v58
	global_load_dwordx4 v[34:37], v[58:59], off sc1 nt
	s_nop 0
	global_load_dwordx4 v[38:41], v[38:39], off sc1 nt
	v_addc_co_u32_e32 v43, vcc, 0, v59, vcc
	v_add_co_u32_e32 v46, vcc, s14, v58
	s_nop 1
	v_addc_co_u32_e32 v47, vcc, 0, v59, vcc
	v_add_co_u32_e32 v50, vcc, s15, v58
	global_load_dwordx4 v[42:45], v[42:43], off sc1 nt
	s_nop 0
	global_load_dwordx4 v[46:49], v[46:47], off sc1 nt
	v_addc_co_u32_e32 v51, vcc, 0, v59, vcc
	v_add_co_u32_e32 v54, vcc, 0xa0000, v58
	s_nop 1
	v_addc_co_u32_e32 v55, vcc, 0, v59, vcc
	v_add_co_u32_e32 v60, vcc, 0xc0000, v58
	global_load_dwordx4 v[50:53], v[50:51], off sc1 nt
	s_nop 0
	global_load_dwordx4 v[54:57], v[54:55], off sc1 nt
	v_addc_co_u32_e32 v61, vcc, 0, v59, vcc
	v_add_co_u32_e32 v62, vcc, 0xe0000, v58
	s_nop 1
	v_addc_co_u32_e32 v63, vcc, 0, v59, vcc
	global_load_dwordx4 v[58:61], v[60:61], off sc1 nt
	s_nop 0
	global_load_dwordx4 v[62:65], v[62:63], off sc1 nt

; template <bool NT = true> __device__ __forceinline__ void tr_load(const TrDesc& d, f32x4 (&v)[8], int lane) {
;     const float* sp = d.src + (size_t)(lane >> 3) * d.ldn + 4 * (lane & 7);
; #pragma unroll
;     for (int i = 0; i < 8; ++i) v[i] = NT ? __builtin_nontemporal_load((const f32x4*)(sp + (size_t)(8 * i) * d.ldn)) : *(const f32x4*)(sp + (size_t)(8 * i) * d.ldn);
; template <class F, bool NT = true> __device__ __forceinline__ void tr_run(F item, int first, int step, int n, LAS float* scr, int lane) {
;     ...
;     for (int it = first; it < n; it += 3 * step) {
;         const bool h1 = it + step < n, h2 = it + 2 * step < n, h3 = it + 3 * step < n, h4 = it + 4 * step < n;
;         if (h2) { dc = item(it + 2 * step); tr_load<NT>(dc, vc, lane); }
.LBB0_1157:
	s_add_i32 s24, s19, s23
	s_cmpk_lt_i32 s24, 0x4000
	s_cselect_b64 s[6:7], -1, 0
	s_cmpk_gt_i32 s24, 0x3fff
	s_cbranch_scc1 .LBB0_1159
	s_ashr_i32 s0, s24, 31
	s_lshr_b32 s0, s0, 25
	s_add_i32 s0, s24, s0
	s_ashr_i32 s1, s0, 7
	s_and_b32 s0, s0, 0xffffff80
	s_sub_i32 s0, s24, s0
	s_lshl_b32 s24, s0, 5
	s_ashr_i32 s25, s24, 31
	s_mul_i32 s0, s0, 0xac000
	s_mul_hi_i32 s26, s24, 0x5600
	s_add_u32 s28, s10, s0
	s_addc_u32 s29, s11, s26
	s_lshl_b32 s26, s1, 6
	s_ashr_i32 s27, s26, 31
	s_lshl_b64 s[0:1], s[26:27], 1
	s_add_u32 s0, s28, s0
	s_addc_u32 s1, s29, s1
	s_lshl_b64 s[26:27], s[26:27], 14
	s_add_u32 s26, s8, s26
	s_addc_u32 s27, s9, s27
	s_lshl_b64 s[24:25], s[24:25], 2
	s_add_u32 s24, s26, s24
	s_addc_u32 s25, s27, s25
	v_mov_b32_e32 v103, v99
	v_lshl_add_u64 v[66:67], s[24:25], 0, v[102:103]
	v_mov_b32_e32 v101, v99
	v_lshl_add_u64 v[90:91], v[66:67], 0, v[100:101]
	v_add_co_u32_e32 v70, vcc, s12, v90
	s_nop 1
	v_addc_co_u32_e32 v71, vcc, 0, v91, vcc
	v_add_co_u32_e32 v74, vcc, s13, v90
	global_load_dwordx4 v[66:69], v[90:91], off sc1 nt
	s_nop 0
	global_load_dwordx4 v[70:73], v[70:71], off sc1 nt
	v_addc_co_u32_e32 v75, vcc, 0, v91, vcc
	v_add_co_u32_e32 v78, vcc, s14, v90
	s_nop 1
	v_addc_co_u32_e32 v79, vcc, 0, v91, vcc
	v_add_co_u32_e32 v82, vcc, 0x80000, v90
	global_load_dwordx4 v[74:77], v[74:75], off sc1 nt
	s_nop 0
	global_load_dwordx4 v[78:81], v[78:79], off sc1 nt
	v_addc_co_u32_e32 v83, vcc, 0, v91, vcc
	v_add_co_u32_e32 v86, vcc, 0xa0000, v90
	s_nop 1
	v_addc_co_u32_e32 v87, vcc, 0, v91, vcc
	v_add_co_u32_e32 v92, vcc, 0xc0000, v90
	global_load_dwordx4 v[82:85], v[82:83], off sc1 nt
	s_nop 0
	global_load_dwordx4 v[86:89], v[86:87], off sc1 nt
	v_addc_co_u32_e32 v93, vcc, 0, v91, vcc
	v_add_co_u32_e32 v94, vcc, 0xe0000, v90
	s_nop 1
	v_addc_co_u32_e32 v95, vcc, 0, v91, vcc
	global_load_dwordx4 v[90:93], v[92:93], off sc1 nt
	s_nop 0
	global_load_dwordx4 v[94:97], v[94:95], off sc1 nt

; template <bool NT = true> __device__ __forceinline__ void tr_load(const TrDesc& d, f32x4 (&v)[8], int lane) {
;     const float* sp = d.src + (size_t)(lane >> 3) * d.ldn + 4 * (lane & 7);
; #pragma unroll
;     for (int i = 0; i < 8; ++i) v[i] = NT ? __builtin_nontemporal_load((const f32x4*)(sp + (size_t)(8 * i) * d.ldn)) : *(const f32x4*)(sp + (size_t)(8 * i) * d.ldn);
; template <class F, bool NT = true> __device__ __forceinline__ void tr_run(F item, int first, int step, int n, LAS float* scr, int lane) {
;     ...
;         if (h3) { da = item(it + 3 * step); tr_load<NT>(da, va, lane); }
.LBB0_1163:
	s_ashr_i32 s4, s24, 31
	s_lshr_b32 s4, s4, 25
	s_add_i32 s4, s24, s4
	s_ashr_i32 s5, s4, 7
	s_and_b32 s4, s4, 0xffffff80
	s_sub_i32 s4, s24, s4
	s_lshl_b32 s24, s4, 5
	s_ashr_i32 s25, s24, 31
	s_mul_i32 s4, s4, 0xac000
	s_mul_hi_i32 s26, s24, 0x5600
	s_add_u32 s28, s10, s4
	s_addc_u32 s29, s11, s26
	s_lshl_b32 s26, s5, 6
	s_ashr_i32 s27, s26, 31
	s_lshl_b64 s[4:5], s[26:27], 1
	s_add_u32 s4, s28, s4
	s_addc_u32 s5, s29, s5
	s_lshl_b64 s[26:27], s[26:27], 14
	s_add_u32 s26, s8, s26
	s_addc_u32 s27, s9, s27
	s_lshl_b64 s[24:25], s[24:25], 2
	s_add_u32 s24, s26, s24
	s_addc_u32 s25, s27, s25
	v_mov_b32_e32 v103, v99
	v_lshl_add_u64 v[2:3], s[24:25], 0, v[102:103]
	v_mov_b32_e32 v101, v99
	v_lshl_add_u64 v[26:27], v[2:3], 0, v[100:101]
	v_add_co_u32_e32 v6, vcc, s12, v26
	s_nop 1
	v_addc_co_u32_e32 v7, vcc, 0, v27, vcc
	v_add_co_u32_e32 v10, vcc, s13, v26
	global_load_dwordx4 v[2:5], v[26:27], off sc1 nt
	s_nop 0
	global_load_dwordx4 v[6:9], v[6:7], off sc1 nt
	v_addc_co_u32_e32 v11, vcc, 0, v27, vcc
	v_add_co_u32_e32 v14, vcc, s14, v26
	s_nop 1
	v_addc_co_u32_e32 v15, vcc, 0, v27, vcc
	v_add_co_u32_e32 v18, vcc, s15, v26
	global_load_dwordx4 v[10:13], v[10:11], off sc1 nt
	s_nop 0
	global_load_dwordx4 v[14:17], v[14:15], off sc1 nt
	v_addc_co_u32_e32 v19, vcc, 0, v27, vcc
	v_add_co_u32_e32 v22, vcc, s16, v26
	s_nop 1
	v_addc_co_u32_e32 v23, vcc, 0, v27, vcc
	v_add_co_u32_e32 v28, vcc, s17, v26
	global_load_dwordx4 v[18:21], v[18:19], off sc1 nt
	s_nop 0
	global_load_dwordx4 v[22:25], v[22:23], off sc1 nt
	v_addc_co_u32_e32 v29, vcc, 0, v27, vcc
	v_add_co_u32_e32 v30, vcc, s18, v26
	s_nop 1
	v_addc_co_u32_e32 v31, vcc, 0, v27, vcc
	global_load_dwordx4 v[26:29], v[28:29], off sc1 nt
	s_nop 0
	global_load_dwordx4 v[30:33], v[30:31], off sc1 nt
	s_add_i32 s24, s23, s74
	s_cmpk_gt_i32 s24, 0x3fff
	s_cbranch_scc1 .LBB0_1161

; template <bool NT = true> __device__ __forceinline__ void tr_load(const TrDesc& d, f32x4 (&v)[8], int lane) {
;     const float* sp = d.src + (size_t)(lane >> 3) * d.ldn + 4 * (lane & 7);
; #pragma unroll
;     for (int i = 0; i < 8; ++i) v[i] = NT ? __builtin_nontemporal_load((const f32x4*)(sp + (size_t)(8 * i) * d.ldn)) : *(const f32x4*)(sp + (size_t)(8 * i) * d.ldn);
; template <class F, bool NT = true> __device__ __forceinline__ void tr_run(F item, int first, int step, int n, LAS float* scr, int lane) {
;     ...
;         if (h4) { db = item(it + 4 * step); tr_load<NT>(db, vb, lane); }
.LBB0_1165:
	s_ashr_i32 s2, s23, 31
	s_lshr_b32 s2, s2, 25
	s_add_i32 s2, s23, s2
	s_ashr_i32 s3, s2, 7
	s_and_b32 s2, s2, 0xffffff80
	s_sub_i32 s2, s23, s2
	s_lshl_b32 s26, s2, 5
	s_ashr_i32 s27, s26, 31
	s_mul_i32 s2, s2, 0xac000
	s_mul_hi_i32 s23, s26, 0x5600
	s_add_u32 s25, s10, s2
	s_addc_u32 s23, s11, s23
	s_lshl_b32 s28, s3, 6
	s_ashr_i32 s29, s28, 31
	s_lshl_b64 s[2:3], s[28:29], 1
	s_add_u32 s2, s25, s2
	s_addc_u32 s3, s23, s3
	s_lshl_b64 s[28:29], s[28:29], 14
	s_add_u32 s23, s8, s28
	s_addc_u32 s25, s9, s29
	s_lshl_b64 s[26:27], s[26:27], 2
	s_add_u32 s26, s23, s26
	s_addc_u32 s27, s25, s27
	v_mov_b32_e32 v103, v99
	v_lshl_add_u64 v[34:35], s[26:27], 0, v[102:103]
	v_mov_b32_e32 v101, v99
	v_lshl_add_u64 v[58:59], v[34:35], 0, v[100:101]
	v_add_co_u32_e32 v38, vcc, s12, v58
	s_nop 1
	v_addc_co_u32_e32 v39, vcc, 0, v59, vcc
	v_add_co_u32_e32 v42, vcc, s13, v58
	global_load_dwordx4 v[34:37], v[58:59], off sc1 nt
	s_nop 0
	global_load_dwordx4 v[38:41], v[38:39], off sc1 nt
	v_addc_co_u32_e32 v43, vcc, 0, v59, vcc
	v_add_co_u32_e32 v46, vcc, s14, v58
	s_nop 1
	v_addc_co_u32_e32 v47, vcc, 0, v59, vcc
	v_add_co_u32_e32 v50, vcc, 0x80000, v58
	global_load_dwordx4 v[42:45], v[42:43], off sc1 nt
	s_nop 0
	global_load_dwordx4 v[46:49], v[46:47], off sc1 nt
	v_addc_co_u32_e32 v51, vcc, 0, v59, vcc
	v_add_co_u32_e32 v54, vcc, 0xa0000, v58
	s_nop 1
	v_addc_co_u32_e32 v55, vcc, 0, v59, vcc
	v_add_co_u32_e32 v60, vcc, 0xc0000, v58
	global_load_dwordx4 v[50:53], v[50:51], off sc1 nt
	s_nop 0
	global_load_dwordx4 v[54:57], v[54:55], off sc1 nt
	v_addc_co_u32_e32 v61, vcc, 0, v59, vcc
	v_add_co_u32_e32 v62, vcc, 0xe0000, v58
	s_nop 1
	v_addc_co_u32_e32 v63, vcc, 0, v59, vcc
	global_load_dwordx4 v[58:61], v[60:61], off sc1 nt
	s_nop 0
	global_load_dwordx4 v[62:65], v[62:63], off sc1 nt
	s_andn2_b64 vcc, exec, s[6:7]
	s_cbranch_vccnz .LBB0_1156

; #define LAS __attribute__((address_space(3)))
; template <bool NT = true> __device__ __forceinline__ void tr_load(const TrDesc& d, f32x4 (&v)[8], int lane) {
;     const float* sp = d.src + (size_t)(lane >> 3) * d.ldn + 4 * (lane & 7);
; #pragma unroll
;     for (int i = 0; i < 8; ++i) v[i] = NT ? __builtin_nontemporal_load((const f32x4*)(sp + (size_t)(8 * i) * d.ldn)) : *(const f32x4*)(sp + (size_t)(8 * i) * d.ldn);
; template <class F, bool NT = true> __device__ __forceinline__ void tr_run(F item, int first, int step, int n, LAS float* scr, int lane) {
;     if (first >= n) return;
;     TrDesc da = item(first), db = da, dc = da; f32x4 va[8], vb[8], vc[8];
;     tr_load<NT>(da, va, lane);
;     if (first + step < n) { db = item(first + step); tr_load<NT>(db, vb, lane); }
; __device__ __forceinline__ void tail1_convert(const Params& p, LAS unsigned char* lds, int tw, int ntw, int wave, int lane) {
;     Tail1Item ti{p.ffn_w_down + (size_t)DFF * DM, (bf16_t*)(p.ws + WS_WDN1)};
;     tr_run(ti, tw, ntw, P0_I_DN1, (LAS float*)(lds + wave * 8704), lane);
; }
.LBB0_1688:
	s_abs_i32 s0, s92
	s_waitcnt vmcnt(7)
	v_cvt_f32_u32_e32 v2, s0
	s_sub_i32 s1, 0, s0
	s_waitcnt lgkmcnt(0)
	s_barrier
	v_rcp_iflag_f32_e32 v2, v2
	s_nop 0
	v_mul_f32_e32 v2, 0x4f7ffffe, v2
	v_cvt_u32_f32_e32 v2, v2
	s_nop 0
	v_readfirstlane_b32 s2, v2
	s_mul_i32 s1, s1, s2
	s_mul_hi_u32 s1, s2, s1
	s_add_i32 s2, s2, s1
	s_mul_hi_u32 s1, s2, 0xac0
	s_mul_i32 s1, s1, s0
	s_sub_i32 s1, 0xac0, s1
	s_sub_i32 s2, s1, s0
	s_cmp_ge_u32 s1, s0
	s_cselect_b32 s1, s2, s1
	s_sub_i32 s2, s1, s0
	s_cmp_ge_u32 s1, s0
	s_cselect_b32 s4, s2, s1
	s_cmp_lg_u32 s4, 0
	s_cbranch_scc0 .LBB0_1706
	v_readlane_b32 s0, v240, 0
	s_cmp_lt_i32 s0, s4
	s_cbranch_scc1 .LBB0_1705
	v_readlane_b32 s0, v240, 0
	s_sub_i32 s0, s0, s4
	s_lshl_b32 s2, s0, 3
	v_readlane_b32 s0, v240, 25
	s_add_i32 s2, s2, s0
	s_cmpk_gt_u32 s2, 0x15ff
	v_readlane_b32 s1, v240, 26
	s_cbranch_scc1 .LBB0_1705
	v_readlane_b32 s8, v240, 4
	s_sub_i32 s0, s92, s4
	v_readlane_b32 s10, v240, 6
	v_readlane_b32 s11, v240, 7
	v_readlane_b32 s18, v240, 14
	v_readlane_b32 s19, v240, 15
	s_lshl_b32 s3, s0, 3
	s_mov_b64 s[10:11], s[18:19]
	v_readlane_b32 s9, v240, 5
	s_add_u32 s8, s10, 0xac00000
	s_addc_u32 s9, s11, 0
	s_add_u32 s10, s58, 0x29f00000
	s_addc_u32 s11, s59, 0
	s_lshr_b32 s0, s2, 1
	s_and_b32 s0, s0, 0xfc0
	s_or_b32 s5, s0, 0x2000
	s_lshl_b32 s0, s5, 14
	s_add_u32 s0, s8, s0
	s_addc_u32 s1, s9, 0
	s_lshl_b32 s6, s2, 5
	s_and_b32 s6, s6, 0xfe0
	s_lshl_b32 s7, s6, 2
	s_add_u32 s0, s0, s7
	v_lshrrev_b32_e32 v66, 3, v164
	s_addc_u32 s1, s1, 0
	v_mov_b32_e32 v99, 0
	v_lshlrev_b32_e32 v98, 14, v66
	v_and_b32_e32 v4, 28, v1
	v_readlane_b32 s12, v240, 8
	v_lshl_add_u64 v[2:3], s[0:1], 0, v[98:99]
	v_lshlrev_b32_e32 v100, 2, v4
	v_mov_b32_e32 v101, v99
	s_waitcnt vmcnt(1)
	v_lshl_add_u64 v[26:27], v[2:3], 0, v[100:101]
	s_mov_b32 s12, 0x20000
	v_readlane_b32 s13, v240, 9
	v_add_co_u32_e32 v10, vcc, s12, v26
	s_mov_b32 s13, 0x40000
	s_nop 0
	v_addc_co_u32_e32 v11, vcc, 0, v27, vcc
	v_readlane_b32 s14, v240, 10
	v_add_co_u32_e32 v18, vcc, s13, v26
	s_mov_b32 s14, 0x60000
	s_nop 0
	v_addc_co_u32_e32 v19, vcc, 0, v27, vcc
	v_readlane_b32 s15, v240, 11
	v_add_co_u32_e32 v20, vcc, s14, v26
	s_mov_b32 s15, 0x80000
	s_nop 0
	v_addc_co_u32_e32 v21, vcc, 0, v27, vcc
	v_readlane_b32 s16, v240, 12
	v_add_co_u32_e32 v28, vcc, s15, v26
	s_mov_b32 s16, 0xa0000
	s_nop 0
	v_addc_co_u32_e32 v29, vcc, 0, v27, vcc
	s_waitcnt vmcnt(0)
	v_add_co_u32_e32 v30, vcc, s16, v26
	global_load_dwordx4 v[2:5], v[26:27], off sc1 nt
	global_load_dwordx4 v[6:9], v[10:11], off sc1 nt
	v_addc_co_u32_e32 v31, vcc, 0, v27, vcc
	v_add_co_u32_e32 v34, vcc, 0xc0000, v26
	global_load_dwordx4 v[10:13], v[18:19], off sc1 nt
	global_load_dwordx4 v[14:17], v[20:21], off sc1 nt
	v_addc_co_u32_e32 v35, vcc, 0, v27, vcc
	v_add_co_u32_e32 v36, vcc, 0xe0000, v26
	global_load_dwordx4 v[18:21], v[28:29], off sc1 nt
	global_load_dwordx4 v[22:25], v[30:31], off sc1 nt
	v_addc_co_u32_e32 v37, vcc, 0, v27, vcc
	global_load_dwordx4 v[26:29], v[34:35], off sc1 nt
	global_load_dwordx4 v[30:33], v[36:37], off sc1 nt
	s_mulk_i32 s6, 0x5600
	s_add_u32 s0, s10, s6
	s_addc_u32 s1, s11, 0
	s_lshl_b32 s5, s5, 1
	s_add_u32 s0, s0, s5
	v_readlane_b32 s17, v240, 13
	s_addc_u32 s1, s1, 0
	v_lshlrev_b32_e32 v34, 12, v66
	s_add_i32 s5, s2, s3
	s_mov_b32 s17, 0xc0000
	s_mov_b32 s18, 0xe0000
	s_cmpk_gt_i32 s5, 0x15ff
	v_lshlrev_b32_e32 v102, 2, v34
	s_mov_b64 s[2:3], s[0:1]
	v_readlane_b32 s20, v240, 16
	v_readlane_b32 s21, v240, 17
	v_readlane_b32 s22, v240, 18
	v_readlane_b32 s23, v240, 19
	s_cbranch_scc1 .LBB0_1693
	s_ashr_i32 s2, s5, 31
	s_lshr_b32 s2, s2, 25
	s_add_i32 s2, s5, s2
	s_ashr_i32 s3, s2, 7
	s_and_b32 s2, s2, 0xffffff80
	s_sub_i32 s5, s5, s2
	s_lshl_b32 s2, s3, 6
	s_addk_i32 s2, 0x2000
	s_ashr_i32 s3, s2, 31
	s_lshl_b64 s[6:7], s[2:3], 14
	s_add_u32 s19, s8, s6
	s_addc_u32 s22, s9, s7
	s_lshl_b32 s6, s5, 5
	s_ashr_i32 s7, s6, 31
	s_lshl_b64 s[20:21], s[6:7], 2
	s_add_u32 s20, s19, s20
	s_addc_u32 s21, s22, s21
	v_mov_b32_e32 v103, v99
	v_lshl_add_u64 v[34:35], s[20:21], 0, v[102:103]
	v_lshl_add_u64 v[58:59], v[34:35], 0, v[100:101]
	v_add_co_u32_e32 v42, vcc, s12, v58
	s_mul_i32 s5, s5, 0xac000
	s_nop 0
	v_addc_co_u32_e32 v43, vcc, 0, v59, vcc
	v_add_co_u32_e32 v50, vcc, s13, v58
	global_load_dwordx4 v[34:37], v[58:59], off sc1 nt
	global_load_dwordx4 v[38:41], v[42:43], off sc1 nt
	v_addc_co_u32_e32 v51, vcc, 0, v59, vcc
	v_add_co_u32_e32 v52, vcc, s14, v58
	s_mul_hi_i32 s6, s6, 0x5600
	s_nop 0
	v_addc_co_u32_e32 v53, vcc, 0, v59, vcc
	v_add_co_u32_e32 v60, vcc, s15, v58
	global_load_dwordx4 v[42:45], v[50:51], off sc1 nt
	global_load_dwordx4 v[46:49], v[52:53], off sc1 nt
	v_addc_co_u32_e32 v61, vcc, 0, v59, vcc
	v_add_co_u32_e32 v62, vcc, 0xa0000, v58
	s_add_u32 s5, s10, s5
	s_nop 0
	v_addc_co_u32_e32 v63, vcc, 0, v59, vcc
	v_add_co_u32_e32 v68, vcc, 0xc0000, v58
	global_load_dwordx4 v[50:53], v[60:61], off sc1 nt
	global_load_dwordx4 v[54:57], v[62:63], off sc1 nt
	v_addc_co_u32_e32 v69, vcc, 0, v59, vcc
	v_add_co_u32_e32 v70, vcc, 0xe0000, v58
	s_addc_u32 s6, s11, s6
	s_nop 0
	v_addc_co_u32_e32 v71, vcc, 0, v59, vcc
	global_load_dwordx4 v[58:61], v[68:69], off sc1 nt
	global_load_dwordx4 v[62:65], v[70:71], off sc1 nt
	s_lshl_b64 s[2:3], s[2:3], 1
	s_add_u32 s2, s5, s2
	s_addc_u32 s3, s6, s3

; template <bool NT = true> __device__ __forceinline__ void tr_load(const TrDesc& d, f32x4 (&v)[8], int lane) {
;     const float* sp = d.src + (size_t)(lane >> 3) * d.ldn + 4 * (lane & 7);
; #pragma unroll
;     for (int i = 0; i < 8; ++i) v[i] = NT ? __builtin_nontemporal_load((const f32x4*)(sp + (size_t)(8 * i) * d.ldn)) : *(const f32x4*)(sp + (size_t)(8 * i) * d.ldn);
; template <class F, bool NT = true> __device__ __forceinline__ void tr_run(F item, int first, int step, int n, LAS float* scr, int lane) {
;     ...
;     for (int it = first; it < n; it += 3 * step) {
;         const bool h1 = it + step < n, h2 = it + 2 * step < n, h3 = it + 3 * step < n, h4 = it + 4 * step < n;
;         if (h2) { dc = item(it + 2 * step); tr_load<NT>(dc, vc, lane); }
.LBB0_1695:
	s_add_i32 s27, s19, s26
	s_cmpk_lt_i32 s27, 0x1600
	s_cselect_b64 s[6:7], -1, 0
	s_cmpk_gt_i32 s27, 0x15ff
	s_cbranch_scc1 .LBB0_1697
	s_ashr_i32 s0, s27, 31
	s_lshr_b32 s0, s0, 25
	s_add_i32 s0, s27, s0
	s_ashr_i32 s1, s0, 7
	s_and_b32 s0, s0, 0xffffff80
	s_sub_i32 s27, s27, s0
	s_lshl_b32 s0, s1, 6
	s_addk_i32 s0, 0x2000
	s_ashr_i32 s1, s0, 31
	s_lshl_b64 s[28:29], s[0:1], 14
	s_add_u32 s33, s8, s28
	s_addc_u32 s34, s9, s29
	s_lshl_b32 s28, s27, 5
	s_ashr_i32 s29, s28, 31
	s_lshl_b64 s[30:31], s[28:29], 2
	s_add_u32 s30, s33, s30
	s_addc_u32 s31, s34, s31
	v_mov_b32_e32 v103, v99
	v_lshl_add_u64 v[66:67], s[30:31], 0, v[102:103]
	v_mov_b32_e32 v101, v99
	v_lshl_add_u64 v[90:91], v[66:67], 0, v[100:101]
	v_add_co_u32_e32 v70, vcc, s12, v90
	s_mul_i32 s27, s27, 0xac000
	s_nop 0
	v_addc_co_u32_e32 v71, vcc, 0, v91, vcc
	v_add_co_u32_e32 v74, vcc, s13, v90
	global_load_dwordx4 v[66:69], v[90:91], off sc1 nt
	s_nop 0
	global_load_dwordx4 v[70:73], v[70:71], off sc1 nt
	v_addc_co_u32_e32 v75, vcc, 0, v91, vcc
	v_add_co_u32_e32 v78, vcc, s14, v90
	s_mul_hi_i32 s28, s28, 0x5600
	s_nop 0
	v_addc_co_u32_e32 v79, vcc, 0, v91, vcc
	v_add_co_u32_e32 v82, vcc, 0x80000, v90
	global_load_dwordx4 v[74:77], v[74:75], off sc1 nt
	s_nop 0
	global_load_dwordx4 v[78:81], v[78:79], off sc1 nt
	v_addc_co_u32_e32 v83, vcc, 0, v91, vcc
	v_add_co_u32_e32 v86, vcc, 0xa0000, v90
	s_add_u32 s27, s10, s27
	s_nop 0
	v_addc_co_u32_e32 v87, vcc, 0, v91, vcc
	v_add_co_u32_e32 v92, vcc, 0xc0000, v90
	global_load_dwordx4 v[82:85], v[82:83], off sc1 nt
	s_nop 0
	global_load_dwordx4 v[86:89], v[86:87], off sc1 nt
	v_addc_co_u32_e32 v93, vcc, 0, v91, vcc
	v_add_co_u32_e32 v94, vcc, 0xe0000, v90
	s_addc_u32 s28, s11, s28
	s_nop 0
	v_addc_co_u32_e32 v95, vcc, 0, v91, vcc
	global_load_dwordx4 v[90:93], v[92:93], off sc1 nt
	s_nop 0
	global_load_dwordx4 v[94:97], v[94:95], off sc1 nt
	s_lshl_b64 s[0:1], s[0:1], 1
	s_add_u32 s0, s27, s0
	s_addc_u32 s1, s28, s1

; template <bool NT = true> __device__ __forceinline__ void tr_load(const TrDesc& d, f32x4 (&v)[8], int lane) {
;     const float* sp = d.src + (size_t)(lane >> 3) * d.ldn + 4 * (lane & 7);
; #pragma unroll
;     for (int i = 0; i < 8; ++i) v[i] = NT ? __builtin_nontemporal_load((const f32x4*)(sp + (size_t)(8 * i) * d.ldn)) : *(const f32x4*)(sp + (size_t)(8 * i) * d.ldn);
; template <class F, bool NT = true> __device__ __forceinline__ void tr_run(F item, int first, int step, int n, LAS float* scr, int lane) {
;     ...
;         if (h3) { da = item(it + 3 * step); tr_load<NT>(da, va, lane); }
.LBB0_1701:
	s_ashr_i32 s4, s27, 31
	s_lshr_b32 s4, s4, 25
	s_add_i32 s4, s27, s4
	s_ashr_i32 s5, s4, 7
	s_and_b32 s4, s4, 0xffffff80
	s_sub_i32 s27, s27, s4
	s_lshl_b32 s4, s5, 6
	s_addk_i32 s4, 0x2000
	s_ashr_i32 s5, s4, 31
	s_lshl_b64 s[28:29], s[4:5], 14
	s_add_u32 s33, s8, s28
	s_addc_u32 s34, s9, s29
	s_lshl_b32 s28, s27, 5
	s_ashr_i32 s29, s28, 31
	s_lshl_b64 s[30:31], s[28:29], 2
	s_add_u32 s30, s33, s30
	s_addc_u32 s31, s34, s31
	v_mov_b32_e32 v103, v99
	v_lshl_add_u64 v[2:3], s[30:31], 0, v[102:103]
	v_mov_b32_e32 v101, v99
	v_lshl_add_u64 v[26:27], v[2:3], 0, v[100:101]
	v_add_co_u32_e32 v6, vcc, s12, v26
	s_mul_i32 s27, s27, 0xac000
	s_nop 0
	v_addc_co_u32_e32 v7, vcc, 0, v27, vcc
	v_add_co_u32_e32 v10, vcc, s13, v26
	global_load_dwordx4 v[2:5], v[26:27], off sc1 nt
	s_nop 0
	global_load_dwordx4 v[6:9], v[6:7], off sc1 nt
	v_addc_co_u32_e32 v11, vcc, 0, v27, vcc
	v_add_co_u32_e32 v14, vcc, s14, v26
	s_mul_hi_i32 s28, s28, 0x5600
	s_nop 0
	v_addc_co_u32_e32 v15, vcc, 0, v27, vcc
	v_add_co_u32_e32 v18, vcc, s15, v26
	global_load_dwordx4 v[10:13], v[10:11], off sc1 nt
	s_nop 0
	global_load_dwordx4 v[14:17], v[14:15], off sc1 nt
	v_addc_co_u32_e32 v19, vcc, 0, v27, vcc
	v_add_co_u32_e32 v22, vcc, s16, v26
	s_add_u32 s27, s10, s27
	s_nop 0
	v_addc_co_u32_e32 v23, vcc, 0, v27, vcc
	v_add_co_u32_e32 v28, vcc, s17, v26
	global_load_dwordx4 v[18:21], v[18:19], off sc1 nt
	s_nop 0
	global_load_dwordx4 v[22:25], v[22:23], off sc1 nt
	v_addc_co_u32_e32 v29, vcc, 0, v27, vcc
	v_add_co_u32_e32 v30, vcc, s18, v26
	s_addc_u32 s28, s11, s28
	s_nop 0
	v_addc_co_u32_e32 v31, vcc, 0, v27, vcc
	global_load_dwordx4 v[26:29], v[28:29], off sc1 nt
	s_nop 0
	global_load_dwordx4 v[30:33], v[30:31], off sc1 nt
	s_lshl_b64 s[4:5], s[4:5], 1
	s_add_u32 s4, s27, s4
	s_addc_u32 s5, s28, s5
	s_add_i32 s27, s23, s26
	s_cmpk_gt_i32 s27, 0x15ff
	s_cbranch_scc1 .LBB0_1699

; template <bool NT = true> __device__ __forceinline__ void tr_load(const TrDesc& d, f32x4 (&v)[8], int lane) {
;     const float* sp = d.src + (size_t)(lane >> 3) * d.ldn + 4 * (lane & 7);
; #pragma unroll
;     for (int i = 0; i < 8; ++i) v[i] = NT ? __builtin_nontemporal_load((const f32x4*)(sp + (size_t)(8 * i) * d.ldn)) : *(const f32x4*)(sp + (size_t)(8 * i) * d.ldn);
; template <class F, bool NT = true> __device__ __forceinline__ void tr_run(F item, int first, int step, int n, LAS float* scr, int lane) {
;     ...
;         if (h4) { db = item(it + 4 * step); tr_load<NT>(db, vb, lane); }
.LBB0_1703:
	s_ashr_i32 s2, s27, 31
	s_lshr_b32 s2, s2, 25
	s_add_i32 s2, s27, s2
	s_ashr_i32 s3, s2, 7
	s_and_b32 s2, s2, 0xffffff80
	s_sub_i32 s27, s27, s2
	s_lshl_b32 s2, s3, 6
	s_addk_i32 s2, 0x2000
	s_ashr_i32 s3, s2, 31
	s_lshl_b64 s[28:29], s[2:3], 14
	s_add_u32 s33, s8, s28
	s_addc_u32 s34, s9, s29
	s_lshl_b32 s28, s27, 5
	s_ashr_i32 s29, s28, 31
	s_lshl_b64 s[30:31], s[28:29], 2
	s_add_u32 s30, s33, s30
	s_addc_u32 s31, s34, s31
	v_mov_b32_e32 v103, v99
	v_lshl_add_u64 v[34:35], s[30:31], 0, v[102:103]
	v_mov_b32_e32 v101, v99
	v_lshl_add_u64 v[58:59], v[34:35], 0, v[100:101]
	v_add_co_u32_e32 v38, vcc, s12, v58
	s_mul_i32 s27, s27, 0xac000
	s_nop 0
	v_addc_co_u32_e32 v39, vcc, 0, v59, vcc
	v_add_co_u32_e32 v42, vcc, s13, v58
	global_load_dwordx4 v[34:37], v[58:59], off sc1 nt
	s_nop 0
	global_load_dwordx4 v[38:41], v[38:39], off sc1 nt
	v_addc_co_u32_e32 v43, vcc, 0, v59, vcc
	v_add_co_u32_e32 v46, vcc, s14, v58
	s_mul_hi_i32 s28, s28, 0x5600
	s_nop 0
	v_addc_co_u32_e32 v47, vcc, 0, v59, vcc
	v_add_co_u32_e32 v50, vcc, 0x80000, v58
	global_load_dwordx4 v[42:45], v[42:43], off sc1 nt
	s_nop 0
	global_load_dwordx4 v[46:49], v[46:47], off sc1 nt
	v_addc_co_u32_e32 v51, vcc, 0, v59, vcc
	v_add_co_u32_e32 v54, vcc, 0xa0000, v58
	s_add_u32 s27, s10, s27
	s_nop 0
	v_addc_co_u32_e32 v55, vcc, 0, v59, vcc
	v_add_co_u32_e32 v60, vcc, 0xc0000, v58
	global_load_dwordx4 v[50:53], v[50:51], off sc1 nt
	s_nop 0
	global_load_dwordx4 v[54:57], v[54:55], off sc1 nt
	v_addc_co_u32_e32 v61, vcc, 0, v59, vcc
	v_add_co_u32_e32 v62, vcc, 0xe0000, v58
	s_addc_u32 s28, s11, s28
	s_nop 0
	v_addc_co_u32_e32 v63, vcc, 0, v59, vcc
	global_load_dwordx4 v[58:61], v[60:61], off sc1 nt
	s_nop 0
	global_load_dwordx4 v[62:65], v[62:63], off sc1 nt
	s_lshl_b64 s[2:3], s[2:3], 1
	s_add_u32 s2, s27, s2
	s_addc_u32 s3, s28, s3
	s_andn2_b64 vcc, exec, s[6:7]
	s_cbranch_vccnz .LBB0_1694

; #define LAS __attribute__((address_space(3)))
; template <bool NT = true> __device__ __forceinline__ void tr_load(const TrDesc& d, f32x4 (&v)[8], int lane) {
;     const float* sp = d.src + (size_t)(lane >> 3) * d.ldn + 4 * (lane & 7);
; #pragma unroll
;     for (int i = 0; i < 8; ++i) v[i] = NT ? __builtin_nontemporal_load((const f32x4*)(sp + (size_t)(8 * i) * d.ldn)) : *(const f32x4*)(sp + (size_t)(8 * i) * d.ldn);
; template <class F, bool NT = true> __device__ __forceinline__ void tr_run(F item, int first, int step, int n, LAS float* scr, int lane) {
;     if (first >= n) return;
;     TrDesc da = item(first), db = da, dc = da; f32x4 va[8], vb[8], vc[8];
;     tr_load<NT>(da, va, lane);
;     if (first + step < n) { db = item(first + step); tr_load<NT>(db, vb, lane); }
; __device__ __forceinline__ void tail1_convert(const Params& p, LAS unsigned char* lds, int tw, int ntw, int wave, int lane) {
;     Tail1Item ti{p.ffn_w_down + (size_t)DFF * DM, (bf16_t*)(p.ws + WS_WDN1)};
;     tr_run(ti, tw, ntw, P0_I_DN1, (LAS float*)(lds + wave * 8704), lane);
; }
.LBB0_1706:
.LBB0_1707:
	v_readlane_b32 s0, v240, 27
	s_cmpk_gt_i32 s0, 0x15ff
	v_readlane_b32 s1, v240, 28
	s_cbranch_scc1 .LBB0_1722
	v_readlane_b32 s0, v240, 4
	v_readlane_b32 s8, v240, 12
	v_readlane_b32 s10, v240, 14
	v_readlane_b32 s9, v240, 13
	v_readlane_b32 s11, v240, 15
	s_add_u32 s8, s10, 0xac00000
	s_addc_u32 s9, s11, 0
	s_add_u32 s10, s58, 0x29f00000
	v_readlane_b32 s24, v240, 27
	s_addc_u32 s11, s59, 0
	s_ashr_i32 s0, s24, 31
	s_lshr_b32 s0, s0, 25
	v_readlane_b32 s1, v240, 5
	s_add_i32 s0, s24, s0
	v_readlane_b32 s6, v240, 10
	s_ashr_i32 s1, s0, 7
	s_and_b32 s0, s0, 0xffffff80
	s_sub_i32 s6, s24, s0
	s_lshl_b32 s0, s1, 6
	s_addk_i32 s0, 0x2000
	v_readlane_b32 s2, v240, 6
	v_readlane_b32 s3, v240, 7
	s_ashr_i32 s1, s0, 31
	v_readlane_b32 s7, v240, 11
	s_lshl_b64 s[2:3], s[0:1], 14
	v_readlane_b32 s12, v240, 16
	s_add_u32 s7, s8, s2
	s_addc_u32 s12, s9, s3
	s_lshl_b32 s2, s6, 5
	v_readlane_b32 s4, v240, 8
	v_readlane_b32 s5, v240, 9
	s_ashr_i32 s3, s2, 31
	s_lshl_b64 s[4:5], s[2:3], 2
	s_add_u32 s4, s7, s4
	v_lshrrev_b32_e32 v66, 3, v164
	s_addc_u32 s5, s12, s5
	v_mov_b32_e32 v99, 0
	v_lshlrev_b32_e32 v98, 14, v66
	v_and_b32_e32 v1, 28, v1
	s_waitcnt vmcnt(7)
	v_lshl_add_u64 v[2:3], s[4:5], 0, v[98:99]
	v_lshlrev_b32_e32 v100, 2, v1
	v_mov_b32_e32 v101, v99
	s_waitcnt vmcnt(1)
	v_lshl_add_u64 v[26:27], v[2:3], 0, v[100:101]
	s_mov_b32 s12, 0x20000
	v_readlane_b32 s13, v240, 17
	v_add_co_u32_e32 v10, vcc, s12, v26
	s_mov_b32 s13, 0x40000
	s_nop 0
	v_addc_co_u32_e32 v11, vcc, 0, v27, vcc
	v_readlane_b32 s14, v240, 18
	v_add_co_u32_e32 v18, vcc, s13, v26
	s_mov_b32 s14, 0x60000
	s_nop 0
	v_addc_co_u32_e32 v19, vcc, 0, v27, vcc
	v_readlane_b32 s15, v240, 19
	v_add_co_u32_e32 v20, vcc, s14, v26
	s_mov_b32 s15, 0x80000
	s_nop 0
	v_addc_co_u32_e32 v21, vcc, 0, v27, vcc
	v_add_co_u32_e32 v28, vcc, s15, v26
	s_mov_b32 s16, 0xa0000
	s_nop 0
	v_addc_co_u32_e32 v29, vcc, 0, v27, vcc
	s_waitcnt vmcnt(0)
	v_add_co_u32_e32 v30, vcc, s16, v26
	global_load_dwordx4 v[2:5], v[26:27], off sc1 nt
	global_load_dwordx4 v[6:9], v[10:11], off sc1 nt
	v_addc_co_u32_e32 v31, vcc, 0, v27, vcc
	v_add_co_u32_e32 v34, vcc, 0xc0000, v26
	global_load_dwordx4 v[10:13], v[18:19], off sc1 nt
	global_load_dwordx4 v[14:17], v[20:21], off sc1 nt
	v_addc_co_u32_e32 v35, vcc, 0, v27, vcc
	v_add_co_u32_e32 v36, vcc, 0xe0000, v26
	global_load_dwordx4 v[18:21], v[28:29], off sc1 nt
	global_load_dwordx4 v[22:25], v[30:31], off sc1 nt
	v_addc_co_u32_e32 v37, vcc, 0, v27, vcc
	global_load_dwordx4 v[26:29], v[34:35], off sc1 nt
	global_load_dwordx4 v[30:33], v[36:37], off sc1 nt
	s_mul_i32 s6, s6, 0xac000
	s_mul_hi_i32 s2, s2, 0x5600
	s_add_u32 s3, s10, s6
	s_addc_u32 s2, s11, s2
	s_lshl_b64 s[0:1], s[0:1], 1
	s_add_u32 s0, s3, s0
	s_addc_u32 s1, s2, s1
	v_lshlrev_b32_e32 v1, 12, v66
	s_add_i32 s4, s24, s74
	s_mov_b32 s17, 0xc0000
	s_mov_b32 s18, 0xe0000
	s_cmpk_gt_i32 s4, 0x15ff
	v_lshlrev_b32_e32 v102, 2, v1
	s_mov_b64 s[2:3], s[0:1]
	v_readlane_b32 s25, v240, 28
	s_cbranch_scc1 .LBB0_1710
	s_ashr_i32 s2, s4, 31
	s_lshr_b32 s2, s2, 25
	s_add_i32 s2, s4, s2
	s_ashr_i32 s3, s2, 7
	s_and_b32 s2, s2, 0xffffff80
	s_sub_i32 s19, s4, s2
	s_lshl_b32 s2, s3, 6
	s_addk_i32 s2, 0x2000
	s_ashr_i32 s3, s2, 31
	s_lshl_b64 s[4:5], s[2:3], 14
	s_add_u32 s20, s8, s4
	s_addc_u32 s21, s9, s5
	s_lshl_b32 s4, s19, 5
	s_ashr_i32 s5, s4, 31
	s_lshl_b64 s[6:7], s[4:5], 2
	s_add_u32 s6, s20, s6
	s_addc_u32 s7, s21, s7
	v_mov_b32_e32 v103, v99
	v_lshl_add_u64 v[34:35], s[6:7], 0, v[102:103]
	v_lshl_add_u64 v[58:59], v[34:35], 0, v[100:101]
	v_add_co_u32_e32 v42, vcc, s12, v58
	s_mul_i32 s19, s19, 0xac000
	s_nop 0
	v_addc_co_u32_e32 v43, vcc, 0, v59, vcc
	v_add_co_u32_e32 v50, vcc, s13, v58
	global_load_dwordx4 v[34:37], v[58:59], off sc1 nt
	global_load_dwordx4 v[38:41], v[42:43], off sc1 nt
	v_addc_co_u32_e32 v51, vcc, 0, v59, vcc
	v_add_co_u32_e32 v52, vcc, s14, v58
	s_mul_hi_i32 s4, s4, 0x5600
	s_nop 0
	v_addc_co_u32_e32 v53, vcc, 0, v59, vcc
	v_add_co_u32_e32 v60, vcc, s15, v58
	global_load_dwordx4 v[42:45], v[50:51], off sc1 nt
	global_load_dwordx4 v[46:49], v[52:53], off sc1 nt
	v_addc_co_u32_e32 v61, vcc, 0, v59, vcc
	v_add_co_u32_e32 v62, vcc, 0xa0000, v58
	s_add_u32 s5, s10, s19
	s_nop 0
	v_addc_co_u32_e32 v63, vcc, 0, v59, vcc
	v_add_co_u32_e32 v68, vcc, 0xc0000, v58
	global_load_dwordx4 v[50:53], v[60:61], off sc1 nt
	global_load_dwordx4 v[54:57], v[62:63], off sc1 nt
	v_addc_co_u32_e32 v69, vcc, 0, v59, vcc
	v_add_co_u32_e32 v70, vcc, 0xe0000, v58
	s_addc_u32 s4, s11, s4
	s_nop 0
	v_addc_co_u32_e32 v71, vcc, 0, v59, vcc
	global_load_dwordx4 v[58:61], v[68:69], off sc1 nt
	global_load_dwordx4 v[62:65], v[70:71], off sc1 nt
	s_lshl_b64 s[2:3], s[2:3], 1
	s_add_u32 s2, s5, s2
	s_addc_u32 s3, s4, s3

; template <bool NT = true> __device__ __forceinline__ void tr_load(const TrDesc& d, f32x4 (&v)[8], int lane) {
;     const float* sp = d.src + (size_t)(lane >> 3) * d.ldn + 4 * (lane & 7);
; #pragma unroll
;     for (int i = 0; i < 8; ++i) v[i] = NT ? __builtin_nontemporal_load((const f32x4*)(sp + (size_t)(8 * i) * d.ldn)) : *(const f32x4*)(sp + (size_t)(8 * i) * d.ldn);
; template <class F, bool NT = true> __device__ __forceinline__ void tr_run(F item, int first, int step, int n, LAS float* scr, int lane) {
;     ...
;     for (int it = first; it < n; it += 3 * step) {
;         const bool h1 = it + step < n, h2 = it + 2 * step < n, h3 = it + 3 * step < n, h4 = it + 4 * step < n;
;         if (h2) { dc = item(it + 2 * step); tr_load<NT>(dc, vc, lane); }
.LBB0_1712:
	s_add_i32 s24, s19, s23
	s_cmpk_lt_i32 s24, 0x1600
	s_cselect_b64 s[6:7], -1, 0
	s_cmpk_gt_i32 s24, 0x15ff
	s_cbranch_scc1 .LBB0_1714
	s_ashr_i32 s0, s24, 31
	s_lshr_b32 s0, s0, 25
	s_add_i32 s0, s24, s0
	s_ashr_i32 s1, s0, 7
	s_and_b32 s0, s0, 0xffffff80
	s_sub_i32 s28, s24, s0
	s_lshl_b32 s0, s1, 6
	s_addk_i32 s0, 0x2000
	s_ashr_i32 s1, s0, 31
	s_lshl_b64 s[24:25], s[0:1], 14
	s_add_u32 s29, s8, s24
	s_addc_u32 s30, s9, s25
	s_lshl_b32 s24, s28, 5
	s_ashr_i32 s25, s24, 31
	s_lshl_b64 s[26:27], s[24:25], 2
	s_add_u32 s26, s29, s26
	s_addc_u32 s27, s30, s27
	v_mov_b32_e32 v103, v99
	v_lshl_add_u64 v[66:67], s[26:27], 0, v[102:103]
	v_mov_b32_e32 v101, v99
	v_lshl_add_u64 v[90:91], v[66:67], 0, v[100:101]
	v_add_co_u32_e32 v74, vcc, s12, v90
	s_mul_i32 s28, s28, 0xac000
	s_nop 0
	v_addc_co_u32_e32 v75, vcc, 0, v91, vcc
	global_load_dwordx4 v[66:69], v[90:91], off sc1 nt
	global_load_dwordx4 v[70:73], v[74:75], off sc1 nt
	v_add_co_u32_e32 v74, vcc, s13, v90
	s_mul_hi_i32 s24, s24, 0x5600
	s_nop 0
	v_addc_co_u32_e32 v75, vcc, 0, v91, vcc
	v_add_co_u32_e32 v78, vcc, s14, v90
	s_add_u32 s25, s10, s28
	s_nop 0
	v_addc_co_u32_e32 v79, vcc, 0, v91, vcc
	v_add_co_u32_e32 v82, vcc, 0x80000, v90
	global_load_dwordx4 v[74:77], v[74:75], off sc1 nt
	s_nop 0
	global_load_dwordx4 v[78:81], v[78:79], off sc1 nt
	v_addc_co_u32_e32 v83, vcc, 0, v91, vcc
	v_add_co_u32_e32 v86, vcc, 0xa0000, v90
	s_addc_u32 s24, s11, s24
	s_nop 0
	v_addc_co_u32_e32 v87, vcc, 0, v91, vcc
	v_add_co_u32_e32 v92, vcc, 0xc0000, v90
	global_load_dwordx4 v[82:85], v[82:83], off sc1 nt
	s_nop 0
	global_load_dwordx4 v[86:89], v[86:87], off sc1 nt
	v_addc_co_u32_e32 v93, vcc, 0, v91, vcc
	v_add_co_u32_e32 v94, vcc, 0xe0000, v90
	s_lshl_b64 s[0:1], s[0:1], 1
	s_nop 0
	v_addc_co_u32_e32 v95, vcc, 0, v91, vcc
	global_load_dwordx4 v[90:93], v[92:93], off sc1 nt
	s_nop 0
	global_load_dwordx4 v[94:97], v[94:95], off sc1 nt
	s_add_u32 s0, s25, s0
	s_addc_u32 s1, s24, s1

; template <bool NT = true> __device__ __forceinline__ void tr_load(const TrDesc& d, f32x4 (&v)[8], int lane) {
;     const float* sp = d.src + (size_t)(lane >> 3) * d.ldn + 4 * (lane & 7);
; #pragma unroll
;     for (int i = 0; i < 8; ++i) v[i] = NT ? __builtin_nontemporal_load((const f32x4*)(sp + (size_t)(8 * i) * d.ldn)) : *(const f32x4*)(sp + (size_t)(8 * i) * d.ldn);
; template <class F, bool NT = true> __device__ __forceinline__ void tr_run(F item, int first, int step, int n, LAS float* scr, int lane) {
;     ...
;         if (h3) { da = item(it + 3 * step); tr_load<NT>(da, va, lane); }
.LBB0_1718:
	s_ashr_i32 s4, s24, 31
	s_lshr_b32 s4, s4, 25
	s_add_i32 s4, s24, s4
	s_ashr_i32 s5, s4, 7
	s_and_b32 s4, s4, 0xffffff80
	s_sub_i32 s28, s24, s4
	s_lshl_b32 s4, s5, 6
	s_addk_i32 s4, 0x2000
	s_ashr_i32 s5, s4, 31
	s_lshl_b64 s[24:25], s[4:5], 14
	s_add_u32 s29, s8, s24
	s_addc_u32 s30, s9, s25
	s_lshl_b32 s24, s28, 5
	s_ashr_i32 s25, s24, 31
	s_lshl_b64 s[26:27], s[24:25], 2
	s_add_u32 s26, s29, s26
	s_addc_u32 s27, s30, s27
	v_mov_b32_e32 v103, v99
	v_lshl_add_u64 v[2:3], s[26:27], 0, v[102:103]
	v_mov_b32_e32 v101, v99
	v_lshl_add_u64 v[26:27], v[2:3], 0, v[100:101]
	v_add_co_u32_e32 v10, vcc, s12, v26
	s_mul_i32 s28, s28, 0xac000
	s_nop 0
	v_addc_co_u32_e32 v11, vcc, 0, v27, vcc
	global_load_dwordx4 v[2:5], v[26:27], off sc1 nt
	global_load_dwordx4 v[6:9], v[10:11], off sc1 nt
	v_add_co_u32_e32 v10, vcc, s13, v26
	s_mul_hi_i32 s24, s24, 0x5600
	s_nop 0
	v_addc_co_u32_e32 v11, vcc, 0, v27, vcc
	v_add_co_u32_e32 v14, vcc, s14, v26
	s_add_u32 s25, s10, s28
	s_nop 0
	v_addc_co_u32_e32 v15, vcc, 0, v27, vcc
	v_add_co_u32_e32 v18, vcc, s15, v26
	global_load_dwordx4 v[10:13], v[10:11], off sc1 nt
	s_nop 0
	global_load_dwordx4 v[14:17], v[14:15], off sc1 nt
	v_addc_co_u32_e32 v19, vcc, 0, v27, vcc
	v_add_co_u32_e32 v22, vcc, s16, v26
	s_addc_u32 s24, s11, s24
	s_nop 0
	v_addc_co_u32_e32 v23, vcc, 0, v27, vcc
	v_add_co_u32_e32 v28, vcc, s17, v26
	global_load_dwordx4 v[18:21], v[18:19], off sc1 nt
	s_nop 0
	global_load_dwordx4 v[22:25], v[22:23], off sc1 nt
	v_addc_co_u32_e32 v29, vcc, 0, v27, vcc
	v_add_co_u32_e32 v30, vcc, s18, v26
	s_lshl_b64 s[4:5], s[4:5], 1
	s_nop 0
	v_addc_co_u32_e32 v31, vcc, 0, v27, vcc
	global_load_dwordx4 v[26:29], v[28:29], off sc1 nt
	s_nop 0
	global_load_dwordx4 v[30:33], v[30:31], off sc1 nt
	s_add_u32 s4, s25, s4
	s_addc_u32 s5, s24, s5
	s_add_i32 s24, s23, s74
	s_cmpk_gt_i32 s24, 0x15ff
	s_cbranch_scc1 .LBB0_1716

; template <bool NT = true> __device__ __forceinline__ void tr_load(const TrDesc& d, f32x4 (&v)[8], int lane) {
;     const float* sp = d.src + (size_t)(lane >> 3) * d.ldn + 4 * (lane & 7);
; #pragma unroll
;     for (int i = 0; i < 8; ++i) v[i] = NT ? __builtin_nontemporal_load((const f32x4*)(sp + (size_t)(8 * i) * d.ldn)) : *(const f32x4*)(sp + (size_t)(8 * i) * d.ldn);
; template <class F, bool NT = true> __device__ __forceinline__ void tr_run(F item, int first, int step, int n, LAS float* scr, int lane) {
;     ...
;         if (h4) { db = item(it + 4 * step); tr_load<NT>(db, vb, lane); }
.LBB0_1720:
	s_ashr_i32 s2, s23, 31
	s_lshr_b32 s2, s2, 25
	s_add_i32 s2, s23, s2
	s_ashr_i32 s3, s2, 7
	s_and_b32 s2, s2, 0xffffff80
	s_sub_i32 s23, s23, s2
	s_lshl_b32 s2, s3, 6
	s_addk_i32 s2, 0x2000
	s_ashr_i32 s3, s2, 31
	s_lshl_b64 s[26:27], s[2:3], 14
	s_add_u32 s25, s8, s26
	s_addc_u32 s30, s9, s27
	s_lshl_b32 s26, s23, 5
	s_ashr_i32 s27, s26, 31
	s_lshl_b64 s[28:29], s[26:27], 2
	s_add_u32 s28, s25, s28
	s_addc_u32 s29, s30, s29
	v_mov_b32_e32 v103, v99
	v_lshl_add_u64 v[34:35], s[28:29], 0, v[102:103]
	v_mov_b32_e32 v101, v99
	v_lshl_add_u64 v[58:59], v[34:35], 0, v[100:101]
	v_add_co_u32_e32 v42, vcc, s12, v58
	s_mul_i32 s23, s23, 0xac000
	s_nop 0
	v_addc_co_u32_e32 v43, vcc, 0, v59, vcc
	global_load_dwordx4 v[34:37], v[58:59], off sc1 nt
	global_load_dwordx4 v[38:41], v[42:43], off sc1 nt
	v_add_co_u32_e32 v42, vcc, s13, v58
	s_mul_hi_i32 s25, s26, 0x5600
	s_nop 0
	v_addc_co_u32_e32 v43, vcc, 0, v59, vcc
	v_add_co_u32_e32 v46, vcc, s14, v58
	s_add_u32 s23, s10, s23
	s_nop 0
	v_addc_co_u32_e32 v47, vcc, 0, v59, vcc
	v_add_co_u32_e32 v50, vcc, 0x80000, v58
	global_load_dwordx4 v[42:45], v[42:43], off sc1 nt
	s_nop 0
	global_load_dwordx4 v[46:49], v[46:47], off sc1 nt
	v_addc_co_u32_e32 v51, vcc, 0, v59, vcc
	v_add_co_u32_e32 v54, vcc, 0xa0000, v58
	s_addc_u32 s25, s11, s25
	s_nop 0
	v_addc_co_u32_e32 v55, vcc, 0, v59, vcc
	v_add_co_u32_e32 v60, vcc, 0xc0000, v58
	global_load_dwordx4 v[50:53], v[50:51], off sc1 nt
	s_nop 0
	global_load_dwordx4 v[54:57], v[54:55], off sc1 nt
	v_addc_co_u32_e32 v61, vcc, 0, v59, vcc
	v_add_co_u32_e32 v62, vcc, 0xe0000, v58
	s_lshl_b64 s[2:3], s[2:3], 1
	s_nop 0
	v_addc_co_u32_e32 v63, vcc, 0, v59, vcc
	global_load_dwordx4 v[58:61], v[60:61], off sc1 nt
	s_nop 0
	global_load_dwordx4 v[62:65], v[62:63], off sc1 nt
	s_add_u32 s2, s23, s2
	s_addc_u32 s3, s25, s3
	s_andn2_b64 vcc, exec, s[6:7]
	s_cbranch_vccnz .LBB0_1711
